# v96 with every per-cluster s_setprio 1/0 flip of the GEMM templates deleted
# speedup vs baseline: 1.0062x; 1.0062x over previous
; #define PG8_STAGE(bufoff, gbase, voff) do { _Pragma("unroll") for (int _i = 0; _i < 2; ++_i) \
;         __builtin_amdgcn_global_load_lds((const unsigned*)((const char*)(gbase) + (voff)[_i]), (LAS unsigned*)(lds + (bufoff) + ldsw + _i * 8192), 16, 0, 0); } while (0)
; #define PG8_LDA(dst, b, h) do { _Pragma("unroll") for (int m = 0; m < 4; ++m) _Pragma("unroll") for (int k = 0; k < 2; ++k) dst[m][k] = *(const LAS bf16x8*)(lds + PG8_SA(b, h) + aoff + m * 2048 + k * 1024); } while (0)
; #define PG8_LDB(dst, b, h) do { _Pragma("unroll") for (int n = 0; n < 2; ++n) _Pragma("unroll") for (int k = 0; k < 2; ++k) dst[n][k] = *(const LAS bf16x8*)(lds + PG8_SB(b, h) + boff + n * 2048 + k * 1024); } while (0)
; #define PG8_MMA(ai, bj, At, Bt) do { __builtin_amdgcn_s_setprio(1); _Pragma("unroll") for (int m = 0; m < 4; ++m) _Pragma("unroll") for (int n = 0; n < 2; ++n) _Pragma("unroll") for (int k = 0; k < 2; ++k) \
;         acc[ai][bj][m][n] = __builtin_amdgcn_mfma_f32_16x16x32_bf16(Bt[n][k], At[m][k], acc[ai][bj][m][n], 0, 0, 0); __builtin_amdgcn_s_setprio(0); } while (0)
; #define PG8_WAIT_V(n) asm volatile("s_waitcnt vmcnt(" #n ")" ::: "memory")
; #define PG8_WAIT_L(n) asm volatile("s_waitcnt lgkmcnt(" #n ")" ::: "memory")
; #define PG8_BAR __builtin_amdgcn_s_barrier()
; #define PG8_SCHED __builtin_amdgcn_sched_barrier(0)
; template <class Epi, class Sched, bool ALIGN_EPI = true, bool SP2 = true>
; DI void gemm_phase(LAS unsigned char* lds, const Gemm g, const Sched& S, const Epi& E) {
;     ...
;             const bool last = (t == nt - 2);
;             const char* a1 = cA + (size_t)(t + 1) * kstep;
;             const char* a2 = last ? nA : cA + (size_t)(t + 2) * kstep; const char* b2 = last ? nB : cB + (size_t)(t + 2) * kstep;
;             const char* a3 = a2 + kstep; const char* b3 = b2 + kstep;
;             PG8_LDB(B0, 0, 0); PG8_LDB(B1, 0, 1); PG8_SCHED; PG8_LDA(At, 0, 0); PG8_STAGE(PG8_SA(1, 1), a1 + hstepA, voffA);
;             PG8_WAIT_V(8); PG8_WAIT_L(0); PG8_BAR; PG8_MMA(0, 0, At, B0); PG8_MMA(0, 1, At, B1); PG8_BAR; PG8_SCHED;
;             PG8_LDA(At, 0, 1); PG8_STAGE(PG8_SB(0, 0), b2, voffB); PG8_STAGE(PG8_SB(0, 1), b2 + hstepB, voffB); PG8_STAGE(PG8_SA(0, 0), a2, voffA);
.LBB0_179:
	ds_read_b128 v[146:149], v156
	ds_read_b128 v[160:163], v156 offset:1024
	ds_read_b128 v[164:167], v156 offset:2048
	ds_read_b128 v[168:171], v156 offset:3072
	ds_read_b128 v[172:175], v157
	ds_read_b128 v[176:179], v157 offset:1024
	ds_read_b128 v[180:183], v157 offset:2048
	ds_read_b128 v[184:187], v157 offset:3072
	s_add_u32 s56, s54, 0xfffc0080
	s_addc_u32 s57, s55, -1
	s_cmp_eq_u32 s97, 12
	s_cselect_b32 s59, s35, s57
	s_cselect_b32 s58, s45, s56
	s_cselect_b32 s57, s19, s96
	s_cselect_b32 s56, s49, s95
	v_lshl_add_u64 v[150:151], s[54:55], 0, v[138:139]
	s_add_i32 m0, s60, 0xc000
	ds_read_b128 v[188:191], v158
	ds_read_b128 v[192:195], v158 offset:1024
	ds_read_b128 v[196:199], v158 offset:2048
	ds_read_b128 v[200:203], v158 offset:3072
	ds_read_b128 v[204:207], v158 offset:4096
	ds_read_b128 v[208:211], v158 offset:5120
	ds_read_b128 v[212:215], v158 offset:6144
	ds_read_b128 v[216:219], v158 offset:7168
	global_load_lds_dwordx4 v[150:151], off
	v_lshl_add_u64 v[150:151], s[54:55], 0, v[140:141]
	s_add_i32 m0, s60, 0xe000
	s_nop 0
	global_load_lds_dwordx4 v[150:151], off
	s_waitcnt vmcnt(8)
	s_waitcnt lgkmcnt(0)
	s_barrier
	s_waitcnt lgkmcnt(0)
	v_mfma_f32_16x16x32_bf16 v[124:127], v[146:149], v[188:191], v[124:127]
	v_mfma_f32_16x16x32_bf16 v[120:123], v[164:167], v[188:191], v[120:123]
	v_mfma_f32_16x16x32_bf16 v[108:111], v[146:149], v[196:199], v[108:111]
	v_mfma_f32_16x16x32_bf16 v[104:107], v[164:167], v[196:199], v[104:107]
	v_mfma_f32_16x16x32_bf16 v[92:95], v[146:149], v[204:207], v[92:95]
	v_mfma_f32_16x16x32_bf16 v[88:91], v[164:167], v[204:207], v[88:91]
	v_mfma_f32_16x16x32_bf16 v[76:79], v[146:149], v[212:215], v[76:79]
	v_mfma_f32_16x16x32_bf16 v[72:75], v[164:167], v[212:215], v[72:75]
	v_mfma_f32_16x16x32_bf16 v[124:127], v[160:163], v[192:195], v[124:127]
	v_mfma_f32_16x16x32_bf16 v[120:123], v[168:171], v[192:195], v[120:123]
	v_mfma_f32_16x16x32_bf16 v[108:111], v[160:163], v[200:203], v[108:111]
	v_mfma_f32_16x16x32_bf16 v[104:107], v[168:171], v[200:203], v[104:107]
	v_mfma_f32_16x16x32_bf16 v[92:95], v[160:163], v[208:211], v[92:95]
	v_mfma_f32_16x16x32_bf16 v[88:91], v[168:171], v[208:211], v[88:91]
	v_mfma_f32_16x16x32_bf16 v[76:79], v[160:163], v[216:219], v[76:79]
	v_mfma_f32_16x16x32_bf16 v[72:75], v[168:171], v[216:219], v[72:75]
	v_mfma_f32_16x16x32_bf16 v[112:115], v[172:175], v[188:191], v[112:115]
	v_mfma_f32_16x16x32_bf16 v[116:119], v[180:183], v[188:191], v[116:119]
	v_mfma_f32_16x16x32_bf16 v[96:99], v[172:175], v[196:199], v[96:99]
	v_mfma_f32_16x16x32_bf16 v[100:103], v[180:183], v[196:199], v[100:103]
	v_mfma_f32_16x16x32_bf16 v[80:83], v[172:175], v[204:207], v[80:83]
	v_mfma_f32_16x16x32_bf16 v[84:87], v[180:183], v[204:207], v[84:87]
	v_mfma_f32_16x16x32_bf16 v[64:67], v[172:175], v[212:215], v[64:67]
	v_mfma_f32_16x16x32_bf16 v[68:71], v[180:183], v[212:215], v[68:71]
	v_mfma_f32_16x16x32_bf16 v[112:115], v[176:179], v[192:195], v[112:115]
	v_mfma_f32_16x16x32_bf16 v[116:119], v[184:187], v[192:195], v[116:119]
	v_mfma_f32_16x16x32_bf16 v[96:99], v[176:179], v[200:203], v[96:99]
	v_mfma_f32_16x16x32_bf16 v[100:103], v[184:187], v[200:203], v[100:103]
	v_mfma_f32_16x16x32_bf16 v[80:83], v[176:179], v[208:211], v[80:83]
	v_mfma_f32_16x16x32_bf16 v[84:87], v[184:187], v[208:211], v[84:87]
	v_mfma_f32_16x16x32_bf16 v[64:67], v[176:179], v[216:219], v[64:67]
	v_mfma_f32_16x16x32_bf16 v[68:71], v[184:187], v[216:219], v[68:71]
	s_barrier
	s_add_i32 vcc_lo, s87, s3
	v_lshl_add_u64 v[150:151], s[56:57], 0, v[130:131]
	s_mov_b32 m0, vcc_lo
	ds_read_b128 v[188:191], v158 offset:16384
	ds_read_b128 v[192:195], v158 offset:17408
	ds_read_b128 v[196:199], v158 offset:18432
	ds_read_b128 v[200:203], v158 offset:19456
	ds_read_b128 v[204:207], v158 offset:20480
	ds_read_b128 v[208:211], v158 offset:21504
	ds_read_b128 v[212:215], v158 offset:22528
	ds_read_b128 v[216:219], v158 offset:23552
	global_load_lds_dwordx4 v[150:151], off
	s_add_i32 m0, vcc_lo, 0x2000
	s_add_u32 vcc_lo, s56, 0x40000
	v_lshl_add_u64 v[220:221], s[56:57], 0, v[134:135]
	s_addc_u32 vcc_hi, s57, 0
	s_add_i32 s91, s88, s3
	global_load_lds_dwordx4 v[220:221], off
	v_lshl_add_u64 v[222:223], vcc, 0, v[130:131]
	s_mov_b32 m0, s91
	v_lshl_add_u64 v[224:225], s[58:59], 0, v[132:133]
	global_load_lds_dwordx4 v[222:223], off
	v_lshl_add_u64 v[222:223], vcc, 0, v[134:135]
	s_add_i32 m0, s91, 0x2000
	s_nop 0
	global_load_lds_dwordx4 v[222:223], off
	v_lshl_add_u64 v[222:223], s[58:59], 0, v[128:129]
	s_mov_b32 m0, s60
	s_nop 0
	global_load_lds_dwordx4 v[222:223], off
	s_mov_b32 m0, s61
	s_nop 0
	global_load_lds_dwordx4 v[224:225], off
	s_waitcnt vmcnt(8)
	s_waitcnt lgkmcnt(0)
	s_barrier
; #define PG8_STAGE(bufoff, gbase, voff) do { _Pragma("unroll") for (int _i = 0; _i < 2; ++_i) \
;         __builtin_amdgcn_global_load_lds((const unsigned*)((const char*)(gbase) + (voff)[_i]), (LAS unsigned*)(lds + (bufoff) + ldsw + _i * 8192), 16, 0, 0); } while (0)
; #define PG8_LDA(dst, b, h) do { _Pragma("unroll") for (int m = 0; m < 4; ++m) _Pragma("unroll") for (int k = 0; k < 2; ++k) dst[m][k] = *(const LAS bf16x8*)(lds + PG8_SA(b, h) + aoff + m * 2048 + k * 1024); } while (0)
; #define PG8_LDB(dst, b, h) do { _Pragma("unroll") for (int n = 0; n < 2; ++n) _Pragma("unroll") for (int k = 0; k < 2; ++k) dst[n][k] = *(const LAS bf16x8*)(lds + PG8_SB(b, h) + boff + n * 2048 + k * 1024); } while (0)
; #define PG8_MMA(ai, bj, At, Bt) do { __builtin_amdgcn_s_setprio(1); _Pragma("unroll") for (int m = 0; m < 4; ++m) _Pragma("unroll") for (int n = 0; n < 2; ++n) _Pragma("unroll") for (int k = 0; k < 2; ++k) \
;         acc[ai][bj][m][n] = __builtin_amdgcn_mfma_f32_16x16x32_bf16(Bt[n][k], At[m][k], acc[ai][bj][m][n], 0, 0, 0); __builtin_amdgcn_s_setprio(0); } while (0)
; #define PG8_WAIT_V(n) asm volatile("s_waitcnt vmcnt(" #n ")" ::: "memory")
; #define PG8_WAIT_L(n) asm volatile("s_waitcnt lgkmcnt(" #n ")" ::: "memory")
; #define PG8_BAR __builtin_amdgcn_s_barrier()
; #define PG8_SCHED __builtin_amdgcn_sched_barrier(0)
; template <class Epi, class Sched, bool ALIGN_EPI = true, bool SP2 = true>
; DI void gemm_phase(LAS unsigned char* lds, const Gemm g, const Sched& S, const Epi& E) {
;     ...
;             PG8_WAIT_V(8); PG8_WAIT_L(0); PG8_BAR; PG8_MMA(1, 0, At, B0); PG8_MMA(1, 1, At, B1); PG8_BAR; PG8_SCHED;
;             PG8_LDB(B0, 1, 0); PG8_LDB(B1, 1, 1); PG8_SCHED; PG8_LDA(At, 1, 0); PG8_STAGE(PG8_SA(0, 1), a2 + hstepA, voffA);
;             PG8_WAIT_V(8); PG8_WAIT_L(0); PG8_BAR; PG8_MMA(0, 0, At, B0); PG8_MMA(0, 1, At, B1); PG8_BAR; PG8_SCHED;
	s_waitcnt lgkmcnt(0)
	v_mfma_f32_16x16x32_bf16 v[60:63], v[146:149], v[188:191], v[60:63]
	v_mfma_f32_16x16x32_bf16 v[56:59], v[164:167], v[188:191], v[56:59]
	v_mfma_f32_16x16x32_bf16 v[44:47], v[146:149], v[196:199], v[44:47]
	v_mfma_f32_16x16x32_bf16 v[40:43], v[164:167], v[196:199], v[40:43]
	v_mfma_f32_16x16x32_bf16 v[28:31], v[146:149], v[204:207], v[28:31]
	v_mfma_f32_16x16x32_bf16 v[24:27], v[164:167], v[204:207], v[24:27]
	v_mfma_f32_16x16x32_bf16 v[12:15], v[146:149], v[212:215], v[12:15]
	v_mfma_f32_16x16x32_bf16 v[8:11], v[164:167], v[212:215], v[8:11]
	v_mfma_f32_16x16x32_bf16 v[60:63], v[160:163], v[192:195], v[60:63]
	v_mfma_f32_16x16x32_bf16 v[56:59], v[168:171], v[192:195], v[56:59]
	v_mfma_f32_16x16x32_bf16 v[44:47], v[160:163], v[200:203], v[44:47]
	v_mfma_f32_16x16x32_bf16 v[40:43], v[168:171], v[200:203], v[40:43]
	v_mfma_f32_16x16x32_bf16 v[28:31], v[160:163], v[208:211], v[28:31]
	v_mfma_f32_16x16x32_bf16 v[24:27], v[168:171], v[208:211], v[24:27]
	v_mfma_f32_16x16x32_bf16 v[12:15], v[160:163], v[216:219], v[12:15]
	v_mfma_f32_16x16x32_bf16 v[8:11], v[168:171], v[216:219], v[8:11]
	v_mfma_f32_16x16x32_bf16 v[48:51], v[172:175], v[188:191], v[48:51]
	v_mfma_f32_16x16x32_bf16 v[52:55], v[180:183], v[188:191], v[52:55]
	v_mfma_f32_16x16x32_bf16 v[32:35], v[172:175], v[196:199], v[32:35]
	v_mfma_f32_16x16x32_bf16 v[36:39], v[180:183], v[196:199], v[36:39]
	v_mfma_f32_16x16x32_bf16 v[16:19], v[172:175], v[204:207], v[16:19]
	v_mfma_f32_16x16x32_bf16 v[20:23], v[180:183], v[204:207], v[20:23]
	v_mfma_f32_16x16x32_bf16 v[4:7], v[172:175], v[212:215], v[4:7]
	v_mfma_f32_16x16x32_bf16 v[0:3], v[180:183], v[212:215], v[0:3]
	v_mfma_f32_16x16x32_bf16 v[48:51], v[176:179], v[192:195], v[48:51]
	v_mfma_f32_16x16x32_bf16 v[52:55], v[184:187], v[192:195], v[52:55]
	v_mfma_f32_16x16x32_bf16 v[32:35], v[176:179], v[200:203], v[32:35]
	v_mfma_f32_16x16x32_bf16 v[36:39], v[184:187], v[200:203], v[36:39]
	v_mfma_f32_16x16x32_bf16 v[16:19], v[176:179], v[208:211], v[16:19]
	v_mfma_f32_16x16x32_bf16 v[20:23], v[184:187], v[208:211], v[20:23]
	v_mfma_f32_16x16x32_bf16 v[4:7], v[176:179], v[216:219], v[4:7]
	v_mfma_f32_16x16x32_bf16 v[0:3], v[184:187], v[216:219], v[0:3]
	s_barrier
	s_add_i32 s91, 0, 0x18000
	v_add_u32_e32 v136, s91, v153
	s_add_i32 vcc_lo, 0, 0x1c000
	ds_read_b128 v[146:149], v136
	ds_read_b128 v[160:163], v136 offset:1024
	ds_read_b128 v[164:167], v136 offset:2048
	ds_read_b128 v[168:171], v136 offset:3072
	v_add_u32_e32 v136, vcc_lo, v153
	ds_read_b128 v[172:175], v136
	ds_read_b128 v[176:179], v136 offset:1024
	ds_read_b128 v[180:183], v136 offset:2048
	ds_read_b128 v[184:187], v136 offset:3072
	s_add_u32 s58, s58, 0x40000
	s_addc_u32 s59, s59, 0
	s_mov_b32 m0, s66
	v_lshl_add_u64 v[228:229], s[58:59], 0, v[128:129]
	ds_read_b128 v[188:191], v158 offset:32768
	ds_read_b128 v[192:195], v158 offset:33792
	ds_read_b128 v[196:199], v158 offset:34816
	ds_read_b128 v[200:203], v158 offset:35840
	ds_read_b128 v[204:207], v158 offset:36864
	ds_read_b128 v[208:211], v158 offset:37888
	ds_read_b128 v[212:215], v158 offset:38912
	ds_read_b128 v[216:219], v158 offset:39936
	global_load_lds_dwordx4 v[228:229], off
	v_lshl_add_u64 v[228:229], s[58:59], 0, v[132:133]
	s_mov_b32 m0, s67
	s_nop 0
	global_load_lds_dwordx4 v[228:229], off
	s_waitcnt vmcnt(8)
	s_waitcnt lgkmcnt(0)
	s_barrier
	s_waitcnt lgkmcnt(0)
	v_mfma_f32_16x16x32_bf16 v[124:127], v[146:149], v[188:191], v[124:127]
	v_mfma_f32_16x16x32_bf16 v[120:123], v[164:167], v[188:191], v[120:123]
	v_mfma_f32_16x16x32_bf16 v[108:111], v[146:149], v[196:199], v[108:111]
	v_mfma_f32_16x16x32_bf16 v[104:107], v[164:167], v[196:199], v[104:107]
	v_mfma_f32_16x16x32_bf16 v[92:95], v[146:149], v[204:207], v[92:95]
	v_mfma_f32_16x16x32_bf16 v[88:91], v[164:167], v[204:207], v[88:91]
	v_mfma_f32_16x16x32_bf16 v[76:79], v[146:149], v[212:215], v[76:79]
	v_mfma_f32_16x16x32_bf16 v[72:75], v[164:167], v[212:215], v[72:75]
	v_mfma_f32_16x16x32_bf16 v[124:127], v[160:163], v[192:195], v[124:127]
	v_mfma_f32_16x16x32_bf16 v[120:123], v[168:171], v[192:195], v[120:123]
	v_mfma_f32_16x16x32_bf16 v[108:111], v[160:163], v[200:203], v[108:111]
	v_mfma_f32_16x16x32_bf16 v[104:107], v[168:171], v[200:203], v[104:107]
	v_mfma_f32_16x16x32_bf16 v[92:95], v[160:163], v[208:211], v[92:95]
	v_mfma_f32_16x16x32_bf16 v[88:91], v[168:171], v[208:211], v[88:91]
	v_mfma_f32_16x16x32_bf16 v[76:79], v[160:163], v[216:219], v[76:79]
	v_mfma_f32_16x16x32_bf16 v[72:75], v[168:171], v[216:219], v[72:75]
	v_mfma_f32_16x16x32_bf16 v[112:115], v[172:175], v[188:191], v[112:115]
	v_mfma_f32_16x16x32_bf16 v[116:119], v[180:183], v[188:191], v[116:119]
	v_mfma_f32_16x16x32_bf16 v[96:99], v[172:175], v[196:199], v[96:99]
	v_mfma_f32_16x16x32_bf16 v[100:103], v[180:183], v[196:199], v[100:103]
	v_mfma_f32_16x16x32_bf16 v[80:83], v[172:175], v[204:207], v[80:83]
	v_mfma_f32_16x16x32_bf16 v[84:87], v[180:183], v[204:207], v[84:87]
	v_mfma_f32_16x16x32_bf16 v[64:67], v[172:175], v[212:215], v[64:67]
	v_mfma_f32_16x16x32_bf16 v[68:71], v[180:183], v[212:215], v[68:71]
	v_mfma_f32_16x16x32_bf16 v[112:115], v[176:179], v[192:195], v[112:115]
	v_mfma_f32_16x16x32_bf16 v[116:119], v[184:187], v[192:195], v[116:119]
	v_mfma_f32_16x16x32_bf16 v[96:99], v[176:179], v[200:203], v[96:99]
	v_mfma_f32_16x16x32_bf16 v[100:103], v[184:187], v[200:203], v[100:103]
	v_mfma_f32_16x16x32_bf16 v[80:83], v[176:179], v[208:211], v[80:83]
	v_mfma_f32_16x16x32_bf16 v[84:87], v[184:187], v[208:211], v[84:87]
	v_mfma_f32_16x16x32_bf16 v[64:67], v[176:179], v[216:219], v[64:67]
	v_mfma_f32_16x16x32_bf16 v[68:71], v[184:187], v[216:219], v[68:71]
	s_barrier
; #define PG8_STAGE(bufoff, gbase, voff) do { _Pragma("unroll") for (int _i = 0; _i < 2; ++_i) \
;         __builtin_amdgcn_global_load_lds((const unsigned*)((const char*)(gbase) + (voff)[_i]), (LAS unsigned*)(lds + (bufoff) + ldsw + _i * 8192), 16, 0, 0); } while (0)
; #define PG8_LDA(dst, b, h) do { _Pragma("unroll") for (int m = 0; m < 4; ++m) _Pragma("unroll") for (int k = 0; k < 2; ++k) dst[m][k] = *(const LAS bf16x8*)(lds + PG8_SA(b, h) + aoff + m * 2048 + k * 1024); } while (0)
; #define PG8_MMA(ai, bj, At, Bt) do { __builtin_amdgcn_s_setprio(1); _Pragma("unroll") for (int m = 0; m < 4; ++m) _Pragma("unroll") for (int n = 0; n < 2; ++n) _Pragma("unroll") for (int k = 0; k < 2; ++k) \
;         acc[ai][bj][m][n] = __builtin_amdgcn_mfma_f32_16x16x32_bf16(Bt[n][k], At[m][k], acc[ai][bj][m][n], 0, 0, 0); __builtin_amdgcn_s_setprio(0); } while (0)
; #define PG8_WAIT_V(n) asm volatile("s_waitcnt vmcnt(" #n ")" ::: "memory")
; #define PG8_WAIT_L(n) asm volatile("s_waitcnt lgkmcnt(" #n ")" ::: "memory")
; #define PG8_BAR __builtin_amdgcn_s_barrier()
; #define PG8_SCHED __builtin_amdgcn_sched_barrier(0)
; template <class Epi, class Sched, bool ALIGN_EPI = true, bool SP2 = true>
; DI void gemm_phase(LAS unsigned char* lds, const Gemm g, const Sched& S, const Epi& E) {
;     ...
;         for (int t = 0; t < nt; t += 2) {
;             const bool last = (t == nt - 2);
;     ...
;             PG8_LDA(At, 1, 1); PG8_STAGE(PG8_SB(1, 0), b3, voffB); PG8_STAGE(PG8_SB(1, 1), b3 + hstepB, voffB); PG8_STAGE(PG8_SA(1, 0), a3, voffA);
;             PG8_WAIT_V(8); PG8_WAIT_L(0); PG8_BAR; PG8_MMA(1, 0, At, B0); PG8_MMA(1, 1, At, B1); PG8_BAR; PG8_SCHED;
	s_add_i32 s58, s91, s3
	v_lshl_add_u64 v[150:151], v[150:151], 0, s[14:15]
	s_mov_b32 m0, s58
	ds_read_b128 v[188:191], v158 offset:49152
	ds_read_b128 v[192:195], v158 offset:50176
	ds_read_b128 v[196:199], v158 offset:51200
	ds_read_b128 v[200:203], v158 offset:52224
	ds_read_b128 v[204:207], v158 offset:53248
	ds_read_b128 v[208:211], v158 offset:54272
	ds_read_b128 v[212:215], v158 offset:55296
	ds_read_b128 v[216:219], v158 offset:56320
	global_load_lds_dwordx4 v[150:151], off
	s_add_i32 m0, s58, 0x2000
	s_add_u32 s56, s56, 0x40080
	v_lshl_add_u64 v[150:151], v[220:221], 0, s[14:15]
	s_addc_u32 s57, s57, 0
	s_add_i32 s58, vcc_lo, s3
	global_load_lds_dwordx4 v[150:151], off
	v_lshl_add_u64 v[150:151], s[56:57], 0, v[130:131]
	s_mov_b32 m0, s58
	s_nop 0
	global_load_lds_dwordx4 v[150:151], off
	v_lshl_add_u64 v[150:151], s[56:57], 0, v[134:135]
	s_add_i32 m0, s58, 0x2000
	s_nop 0
	global_load_lds_dwordx4 v[150:151], off
	v_lshl_add_u64 v[150:151], v[222:223], 0, s[14:15]
	s_mov_b32 m0, s74
	s_nop 0
	global_load_lds_dwordx4 v[150:151], off
	v_lshl_add_u64 v[150:151], v[224:225], 0, s[14:15]
	s_mov_b32 m0, s75
	s_nop 0
	global_load_lds_dwordx4 v[150:151], off
	s_waitcnt vmcnt(8)
	s_waitcnt lgkmcnt(0)
	s_barrier
	s_waitcnt lgkmcnt(0)
	v_mfma_f32_16x16x32_bf16 v[60:63], v[146:149], v[188:191], v[60:63]
	v_mfma_f32_16x16x32_bf16 v[56:59], v[164:167], v[188:191], v[56:59]
	v_mfma_f32_16x16x32_bf16 v[44:47], v[146:149], v[196:199], v[44:47]
	v_mfma_f32_16x16x32_bf16 v[40:43], v[164:167], v[196:199], v[40:43]
	v_mfma_f32_16x16x32_bf16 v[28:31], v[146:149], v[204:207], v[28:31]
	v_mfma_f32_16x16x32_bf16 v[24:27], v[164:167], v[204:207], v[24:27]
	v_mfma_f32_16x16x32_bf16 v[12:15], v[146:149], v[212:215], v[12:15]
	v_mfma_f32_16x16x32_bf16 v[8:11], v[164:167], v[212:215], v[8:11]
	v_mfma_f32_16x16x32_bf16 v[60:63], v[160:163], v[192:195], v[60:63]
	v_mfma_f32_16x16x32_bf16 v[56:59], v[168:171], v[192:195], v[56:59]
	v_mfma_f32_16x16x32_bf16 v[44:47], v[160:163], v[200:203], v[44:47]
	v_mfma_f32_16x16x32_bf16 v[40:43], v[168:171], v[200:203], v[40:43]
	v_mfma_f32_16x16x32_bf16 v[28:31], v[160:163], v[208:211], v[28:31]
	v_mfma_f32_16x16x32_bf16 v[24:27], v[168:171], v[208:211], v[24:27]
	v_mfma_f32_16x16x32_bf16 v[12:15], v[160:163], v[216:219], v[12:15]
	v_mfma_f32_16x16x32_bf16 v[8:11], v[168:171], v[216:219], v[8:11]
	v_mfma_f32_16x16x32_bf16 v[48:51], v[172:175], v[188:191], v[48:51]
	v_mfma_f32_16x16x32_bf16 v[52:55], v[180:183], v[188:191], v[52:55]
	v_mfma_f32_16x16x32_bf16 v[32:35], v[172:175], v[196:199], v[32:35]
	v_mfma_f32_16x16x32_bf16 v[36:39], v[180:183], v[196:199], v[36:39]
	v_mfma_f32_16x16x32_bf16 v[16:19], v[172:175], v[204:207], v[16:19]
	v_mfma_f32_16x16x32_bf16 v[20:23], v[180:183], v[204:207], v[20:23]
	v_mfma_f32_16x16x32_bf16 v[4:7], v[172:175], v[212:215], v[4:7]
	v_mfma_f32_16x16x32_bf16 v[0:3], v[180:183], v[212:215], v[0:3]
	v_mfma_f32_16x16x32_bf16 v[48:51], v[176:179], v[192:195], v[48:51]
	v_mfma_f32_16x16x32_bf16 v[52:55], v[184:187], v[192:195], v[52:55]
	v_mfma_f32_16x16x32_bf16 v[32:35], v[176:179], v[200:203], v[32:35]
	v_mfma_f32_16x16x32_bf16 v[36:39], v[184:187], v[200:203], v[36:39]
	v_mfma_f32_16x16x32_bf16 v[16:19], v[176:179], v[208:211], v[16:19]
	v_mfma_f32_16x16x32_bf16 v[20:23], v[184:187], v[208:211], v[20:23]
	v_mfma_f32_16x16x32_bf16 v[4:7], v[176:179], v[216:219], v[4:7]
	v_mfma_f32_16x16x32_bf16 v[0:3], v[184:187], v[216:219], v[0:3]
	s_barrier
	s_add_i32 s97, s97, 2
	s_add_u32 s54, s54, 0x100
	s_addc_u32 s55, s55, 0
	s_add_u32 s95, s95, 0x100
	s_addc_u32 s96, s96, 0
	s_cmp_gt_u32 s97, 13
	s_cbranch_scc0 .LBB0_179
	s_and_b64 vcc, exec, s[16:17]
	s_cbranch_vccz .LBB0_182
	s_barrier

; #define PG8_STAGE(bufoff, gbase, voff) do { _Pragma("unroll") for (int _i = 0; _i < 2; ++_i) \
;         __builtin_amdgcn_global_load_lds((const unsigned*)((const char*)(gbase) + (voff)[_i]), (LAS unsigned*)(lds + (bufoff) + ldsw + _i * 8192), 16, 0, 0); } while (0)
; #define PG8_LDA(dst, b, h) do { _Pragma("unroll") for (int m = 0; m < 4; ++m) _Pragma("unroll") for (int k = 0; k < 2; ++k) dst[m][k] = *(const LAS bf16x8*)(lds + PG8_SA(b, h) + aoff + m * 2048 + k * 1024); } while (0)
; #define PG8_LDB(dst, b, h) do { _Pragma("unroll") for (int n = 0; n < 2; ++n) _Pragma("unroll") for (int k = 0; k < 2; ++k) dst[n][k] = *(const LAS bf16x8*)(lds + PG8_SB(b, h) + boff + n * 2048 + k * 1024); } while (0)
; #define PG8_MMA(ai, bj, At, Bt) do { __builtin_amdgcn_s_setprio(1); _Pragma("unroll") for (int m = 0; m < 4; ++m) _Pragma("unroll") for (int n = 0; n < 2; ++n) _Pragma("unroll") for (int k = 0; k < 2; ++k) \
;         acc[ai][bj][m][n] = __builtin_amdgcn_mfma_f32_16x16x32_bf16(Bt[n][k], At[m][k], acc[ai][bj][m][n], 0, 0, 0); __builtin_amdgcn_s_setprio(0); } while (0)
; #define PG8_WAIT_V(n) asm volatile("s_waitcnt vmcnt(" #n ")" ::: "memory")
; #define PG8_WAIT_L(n) asm volatile("s_waitcnt lgkmcnt(" #n ")" ::: "memory")
; #define PG8_BAR __builtin_amdgcn_s_barrier()
; #define PG8_SCHED __builtin_amdgcn_sched_barrier(0)
; template <class Epi, class Sched, bool ALIGN_EPI = true, bool SP2 = true>
; DI void gemm_phase(LAS unsigned char* lds, const Gemm g, const Sched& S, const Epi& E) {
;     ...
;             const bool last = (t == nt - 2);
;             const char* a1 = cA + (size_t)(t + 1) * kstep;
;             const char* a2 = last ? nA : cA + (size_t)(t + 2) * kstep; const char* b2 = last ? nB : cB + (size_t)(t + 2) * kstep;
;             const char* a3 = a2 + kstep; const char* b3 = b2 + kstep;
;             PG8_LDB(B0, 0, 0); PG8_LDB(B1, 0, 1); PG8_SCHED; PG8_LDA(At, 0, 0); PG8_STAGE(PG8_SA(1, 1), a1 + hstepA, voffA);
;             PG8_WAIT_V(8); PG8_WAIT_L(0); PG8_BAR; PG8_MMA(0, 0, At, B0); PG8_MMA(0, 1, At, B1); PG8_BAR; PG8_SCHED;
;             PG8_LDA(At, 0, 1); PG8_STAGE(PG8_SB(0, 0), b2, voffB); PG8_STAGE(PG8_SB(0, 1), b2 + hstepB, voffB); PG8_STAGE(PG8_SA(0, 0), a2, voffA);
.LBB0_619:
	ds_read_b128 v[140:143], v163
	ds_read_b128 v[144:147], v163 offset:1024
	ds_read_b128 v[148:151], v163 offset:2048
	ds_read_b128 v[152:155], v163 offset:3072
	ds_read_b128 v[156:159], v164
	ds_read_b128 v[166:169], v164 offset:1024
	ds_read_b128 v[170:173], v164 offset:2048
	ds_read_b128 v[174:177], v164 offset:3072
	s_add_u32 s60, s58, 0xfff80080
	s_addc_u32 s61, s59, -1
	s_cmp_eq_u32 s94, 28
	s_cselect_b32 s63, s45, s61
	s_cselect_b32 s62, s88, s60
	s_cselect_b32 s61, s43, s93
	s_cselect_b32 s60, s89, s92
	v_lshl_add_u64 v[210:211], s[58:59], 0, v[132:133]
	s_add_i32 m0, s73, 0xc000
	ds_read_b128 v[178:181], v165
	ds_read_b128 v[182:185], v165 offset:1024
	ds_read_b128 v[186:189], v165 offset:2048
	ds_read_b128 v[190:193], v165 offset:3072
	ds_read_b128 v[194:197], v165 offset:4096
	ds_read_b128 v[198:201], v165 offset:5120
	ds_read_b128 v[202:205], v165 offset:6144
	ds_read_b128 v[206:209], v165 offset:7168
	global_load_lds_dwordx4 v[210:211], off
	v_lshl_add_u64 v[210:211], s[58:59], 0, v[134:135]
	s_add_i32 m0, s73, 0xe000
	s_nop 0
	global_load_lds_dwordx4 v[210:211], off
	s_waitcnt vmcnt(8)
	s_waitcnt lgkmcnt(0)
	s_barrier
	s_waitcnt lgkmcnt(0)
	v_mfma_f32_16x16x32_bf16 v[124:127], v[140:143], v[178:181], v[124:127]
	v_mfma_f32_16x16x32_bf16 v[120:123], v[148:151], v[178:181], v[120:123]
	v_mfma_f32_16x16x32_bf16 v[112:115], v[140:143], v[186:189], v[112:115]
	v_mfma_f32_16x16x32_bf16 v[104:107], v[148:151], v[186:189], v[104:107]
	v_mfma_f32_16x16x32_bf16 v[96:99], v[140:143], v[194:197], v[96:99]
	v_mfma_f32_16x16x32_bf16 v[88:91], v[148:151], v[194:197], v[88:91]
	v_mfma_f32_16x16x32_bf16 v[80:83], v[140:143], v[202:205], v[80:83]
	v_mfma_f32_16x16x32_bf16 v[72:75], v[148:151], v[202:205], v[72:75]
	v_mfma_f32_16x16x32_bf16 v[124:127], v[144:147], v[182:185], v[124:127]
	v_mfma_f32_16x16x32_bf16 v[120:123], v[152:155], v[182:185], v[120:123]
	v_mfma_f32_16x16x32_bf16 v[112:115], v[144:147], v[190:193], v[112:115]
	v_mfma_f32_16x16x32_bf16 v[104:107], v[152:155], v[190:193], v[104:107]
	v_mfma_f32_16x16x32_bf16 v[96:99], v[144:147], v[198:201], v[96:99]
	v_mfma_f32_16x16x32_bf16 v[88:91], v[152:155], v[198:201], v[88:91]
	v_mfma_f32_16x16x32_bf16 v[80:83], v[144:147], v[206:209], v[80:83]
	v_mfma_f32_16x16x32_bf16 v[72:75], v[152:155], v[206:209], v[72:75]
	v_mfma_f32_16x16x32_bf16 v[116:119], v[156:159], v[178:181], v[116:119]
	v_mfma_f32_16x16x32_bf16 v[108:111], v[170:173], v[178:181], v[108:111]
	v_mfma_f32_16x16x32_bf16 v[100:103], v[156:159], v[186:189], v[100:103]
	v_mfma_f32_16x16x32_bf16 v[92:95], v[170:173], v[186:189], v[92:95]
	v_mfma_f32_16x16x32_bf16 v[84:87], v[156:159], v[194:197], v[84:87]
	v_mfma_f32_16x16x32_bf16 v[76:79], v[170:173], v[194:197], v[76:79]
	v_mfma_f32_16x16x32_bf16 v[68:71], v[156:159], v[202:205], v[68:71]
	v_mfma_f32_16x16x32_bf16 v[64:67], v[170:173], v[202:205], v[64:67]
	v_mfma_f32_16x16x32_bf16 v[116:119], v[166:169], v[182:185], v[116:119]
	v_mfma_f32_16x16x32_bf16 v[108:111], v[174:177], v[182:185], v[108:111]
	v_mfma_f32_16x16x32_bf16 v[100:103], v[166:169], v[190:193], v[100:103]
	v_mfma_f32_16x16x32_bf16 v[92:95], v[174:177], v[190:193], v[92:95]
	v_mfma_f32_16x16x32_bf16 v[84:87], v[166:169], v[198:201], v[84:87]
	v_mfma_f32_16x16x32_bf16 v[76:79], v[174:177], v[198:201], v[76:79]
	v_mfma_f32_16x16x32_bf16 v[68:71], v[166:169], v[206:209], v[68:71]
	v_mfma_f32_16x16x32_bf16 v[64:67], v[174:177], v[206:209], v[64:67]
	s_barrier
	s_add_i32 s91, s86, s72
	v_lshl_add_u64 v[210:211], s[60:61], 0, v[128:129]
	s_mov_b32 m0, s91
	ds_read_b128 v[178:181], v165 offset:16384
	ds_read_b128 v[182:185], v165 offset:17408
	ds_read_b128 v[186:189], v165 offset:18432
	ds_read_b128 v[190:193], v165 offset:19456
	ds_read_b128 v[194:197], v165 offset:20480
	ds_read_b128 v[198:201], v165 offset:21504
	ds_read_b128 v[202:205], v165 offset:22528
	ds_read_b128 v[206:209], v165 offset:23552
	global_load_lds_dwordx4 v[210:211], off
	s_add_i32 m0, s91, 0x2000
	s_add_u32 s96, s60, 0x80000
	v_lshl_add_u64 v[212:213], s[60:61], 0, v[130:131]
	s_addc_u32 s97, s61, 0
	s_add_i32 s91, s87, s72
	global_load_lds_dwordx4 v[212:213], off
	v_lshl_add_u64 v[214:215], s[96:97], 0, v[128:129]
	s_mov_b32 m0, s91
	v_lshl_add_u64 v[216:217], s[62:63], 0, v[130:131]
	global_load_lds_dwordx4 v[214:215], off
	v_lshl_add_u64 v[214:215], s[96:97], 0, v[130:131]
	s_add_i32 m0, s91, 0x2000
	s_nop 0
	global_load_lds_dwordx4 v[214:215], off
	v_lshl_add_u64 v[214:215], s[62:63], 0, v[128:129]
	s_mov_b32 m0, s73
	s_nop 0
	global_load_lds_dwordx4 v[214:215], off
	s_mov_b32 m0, s74
	s_nop 0
	global_load_lds_dwordx4 v[216:217], off
	s_waitcnt vmcnt(8)
	s_waitcnt lgkmcnt(0)
	s_barrier
; #define PG8_STAGE(bufoff, gbase, voff) do { _Pragma("unroll") for (int _i = 0; _i < 2; ++_i) \
;         __builtin_amdgcn_global_load_lds((const unsigned*)((const char*)(gbase) + (voff)[_i]), (LAS unsigned*)(lds + (bufoff) + ldsw + _i * 8192), 16, 0, 0); } while (0)
; #define PG8_LDA(dst, b, h) do { _Pragma("unroll") for (int m = 0; m < 4; ++m) _Pragma("unroll") for (int k = 0; k < 2; ++k) dst[m][k] = *(const LAS bf16x8*)(lds + PG8_SA(b, h) + aoff + m * 2048 + k * 1024); } while (0)
; #define PG8_LDB(dst, b, h) do { _Pragma("unroll") for (int n = 0; n < 2; ++n) _Pragma("unroll") for (int k = 0; k < 2; ++k) dst[n][k] = *(const LAS bf16x8*)(lds + PG8_SB(b, h) + boff + n * 2048 + k * 1024); } while (0)
; #define PG8_MMA(ai, bj, At, Bt) do { __builtin_amdgcn_s_setprio(1); _Pragma("unroll") for (int m = 0; m < 4; ++m) _Pragma("unroll") for (int n = 0; n < 2; ++n) _Pragma("unroll") for (int k = 0; k < 2; ++k) \
;         acc[ai][bj][m][n] = __builtin_amdgcn_mfma_f32_16x16x32_bf16(Bt[n][k], At[m][k], acc[ai][bj][m][n], 0, 0, 0); __builtin_amdgcn_s_setprio(0); } while (0)
; #define PG8_WAIT_V(n) asm volatile("s_waitcnt vmcnt(" #n ")" ::: "memory")
; #define PG8_WAIT_L(n) asm volatile("s_waitcnt lgkmcnt(" #n ")" ::: "memory")
; #define PG8_BAR __builtin_amdgcn_s_barrier()
; #define PG8_SCHED __builtin_amdgcn_sched_barrier(0)
; template <class Epi, class Sched, bool ALIGN_EPI = true, bool SP2 = true>
; DI void gemm_phase(LAS unsigned char* lds, const Gemm g, const Sched& S, const Epi& E) {
;     ...
;             PG8_WAIT_V(8); PG8_WAIT_L(0); PG8_BAR; PG8_MMA(1, 0, At, B0); PG8_MMA(1, 1, At, B1); PG8_BAR; PG8_SCHED;
;             PG8_LDB(B0, 1, 0); PG8_LDB(B1, 1, 1); PG8_SCHED; PG8_LDA(At, 1, 0); PG8_STAGE(PG8_SA(0, 1), a2 + hstepA, voffA);
;             PG8_WAIT_V(8); PG8_WAIT_L(0); PG8_BAR; PG8_MMA(0, 0, At, B0); PG8_MMA(0, 1, At, B1); PG8_BAR; PG8_SCHED;
	s_waitcnt lgkmcnt(0)
	v_mfma_f32_16x16x32_bf16 v[60:63], v[140:143], v[178:181], v[60:63]
	v_mfma_f32_16x16x32_bf16 v[56:59], v[148:151], v[178:181], v[56:59]
	v_mfma_f32_16x16x32_bf16 v[48:51], v[140:143], v[186:189], v[48:51]
	v_mfma_f32_16x16x32_bf16 v[40:43], v[148:151], v[186:189], v[40:43]
	v_mfma_f32_16x16x32_bf16 v[32:35], v[140:143], v[194:197], v[32:35]
	v_mfma_f32_16x16x32_bf16 v[24:27], v[148:151], v[194:197], v[24:27]
	v_mfma_f32_16x16x32_bf16 v[16:19], v[140:143], v[202:205], v[16:19]
	v_mfma_f32_16x16x32_bf16 v[8:11], v[148:151], v[202:205], v[8:11]
	v_mfma_f32_16x16x32_bf16 v[60:63], v[144:147], v[182:185], v[60:63]
	v_mfma_f32_16x16x32_bf16 v[56:59], v[152:155], v[182:185], v[56:59]
	v_mfma_f32_16x16x32_bf16 v[48:51], v[144:147], v[190:193], v[48:51]
	v_mfma_f32_16x16x32_bf16 v[40:43], v[152:155], v[190:193], v[40:43]
	v_mfma_f32_16x16x32_bf16 v[32:35], v[144:147], v[198:201], v[32:35]
	v_mfma_f32_16x16x32_bf16 v[24:27], v[152:155], v[198:201], v[24:27]
	v_mfma_f32_16x16x32_bf16 v[16:19], v[144:147], v[206:209], v[16:19]
	v_mfma_f32_16x16x32_bf16 v[8:11], v[152:155], v[206:209], v[8:11]
	v_mfma_f32_16x16x32_bf16 v[52:55], v[156:159], v[178:181], v[52:55]
	v_mfma_f32_16x16x32_bf16 v[44:47], v[170:173], v[178:181], v[44:47]
	v_mfma_f32_16x16x32_bf16 v[36:39], v[156:159], v[186:189], v[36:39]
	v_mfma_f32_16x16x32_bf16 v[28:31], v[170:173], v[186:189], v[28:31]
	v_mfma_f32_16x16x32_bf16 v[20:23], v[156:159], v[194:197], v[20:23]
	v_mfma_f32_16x16x32_bf16 v[12:15], v[170:173], v[194:197], v[12:15]
	v_mfma_f32_16x16x32_bf16 v[4:7], v[156:159], v[202:205], v[4:7]
	v_mfma_f32_16x16x32_bf16 v[0:3], v[170:173], v[202:205], v[0:3]
	v_mfma_f32_16x16x32_bf16 v[52:55], v[166:169], v[182:185], v[52:55]
	v_mfma_f32_16x16x32_bf16 v[44:47], v[174:177], v[182:185], v[44:47]
	v_mfma_f32_16x16x32_bf16 v[36:39], v[166:169], v[190:193], v[36:39]
	v_mfma_f32_16x16x32_bf16 v[28:31], v[174:177], v[190:193], v[28:31]
	v_mfma_f32_16x16x32_bf16 v[20:23], v[166:169], v[198:201], v[20:23]
	v_mfma_f32_16x16x32_bf16 v[12:15], v[174:177], v[198:201], v[12:15]
	v_mfma_f32_16x16x32_bf16 v[4:7], v[166:169], v[206:209], v[4:7]
	v_mfma_f32_16x16x32_bf16 v[0:3], v[174:177], v[206:209], v[0:3]
	s_barrier
	s_add_i32 s91, 0, 0x18000
	s_add_i32 s95, 0, 0x1c000
	v_add_u32_e32 v152, s91, v161
	v_add_u32_e32 v174, s95, v161
	ds_read_b128 v[140:143], v152
	ds_read_b128 v[144:147], v152 offset:1024
	ds_read_b128 v[148:151], v152 offset:2048
	ds_read_b128 v[152:155], v152 offset:3072
	ds_read_b128 v[156:159], v174
	ds_read_b128 v[166:169], v174 offset:1024
	ds_read_b128 v[170:173], v174 offset:2048
	ds_read_b128 v[174:177], v174 offset:3072
	s_add_u32 s62, s62, 0x80000
	s_addc_u32 s63, s63, 0
	s_mov_b32 m0, s75
	v_lshl_add_u64 v[218:219], s[62:63], 0, v[128:129]
	ds_read_b128 v[178:181], v165 offset:32768
	ds_read_b128 v[182:185], v165 offset:33792
	ds_read_b128 v[186:189], v165 offset:34816
	ds_read_b128 v[190:193], v165 offset:35840
	ds_read_b128 v[194:197], v165 offset:36864
	ds_read_b128 v[198:201], v165 offset:37888
	ds_read_b128 v[202:205], v165 offset:38912
	ds_read_b128 v[206:209], v165 offset:39936
	global_load_lds_dwordx4 v[218:219], off
	v_lshl_add_u64 v[218:219], s[62:63], 0, v[130:131]
	s_mov_b32 m0, s76
	s_nop 0
	global_load_lds_dwordx4 v[218:219], off
	s_waitcnt vmcnt(8)
	s_waitcnt lgkmcnt(0)
	s_barrier
	s_waitcnt lgkmcnt(0)
	v_mfma_f32_16x16x32_bf16 v[124:127], v[140:143], v[178:181], v[124:127]
	v_mfma_f32_16x16x32_bf16 v[120:123], v[148:151], v[178:181], v[120:123]
	v_mfma_f32_16x16x32_bf16 v[112:115], v[140:143], v[186:189], v[112:115]
	v_mfma_f32_16x16x32_bf16 v[104:107], v[148:151], v[186:189], v[104:107]
	v_mfma_f32_16x16x32_bf16 v[96:99], v[140:143], v[194:197], v[96:99]
	v_mfma_f32_16x16x32_bf16 v[88:91], v[148:151], v[194:197], v[88:91]
	v_mfma_f32_16x16x32_bf16 v[80:83], v[140:143], v[202:205], v[80:83]
	v_mfma_f32_16x16x32_bf16 v[72:75], v[148:151], v[202:205], v[72:75]
	v_mfma_f32_16x16x32_bf16 v[124:127], v[144:147], v[182:185], v[124:127]
	v_mfma_f32_16x16x32_bf16 v[120:123], v[152:155], v[182:185], v[120:123]
	v_mfma_f32_16x16x32_bf16 v[112:115], v[144:147], v[190:193], v[112:115]
	v_mfma_f32_16x16x32_bf16 v[104:107], v[152:155], v[190:193], v[104:107]
	v_mfma_f32_16x16x32_bf16 v[96:99], v[144:147], v[198:201], v[96:99]
	v_mfma_f32_16x16x32_bf16 v[88:91], v[152:155], v[198:201], v[88:91]
	v_mfma_f32_16x16x32_bf16 v[80:83], v[144:147], v[206:209], v[80:83]
	v_mfma_f32_16x16x32_bf16 v[72:75], v[152:155], v[206:209], v[72:75]
	v_mfma_f32_16x16x32_bf16 v[116:119], v[156:159], v[178:181], v[116:119]
	v_mfma_f32_16x16x32_bf16 v[108:111], v[170:173], v[178:181], v[108:111]
	v_mfma_f32_16x16x32_bf16 v[100:103], v[156:159], v[186:189], v[100:103]
	v_mfma_f32_16x16x32_bf16 v[92:95], v[170:173], v[186:189], v[92:95]
	v_mfma_f32_16x16x32_bf16 v[84:87], v[156:159], v[194:197], v[84:87]
	v_mfma_f32_16x16x32_bf16 v[76:79], v[170:173], v[194:197], v[76:79]
	v_mfma_f32_16x16x32_bf16 v[68:71], v[156:159], v[202:205], v[68:71]
	v_mfma_f32_16x16x32_bf16 v[64:67], v[170:173], v[202:205], v[64:67]
	v_mfma_f32_16x16x32_bf16 v[116:119], v[166:169], v[182:185], v[116:119]
	v_mfma_f32_16x16x32_bf16 v[108:111], v[174:177], v[182:185], v[108:111]
	v_mfma_f32_16x16x32_bf16 v[100:103], v[166:169], v[190:193], v[100:103]
	v_mfma_f32_16x16x32_bf16 v[92:95], v[174:177], v[190:193], v[92:95]
	v_mfma_f32_16x16x32_bf16 v[84:87], v[166:169], v[198:201], v[84:87]
	v_mfma_f32_16x16x32_bf16 v[76:79], v[174:177], v[198:201], v[76:79]
	v_mfma_f32_16x16x32_bf16 v[68:71], v[166:169], v[206:209], v[68:71]
	v_mfma_f32_16x16x32_bf16 v[64:67], v[174:177], v[206:209], v[64:67]
	s_barrier
; #define PG8_STAGE(bufoff, gbase, voff) do { _Pragma("unroll") for (int _i = 0; _i < 2; ++_i) \
;         __builtin_amdgcn_global_load_lds((const unsigned*)((const char*)(gbase) + (voff)[_i]), (LAS unsigned*)(lds + (bufoff) + ldsw + _i * 8192), 16, 0, 0); } while (0)
; #define PG8_LDA(dst, b, h) do { _Pragma("unroll") for (int m = 0; m < 4; ++m) _Pragma("unroll") for (int k = 0; k < 2; ++k) dst[m][k] = *(const LAS bf16x8*)(lds + PG8_SA(b, h) + aoff + m * 2048 + k * 1024); } while (0)
; #define PG8_MMA(ai, bj, At, Bt) do { __builtin_amdgcn_s_setprio(1); _Pragma("unroll") for (int m = 0; m < 4; ++m) _Pragma("unroll") for (int n = 0; n < 2; ++n) _Pragma("unroll") for (int k = 0; k < 2; ++k) \
;         acc[ai][bj][m][n] = __builtin_amdgcn_mfma_f32_16x16x32_bf16(Bt[n][k], At[m][k], acc[ai][bj][m][n], 0, 0, 0); __builtin_amdgcn_s_setprio(0); } while (0)
; #define PG8_WAIT_V(n) asm volatile("s_waitcnt vmcnt(" #n ")" ::: "memory")
; #define PG8_WAIT_L(n) asm volatile("s_waitcnt lgkmcnt(" #n ")" ::: "memory")
; #define PG8_BAR __builtin_amdgcn_s_barrier()
; #define PG8_SCHED __builtin_amdgcn_sched_barrier(0)
; template <class Epi, class Sched, bool ALIGN_EPI = true, bool SP2 = true>
; DI void gemm_phase(LAS unsigned char* lds, const Gemm g, const Sched& S, const Epi& E) {
;     ...
;         for (int t = 0; t < nt; t += 2) {
;             const bool last = (t == nt - 2);
;     ...
;             PG8_LDA(At, 1, 1); PG8_STAGE(PG8_SB(1, 0), b3, voffB); PG8_STAGE(PG8_SB(1, 1), b3 + hstepB, voffB); PG8_STAGE(PG8_SA(1, 0), a3, voffA);
;             PG8_WAIT_V(8); PG8_WAIT_L(0); PG8_BAR; PG8_MMA(1, 0, At, B0); PG8_MMA(1, 1, At, B1); PG8_BAR; PG8_SCHED;
	s_add_i32 s62, s91, s72
	v_lshl_add_u64 v[210:211], v[210:211], 0, s[10:11]
	s_mov_b32 m0, s62
	ds_read_b128 v[178:181], v165 offset:49152
	ds_read_b128 v[182:185], v165 offset:50176
	ds_read_b128 v[186:189], v165 offset:51200
	ds_read_b128 v[190:193], v165 offset:52224
	ds_read_b128 v[194:197], v165 offset:53248
	ds_read_b128 v[198:201], v165 offset:54272
	ds_read_b128 v[202:205], v165 offset:55296
	ds_read_b128 v[206:209], v165 offset:56320
	global_load_lds_dwordx4 v[210:211], off
	s_add_i32 m0, s62, 0x2000
	s_add_u32 s60, s60, 0x80080
	v_lshl_add_u64 v[210:211], v[212:213], 0, s[10:11]
	s_addc_u32 s61, s61, 0
	s_add_i32 s62, s95, s72
	global_load_lds_dwordx4 v[210:211], off
	v_lshl_add_u64 v[210:211], s[60:61], 0, v[128:129]
	s_mov_b32 m0, s62
	s_nop 0
	global_load_lds_dwordx4 v[210:211], off
	v_lshl_add_u64 v[210:211], s[60:61], 0, v[130:131]
	s_add_i32 m0, s62, 0x2000
	s_nop 0
	global_load_lds_dwordx4 v[210:211], off
	v_lshl_add_u64 v[210:211], v[214:215], 0, s[10:11]
	s_mov_b32 m0, s79
	s_nop 0
	global_load_lds_dwordx4 v[210:211], off
	v_lshl_add_u64 v[210:211], v[216:217], 0, s[10:11]
	s_mov_b32 m0, s81
	s_nop 0
	global_load_lds_dwordx4 v[210:211], off
	s_waitcnt vmcnt(8)
	s_waitcnt lgkmcnt(0)
	s_barrier
	s_waitcnt lgkmcnt(0)
	v_mfma_f32_16x16x32_bf16 v[60:63], v[140:143], v[178:181], v[60:63]
	v_mfma_f32_16x16x32_bf16 v[56:59], v[148:151], v[178:181], v[56:59]
	v_mfma_f32_16x16x32_bf16 v[48:51], v[140:143], v[186:189], v[48:51]
	v_mfma_f32_16x16x32_bf16 v[40:43], v[148:151], v[186:189], v[40:43]
	v_mfma_f32_16x16x32_bf16 v[32:35], v[140:143], v[194:197], v[32:35]
	v_mfma_f32_16x16x32_bf16 v[24:27], v[148:151], v[194:197], v[24:27]
	v_mfma_f32_16x16x32_bf16 v[16:19], v[140:143], v[202:205], v[16:19]
	v_mfma_f32_16x16x32_bf16 v[8:11], v[148:151], v[202:205], v[8:11]
	v_mfma_f32_16x16x32_bf16 v[60:63], v[144:147], v[182:185], v[60:63]
	v_mfma_f32_16x16x32_bf16 v[56:59], v[152:155], v[182:185], v[56:59]
	v_mfma_f32_16x16x32_bf16 v[48:51], v[144:147], v[190:193], v[48:51]
	v_mfma_f32_16x16x32_bf16 v[40:43], v[152:155], v[190:193], v[40:43]
	v_mfma_f32_16x16x32_bf16 v[32:35], v[144:147], v[198:201], v[32:35]
	v_mfma_f32_16x16x32_bf16 v[24:27], v[152:155], v[198:201], v[24:27]
	v_mfma_f32_16x16x32_bf16 v[16:19], v[144:147], v[206:209], v[16:19]
	v_mfma_f32_16x16x32_bf16 v[8:11], v[152:155], v[206:209], v[8:11]
	v_mfma_f32_16x16x32_bf16 v[52:55], v[156:159], v[178:181], v[52:55]
	v_mfma_f32_16x16x32_bf16 v[44:47], v[170:173], v[178:181], v[44:47]
	v_mfma_f32_16x16x32_bf16 v[36:39], v[156:159], v[186:189], v[36:39]
	v_mfma_f32_16x16x32_bf16 v[28:31], v[170:173], v[186:189], v[28:31]
	v_mfma_f32_16x16x32_bf16 v[20:23], v[156:159], v[194:197], v[20:23]
	v_mfma_f32_16x16x32_bf16 v[12:15], v[170:173], v[194:197], v[12:15]
	v_mfma_f32_16x16x32_bf16 v[4:7], v[156:159], v[202:205], v[4:7]
	v_mfma_f32_16x16x32_bf16 v[0:3], v[170:173], v[202:205], v[0:3]
	v_mfma_f32_16x16x32_bf16 v[52:55], v[166:169], v[182:185], v[52:55]
	v_mfma_f32_16x16x32_bf16 v[44:47], v[174:177], v[182:185], v[44:47]
	v_mfma_f32_16x16x32_bf16 v[36:39], v[166:169], v[190:193], v[36:39]
	v_mfma_f32_16x16x32_bf16 v[28:31], v[174:177], v[190:193], v[28:31]
	v_mfma_f32_16x16x32_bf16 v[20:23], v[166:169], v[198:201], v[20:23]
	v_mfma_f32_16x16x32_bf16 v[12:15], v[174:177], v[198:201], v[12:15]
	v_mfma_f32_16x16x32_bf16 v[4:7], v[166:169], v[206:209], v[4:7]
	v_mfma_f32_16x16x32_bf16 v[0:3], v[174:177], v[206:209], v[0:3]
	s_barrier
	s_add_i32 s94, s94, 2
	s_add_u32 s58, s58, 0x100
	s_addc_u32 s59, s59, 0
	s_add_u32 s92, s92, 0x100
	s_addc_u32 s93, s93, 0
	s_cmp_gt_u32 s94, 29
	s_cbranch_scc0 .LBB0_619
	s_and_b64 vcc, exec, s[12:13]
	s_cbranch_vccz .LBB0_622
	s_barrier

; #define PG8_STAGE(bufoff, gbase, voff) do { _Pragma("unroll") for (int _i = 0; _i < 2; ++_i) \
;         __builtin_amdgcn_global_load_lds((const unsigned*)((const char*)(gbase) + (voff)[_i]), (LAS unsigned*)(lds + (bufoff) + ldsw + _i * 8192), 16, 0, 0); } while (0)
; #define PG8_LDA(dst, b, h) do { _Pragma("unroll") for (int m = 0; m < 4; ++m) _Pragma("unroll") for (int k = 0; k < 2; ++k) dst[m][k] = *(const LAS bf16x8*)(lds + PG8_SA(b, h) + aoff + m * 2048 + k * 1024); } while (0)
; #define PG8_LDB(dst, b, h) do { _Pragma("unroll") for (int n = 0; n < 2; ++n) _Pragma("unroll") for (int k = 0; k < 2; ++k) dst[n][k] = *(const LAS bf16x8*)(lds + PG8_SB(b, h) + boff + n * 2048 + k * 1024); } while (0)
; #define PG8_MMA(ai, bj, At, Bt) do { __builtin_amdgcn_s_setprio(1); _Pragma("unroll") for (int m = 0; m < 4; ++m) _Pragma("unroll") for (int n = 0; n < 2; ++n) _Pragma("unroll") for (int k = 0; k < 2; ++k) \
;         acc[ai][bj][m][n] = __builtin_amdgcn_mfma_f32_16x16x32_bf16(Bt[n][k], At[m][k], acc[ai][bj][m][n], 0, 0, 0); __builtin_amdgcn_s_setprio(0); } while (0)
; #define PG8_WAIT_V(n) asm volatile("s_waitcnt vmcnt(" #n ")" ::: "memory")
; #define PG8_WAIT_L(n) asm volatile("s_waitcnt lgkmcnt(" #n ")" ::: "memory")
; #define PG8_BAR __builtin_amdgcn_s_barrier()
; #define PG8_SCHED __builtin_amdgcn_sched_barrier(0)
; template <class Epi, class Sched, bool ALIGN_EPI = true, bool SP2 = true>
; DI void gemm_phase(LAS unsigned char* lds, const Gemm g, const Sched& S, const Epi& E) {
;     ...
;             const bool last = (t == nt - 2);
;             const char* a1 = cA + (size_t)(t + 1) * kstep;
;             const char* a2 = last ? nA : cA + (size_t)(t + 2) * kstep; const char* b2 = last ? nB : cB + (size_t)(t + 2) * kstep;
;             const char* a3 = a2 + kstep; const char* b3 = b2 + kstep;
;             PG8_LDB(B0, 0, 0); PG8_LDB(B1, 0, 1); PG8_SCHED; PG8_LDA(At, 0, 0); PG8_STAGE(PG8_SA(1, 1), a1 + hstepA, voffA);
;             PG8_WAIT_V(8); PG8_WAIT_L(0); PG8_BAR; PG8_MMA(0, 0, At, B0); PG8_MMA(0, 1, At, B1); PG8_BAR; PG8_SCHED;
;             PG8_LDA(At, 0, 1); PG8_STAGE(PG8_SB(0, 0), b2, voffB); PG8_STAGE(PG8_SB(0, 1), b2 + hstepB, voffB); PG8_STAGE(PG8_SA(0, 0), a2, voffA);
.LBB0_773:
	v_add_u32_e32 v170, s92, v178
	v_add_u32_e32 v193, s93, v178
	ds_read_b128 v[158:161], v170
	ds_read_b128 v[162:165], v170 offset:1024
	ds_read_b128 v[166:169], v170 offset:2048
	ds_read_b128 v[170:173], v170 offset:3072
	ds_read_b128 v[174:177], v193
	ds_read_b128 v[194:197], v193 offset:1024
	ds_read_b128 v[198:201], v193 offset:2048
	ds_read_b128 v[202:205], v193 offset:3072
	s_add_u32 s66, s10, 0xfff80080
	s_addc_u32 s67, s11, -1
	s_cmp_eq_u32 s97, 28
	s_cselect_b32 s73, s55, s67
	s_cselect_b32 s72, s63, s66
	s_cselect_b32 s67, s57, s96
	s_cselect_b32 s66, s65, s95
	v_lshl_add_u64 v[240:241], s[10:11], 0, v[150:151]
	s_add_i32 m0, s78, 0xc000
	ds_read_b128 v[206:209], v190
	ds_read_b128 v[210:213], v190 offset:1024
	ds_read_b128 v[214:217], v190 offset:2048
	ds_read_b128 v[218:221], v190 offset:3072
	ds_read_b128 v[222:225], v190 offset:4096
	ds_read_b128 v[228:231], v190 offset:5120
	ds_read_b128 v[232:235], v190 offset:6144
	ds_read_b128 v[236:239], v190 offset:7168
	global_load_lds_dwordx4 v[240:241], off
	v_lshl_add_u64 v[240:241], s[10:11], 0, v[152:153]
	s_add_i32 m0, s78, 0xe000
	s_nop 0
	global_load_lds_dwordx4 v[240:241], off
	s_waitcnt vmcnt(8)
	s_waitcnt lgkmcnt(0)
	s_barrier
	s_waitcnt lgkmcnt(0)
	v_mfma_f32_16x16x32_bf16 v[124:127], v[158:161], v[206:209], v[124:127]
	v_mfma_f32_16x16x32_bf16 v[120:123], v[166:169], v[206:209], v[120:123]
	v_mfma_f32_16x16x32_bf16 v[108:111], v[158:161], v[214:217], v[108:111]
	v_mfma_f32_16x16x32_bf16 v[104:107], v[166:169], v[214:217], v[104:107]
	v_mfma_f32_16x16x32_bf16 v[92:95], v[158:161], v[222:225], v[92:95]
	v_mfma_f32_16x16x32_bf16 v[88:91], v[166:169], v[222:225], v[88:91]
	v_mfma_f32_16x16x32_bf16 v[76:79], v[158:161], v[232:235], v[76:79]
	v_mfma_f32_16x16x32_bf16 v[72:75], v[166:169], v[232:235], v[72:75]
	v_mfma_f32_16x16x32_bf16 v[124:127], v[162:165], v[210:213], v[124:127]
	v_mfma_f32_16x16x32_bf16 v[120:123], v[170:173], v[210:213], v[120:123]
	v_mfma_f32_16x16x32_bf16 v[108:111], v[162:165], v[218:221], v[108:111]
	v_mfma_f32_16x16x32_bf16 v[104:107], v[170:173], v[218:221], v[104:107]
	v_mfma_f32_16x16x32_bf16 v[92:95], v[162:165], v[228:231], v[92:95]
	v_mfma_f32_16x16x32_bf16 v[88:91], v[170:173], v[228:231], v[88:91]
	v_mfma_f32_16x16x32_bf16 v[76:79], v[162:165], v[236:239], v[76:79]
	v_mfma_f32_16x16x32_bf16 v[72:75], v[170:173], v[236:239], v[72:75]
	v_mfma_f32_16x16x32_bf16 v[116:119], v[174:177], v[206:209], v[116:119]
	v_mfma_f32_16x16x32_bf16 v[112:115], v[198:201], v[206:209], v[112:115]
	v_mfma_f32_16x16x32_bf16 v[100:103], v[174:177], v[214:217], v[100:103]
	v_mfma_f32_16x16x32_bf16 v[96:99], v[198:201], v[214:217], v[96:99]
	v_mfma_f32_16x16x32_bf16 v[84:87], v[174:177], v[222:225], v[84:87]
	v_mfma_f32_16x16x32_bf16 v[80:83], v[198:201], v[222:225], v[80:83]
	v_mfma_f32_16x16x32_bf16 v[68:71], v[174:177], v[232:235], v[68:71]
	v_mfma_f32_16x16x32_bf16 v[64:67], v[198:201], v[232:235], v[64:67]
	v_mfma_f32_16x16x32_bf16 v[116:119], v[194:197], v[210:213], v[116:119]
	v_mfma_f32_16x16x32_bf16 v[112:115], v[202:205], v[210:213], v[112:115]
	v_mfma_f32_16x16x32_bf16 v[100:103], v[194:197], v[218:221], v[100:103]
	v_mfma_f32_16x16x32_bf16 v[96:99], v[202:205], v[218:221], v[96:99]
	v_mfma_f32_16x16x32_bf16 v[84:87], v[194:197], v[228:231], v[84:87]
	v_mfma_f32_16x16x32_bf16 v[80:83], v[202:205], v[228:231], v[80:83]
	v_mfma_f32_16x16x32_bf16 v[68:71], v[194:197], v[236:239], v[68:71]
	v_mfma_f32_16x16x32_bf16 v[64:67], v[202:205], v[236:239], v[64:67]
	s_barrier
	s_add_i32 s91, s92, s77
	v_lshl_add_u64 v[240:241], s[66:67], 0, v[130:131]
	s_mov_b32 m0, s91
	ds_read_b128 v[206:209], v190 offset:16384
	ds_read_b128 v[210:213], v190 offset:17408
	ds_read_b128 v[214:217], v190 offset:18432
	ds_read_b128 v[218:221], v190 offset:19456
	ds_read_b128 v[222:225], v190 offset:20480
	ds_read_b128 v[228:231], v190 offset:21504
	ds_read_b128 v[232:235], v190 offset:22528
	ds_read_b128 v[236:239], v190 offset:23552
	global_load_lds_dwordx4 v[240:241], off
	s_add_i32 m0, s91, 0x2000
	s_add_u32 vcc_lo, s66, 0x80000
	v_lshl_add_u64 v[242:243], s[66:67], 0, v[132:133]
	s_addc_u32 vcc_hi, s67, 0
	s_add_i32 s91, s93, s77
	global_load_lds_dwordx4 v[242:243], off
	v_lshl_add_u64 v[244:245], vcc, 0, v[130:131]
	s_mov_b32 m0, s91
	v_lshl_add_u64 v[246:247], s[72:73], 0, v[132:133]
	global_load_lds_dwordx4 v[244:245], off
	v_lshl_add_u64 v[244:245], vcc, 0, v[132:133]
	s_add_i32 m0, s91, 0x2000
	s_nop 0
	global_load_lds_dwordx4 v[244:245], off
	v_lshl_add_u64 v[244:245], s[72:73], 0, v[130:131]
	s_mov_b32 m0, s78
	s_nop 0
	global_load_lds_dwordx4 v[244:245], off
	s_mov_b32 m0, s79
	s_nop 0
	global_load_lds_dwordx4 v[246:247], off
	s_waitcnt vmcnt(8)
	s_waitcnt lgkmcnt(0)
	s_barrier
; #define PG8_STAGE(bufoff, gbase, voff) do { _Pragma("unroll") for (int _i = 0; _i < 2; ++_i) \
;         __builtin_amdgcn_global_load_lds((const unsigned*)((const char*)(gbase) + (voff)[_i]), (LAS unsigned*)(lds + (bufoff) + ldsw + _i * 8192), 16, 0, 0); } while (0)
; #define PG8_LDA(dst, b, h) do { _Pragma("unroll") for (int m = 0; m < 4; ++m) _Pragma("unroll") for (int k = 0; k < 2; ++k) dst[m][k] = *(const LAS bf16x8*)(lds + PG8_SA(b, h) + aoff + m * 2048 + k * 1024); } while (0)
; #define PG8_LDB(dst, b, h) do { _Pragma("unroll") for (int n = 0; n < 2; ++n) _Pragma("unroll") for (int k = 0; k < 2; ++k) dst[n][k] = *(const LAS bf16x8*)(lds + PG8_SB(b, h) + boff + n * 2048 + k * 1024); } while (0)
; #define PG8_MMA(ai, bj, At, Bt) do { __builtin_amdgcn_s_setprio(1); _Pragma("unroll") for (int m = 0; m < 4; ++m) _Pragma("unroll") for (int n = 0; n < 2; ++n) _Pragma("unroll") for (int k = 0; k < 2; ++k) \
;         acc[ai][bj][m][n] = __builtin_amdgcn_mfma_f32_16x16x32_bf16(Bt[n][k], At[m][k], acc[ai][bj][m][n], 0, 0, 0); __builtin_amdgcn_s_setprio(0); } while (0)
; #define PG8_WAIT_V(n) asm volatile("s_waitcnt vmcnt(" #n ")" ::: "memory")
; #define PG8_WAIT_L(n) asm volatile("s_waitcnt lgkmcnt(" #n ")" ::: "memory")
; #define PG8_BAR __builtin_amdgcn_s_barrier()
; #define PG8_SCHED __builtin_amdgcn_sched_barrier(0)
; template <class Epi, class Sched, bool ALIGN_EPI = true, bool SP2 = true>
; DI void gemm_phase(LAS unsigned char* lds, const Gemm g, const Sched& S, const Epi& E) {
;     ...
;             PG8_WAIT_V(8); PG8_WAIT_L(0); PG8_BAR; PG8_MMA(1, 0, At, B0); PG8_MMA(1, 1, At, B1); PG8_BAR; PG8_SCHED;
;             PG8_LDB(B0, 1, 0); PG8_LDB(B1, 1, 1); PG8_SCHED; PG8_LDA(At, 1, 0); PG8_STAGE(PG8_SA(0, 1), a2 + hstepA, voffA);
;             PG8_WAIT_V(8); PG8_WAIT_L(0); PG8_BAR; PG8_MMA(0, 0, At, B0); PG8_MMA(0, 1, At, B1); PG8_BAR; PG8_SCHED;
	s_waitcnt lgkmcnt(0)
	v_mfma_f32_16x16x32_bf16 v[60:63], v[158:161], v[206:209], v[60:63]
	v_mfma_f32_16x16x32_bf16 v[56:59], v[166:169], v[206:209], v[56:59]
	v_mfma_f32_16x16x32_bf16 v[44:47], v[158:161], v[214:217], v[44:47]
	v_mfma_f32_16x16x32_bf16 v[40:43], v[166:169], v[214:217], v[40:43]
	v_mfma_f32_16x16x32_bf16 v[28:31], v[158:161], v[222:225], v[28:31]
	v_mfma_f32_16x16x32_bf16 v[24:27], v[166:169], v[222:225], v[24:27]
	v_mfma_f32_16x16x32_bf16 v[12:15], v[158:161], v[232:235], v[12:15]
	v_mfma_f32_16x16x32_bf16 v[8:11], v[166:169], v[232:235], v[8:11]
	v_mfma_f32_16x16x32_bf16 v[60:63], v[162:165], v[210:213], v[60:63]
	v_mfma_f32_16x16x32_bf16 v[56:59], v[170:173], v[210:213], v[56:59]
	v_mfma_f32_16x16x32_bf16 v[44:47], v[162:165], v[218:221], v[44:47]
	v_mfma_f32_16x16x32_bf16 v[40:43], v[170:173], v[218:221], v[40:43]
	v_mfma_f32_16x16x32_bf16 v[28:31], v[162:165], v[228:231], v[28:31]
	v_mfma_f32_16x16x32_bf16 v[24:27], v[170:173], v[228:231], v[24:27]
	v_mfma_f32_16x16x32_bf16 v[12:15], v[162:165], v[236:239], v[12:15]
	v_mfma_f32_16x16x32_bf16 v[8:11], v[170:173], v[236:239], v[8:11]
	v_mfma_f32_16x16x32_bf16 v[52:55], v[174:177], v[206:209], v[52:55]
	v_mfma_f32_16x16x32_bf16 v[48:51], v[198:201], v[206:209], v[48:51]
	v_mfma_f32_16x16x32_bf16 v[36:39], v[174:177], v[214:217], v[36:39]
	v_mfma_f32_16x16x32_bf16 v[32:35], v[198:201], v[214:217], v[32:35]
	v_mfma_f32_16x16x32_bf16 v[20:23], v[174:177], v[222:225], v[20:23]
	v_mfma_f32_16x16x32_bf16 v[16:19], v[198:201], v[222:225], v[16:19]
	v_mfma_f32_16x16x32_bf16 v[4:7], v[174:177], v[232:235], v[4:7]
	v_mfma_f32_16x16x32_bf16 v[0:3], v[198:201], v[232:235], v[0:3]
	v_mfma_f32_16x16x32_bf16 v[52:55], v[194:197], v[210:213], v[52:55]
	v_mfma_f32_16x16x32_bf16 v[48:51], v[202:205], v[210:213], v[48:51]
	v_mfma_f32_16x16x32_bf16 v[36:39], v[194:197], v[218:221], v[36:39]
	v_mfma_f32_16x16x32_bf16 v[32:35], v[202:205], v[218:221], v[32:35]
	v_mfma_f32_16x16x32_bf16 v[20:23], v[194:197], v[228:231], v[20:23]
	v_mfma_f32_16x16x32_bf16 v[16:19], v[202:205], v[228:231], v[16:19]
	v_mfma_f32_16x16x32_bf16 v[4:7], v[194:197], v[236:239], v[4:7]
	v_mfma_f32_16x16x32_bf16 v[0:3], v[202:205], v[236:239], v[0:3]
	s_barrier
	s_add_i32 s91, 0, 0x18000
	s_add_i32 vcc_lo, 0, 0x1c000
	v_add_u32_e32 v170, s91, v178
	v_add_u32_e32 v193, vcc_lo, v178
	ds_read_b128 v[158:161], v170
	ds_read_b128 v[162:165], v170 offset:1024
	ds_read_b128 v[166:169], v170 offset:2048
	ds_read_b128 v[170:173], v170 offset:3072
	ds_read_b128 v[174:177], v193
	ds_read_b128 v[194:197], v193 offset:1024
	ds_read_b128 v[198:201], v193 offset:2048
	ds_read_b128 v[202:205], v193 offset:3072
	s_add_u32 s72, s72, 0x80000
	s_addc_u32 s73, s73, 0
	s_mov_b32 m0, s81
	v_lshl_add_u64 v[248:249], s[72:73], 0, v[130:131]
	ds_read_b128 v[206:209], v190 offset:32768
	ds_read_b128 v[210:213], v190 offset:33792
	ds_read_b128 v[214:217], v190 offset:34816
	ds_read_b128 v[218:221], v190 offset:35840
	ds_read_b128 v[222:225], v190 offset:36864
	ds_read_b128 v[228:231], v190 offset:37888
	ds_read_b128 v[232:235], v190 offset:38912
	ds_read_b128 v[236:239], v190 offset:39936
	global_load_lds_dwordx4 v[248:249], off
	v_lshl_add_u64 v[248:249], s[72:73], 0, v[132:133]
	s_mov_b32 m0, s84
	s_nop 0
	global_load_lds_dwordx4 v[248:249], off
	s_waitcnt vmcnt(8)
	s_waitcnt lgkmcnt(0)
	s_barrier
	s_waitcnt lgkmcnt(0)
	v_mfma_f32_16x16x32_bf16 v[124:127], v[158:161], v[206:209], v[124:127]
	v_mfma_f32_16x16x32_bf16 v[120:123], v[166:169], v[206:209], v[120:123]
	v_mfma_f32_16x16x32_bf16 v[108:111], v[158:161], v[214:217], v[108:111]
	v_mfma_f32_16x16x32_bf16 v[104:107], v[166:169], v[214:217], v[104:107]
	v_mfma_f32_16x16x32_bf16 v[92:95], v[158:161], v[222:225], v[92:95]
	v_mfma_f32_16x16x32_bf16 v[88:91], v[166:169], v[222:225], v[88:91]
	v_mfma_f32_16x16x32_bf16 v[76:79], v[158:161], v[232:235], v[76:79]
	v_mfma_f32_16x16x32_bf16 v[72:75], v[166:169], v[232:235], v[72:75]
	v_mfma_f32_16x16x32_bf16 v[124:127], v[162:165], v[210:213], v[124:127]
	v_mfma_f32_16x16x32_bf16 v[120:123], v[170:173], v[210:213], v[120:123]
	v_mfma_f32_16x16x32_bf16 v[108:111], v[162:165], v[218:221], v[108:111]
	v_mfma_f32_16x16x32_bf16 v[104:107], v[170:173], v[218:221], v[104:107]
	v_mfma_f32_16x16x32_bf16 v[92:95], v[162:165], v[228:231], v[92:95]
	v_mfma_f32_16x16x32_bf16 v[88:91], v[170:173], v[228:231], v[88:91]
	v_mfma_f32_16x16x32_bf16 v[76:79], v[162:165], v[236:239], v[76:79]
	v_mfma_f32_16x16x32_bf16 v[72:75], v[170:173], v[236:239], v[72:75]
	v_mfma_f32_16x16x32_bf16 v[116:119], v[174:177], v[206:209], v[116:119]
	v_mfma_f32_16x16x32_bf16 v[112:115], v[198:201], v[206:209], v[112:115]
	v_mfma_f32_16x16x32_bf16 v[100:103], v[174:177], v[214:217], v[100:103]
	v_mfma_f32_16x16x32_bf16 v[96:99], v[198:201], v[214:217], v[96:99]
	v_mfma_f32_16x16x32_bf16 v[84:87], v[174:177], v[222:225], v[84:87]
	v_mfma_f32_16x16x32_bf16 v[80:83], v[198:201], v[222:225], v[80:83]
	v_mfma_f32_16x16x32_bf16 v[68:71], v[174:177], v[232:235], v[68:71]
	v_mfma_f32_16x16x32_bf16 v[64:67], v[198:201], v[232:235], v[64:67]
	v_mfma_f32_16x16x32_bf16 v[116:119], v[194:197], v[210:213], v[116:119]
	v_mfma_f32_16x16x32_bf16 v[112:115], v[202:205], v[210:213], v[112:115]
	v_mfma_f32_16x16x32_bf16 v[100:103], v[194:197], v[218:221], v[100:103]
	v_mfma_f32_16x16x32_bf16 v[96:99], v[202:205], v[218:221], v[96:99]
	v_mfma_f32_16x16x32_bf16 v[84:87], v[194:197], v[228:231], v[84:87]
	v_mfma_f32_16x16x32_bf16 v[80:83], v[202:205], v[228:231], v[80:83]
	v_mfma_f32_16x16x32_bf16 v[68:71], v[194:197], v[236:239], v[68:71]
	v_mfma_f32_16x16x32_bf16 v[64:67], v[202:205], v[236:239], v[64:67]
	s_barrier
; #define PG8_STAGE(bufoff, gbase, voff) do { _Pragma("unroll") for (int _i = 0; _i < 2; ++_i) \
;         __builtin_amdgcn_global_load_lds((const unsigned*)((const char*)(gbase) + (voff)[_i]), (LAS unsigned*)(lds + (bufoff) + ldsw + _i * 8192), 16, 0, 0); } while (0)
; #define PG8_LDA(dst, b, h) do { _Pragma("unroll") for (int m = 0; m < 4; ++m) _Pragma("unroll") for (int k = 0; k < 2; ++k) dst[m][k] = *(const LAS bf16x8*)(lds + PG8_SA(b, h) + aoff + m * 2048 + k * 1024); } while (0)
; #define PG8_MMA(ai, bj, At, Bt) do { __builtin_amdgcn_s_setprio(1); _Pragma("unroll") for (int m = 0; m < 4; ++m) _Pragma("unroll") for (int n = 0; n < 2; ++n) _Pragma("unroll") for (int k = 0; k < 2; ++k) \
;         acc[ai][bj][m][n] = __builtin_amdgcn_mfma_f32_16x16x32_bf16(Bt[n][k], At[m][k], acc[ai][bj][m][n], 0, 0, 0); __builtin_amdgcn_s_setprio(0); } while (0)
; #define PG8_WAIT_V(n) asm volatile("s_waitcnt vmcnt(" #n ")" ::: "memory")
; #define PG8_WAIT_L(n) asm volatile("s_waitcnt lgkmcnt(" #n ")" ::: "memory")
; #define PG8_BAR __builtin_amdgcn_s_barrier()
; #define PG8_SCHED __builtin_amdgcn_sched_barrier(0)
; template <class Epi, class Sched, bool ALIGN_EPI = true, bool SP2 = true>
; DI void gemm_phase(LAS unsigned char* lds, const Gemm g, const Sched& S, const Epi& E) {
;     ...
;         for (int t = 0; t < nt; t += 2) {
;             const bool last = (t == nt - 2);
;     ...
;             PG8_LDA(At, 1, 1); PG8_STAGE(PG8_SB(1, 0), b3, voffB); PG8_STAGE(PG8_SB(1, 1), b3 + hstepB, voffB); PG8_STAGE(PG8_SA(1, 0), a3, voffA);
;             PG8_WAIT_V(8); PG8_WAIT_L(0); PG8_BAR; PG8_MMA(1, 0, At, B0); PG8_MMA(1, 1, At, B1); PG8_BAR; PG8_SCHED;
	s_add_i32 s72, s91, s77
	v_lshl_add_u64 v[240:241], v[240:241], 0, s[42:43]
	s_mov_b32 m0, s72
	ds_read_b128 v[206:209], v190 offset:49152
	ds_read_b128 v[210:213], v190 offset:50176
	ds_read_b128 v[214:217], v190 offset:51200
	ds_read_b128 v[218:221], v190 offset:52224
	ds_read_b128 v[222:225], v190 offset:53248
	ds_read_b128 v[228:231], v190 offset:54272
	ds_read_b128 v[232:235], v190 offset:55296
	ds_read_b128 v[236:239], v190 offset:56320
	global_load_lds_dwordx4 v[240:241], off
	s_add_i32 m0, s72, 0x2000
	s_add_u32 s66, s66, 0x80080
	v_lshl_add_u64 v[240:241], v[242:243], 0, s[42:43]
	s_addc_u32 s67, s67, 0
	s_add_i32 s72, vcc_lo, s77
	global_load_lds_dwordx4 v[240:241], off
	v_lshl_add_u64 v[240:241], s[66:67], 0, v[130:131]
	s_mov_b32 m0, s72
	s_nop 0
	global_load_lds_dwordx4 v[240:241], off
	v_lshl_add_u64 v[240:241], s[66:67], 0, v[132:133]
	s_add_i32 m0, s72, 0x2000
	s_nop 0
	global_load_lds_dwordx4 v[240:241], off
	v_lshl_add_u64 v[240:241], v[244:245], 0, s[42:43]
	s_mov_b32 m0, s86
	s_nop 0
	global_load_lds_dwordx4 v[240:241], off
	v_lshl_add_u64 v[240:241], v[246:247], 0, s[42:43]
	s_mov_b32 m0, s87
	s_nop 0
	global_load_lds_dwordx4 v[240:241], off
	s_waitcnt vmcnt(8)
	s_waitcnt lgkmcnt(0)
	s_barrier
	s_waitcnt lgkmcnt(0)
	v_mfma_f32_16x16x32_bf16 v[60:63], v[158:161], v[206:209], v[60:63]
	v_mfma_f32_16x16x32_bf16 v[56:59], v[166:169], v[206:209], v[56:59]
	v_mfma_f32_16x16x32_bf16 v[44:47], v[158:161], v[214:217], v[44:47]
	v_mfma_f32_16x16x32_bf16 v[40:43], v[166:169], v[214:217], v[40:43]
	v_mfma_f32_16x16x32_bf16 v[28:31], v[158:161], v[222:225], v[28:31]
	v_mfma_f32_16x16x32_bf16 v[24:27], v[166:169], v[222:225], v[24:27]
	v_mfma_f32_16x16x32_bf16 v[12:15], v[158:161], v[232:235], v[12:15]
	v_mfma_f32_16x16x32_bf16 v[8:11], v[166:169], v[232:235], v[8:11]
	v_mfma_f32_16x16x32_bf16 v[60:63], v[162:165], v[210:213], v[60:63]
	v_mfma_f32_16x16x32_bf16 v[56:59], v[170:173], v[210:213], v[56:59]
	v_mfma_f32_16x16x32_bf16 v[44:47], v[162:165], v[218:221], v[44:47]
	v_mfma_f32_16x16x32_bf16 v[40:43], v[170:173], v[218:221], v[40:43]
	v_mfma_f32_16x16x32_bf16 v[28:31], v[162:165], v[228:231], v[28:31]
	v_mfma_f32_16x16x32_bf16 v[24:27], v[170:173], v[228:231], v[24:27]
	v_mfma_f32_16x16x32_bf16 v[12:15], v[162:165], v[236:239], v[12:15]
	v_mfma_f32_16x16x32_bf16 v[8:11], v[170:173], v[236:239], v[8:11]
	v_mfma_f32_16x16x32_bf16 v[52:55], v[174:177], v[206:209], v[52:55]
	v_mfma_f32_16x16x32_bf16 v[48:51], v[198:201], v[206:209], v[48:51]
	v_mfma_f32_16x16x32_bf16 v[36:39], v[174:177], v[214:217], v[36:39]
	v_mfma_f32_16x16x32_bf16 v[32:35], v[198:201], v[214:217], v[32:35]
	v_mfma_f32_16x16x32_bf16 v[20:23], v[174:177], v[222:225], v[20:23]
	v_mfma_f32_16x16x32_bf16 v[16:19], v[198:201], v[222:225], v[16:19]
	v_mfma_f32_16x16x32_bf16 v[4:7], v[174:177], v[232:235], v[4:7]
	v_mfma_f32_16x16x32_bf16 v[0:3], v[198:201], v[232:235], v[0:3]
	v_mfma_f32_16x16x32_bf16 v[52:55], v[194:197], v[210:213], v[52:55]
	v_mfma_f32_16x16x32_bf16 v[48:51], v[202:205], v[210:213], v[48:51]
	v_mfma_f32_16x16x32_bf16 v[36:39], v[194:197], v[218:221], v[36:39]
	v_mfma_f32_16x16x32_bf16 v[32:35], v[202:205], v[218:221], v[32:35]
	v_mfma_f32_16x16x32_bf16 v[20:23], v[194:197], v[228:231], v[20:23]
	v_mfma_f32_16x16x32_bf16 v[16:19], v[202:205], v[228:231], v[16:19]
	v_mfma_f32_16x16x32_bf16 v[4:7], v[194:197], v[236:239], v[4:7]
	v_mfma_f32_16x16x32_bf16 v[0:3], v[202:205], v[236:239], v[0:3]
	s_barrier
	s_add_i32 s97, s97, 2
	s_add_u32 s10, s10, 0x100
	s_addc_u32 s11, s11, 0
	s_add_u32 s95, s95, 0x100
	s_addc_u32 s96, s96, 0
	s_cmp_gt_u32 s97, 29
	s_cbranch_scc0 .LBB0_773
	s_and_b64 vcc, exec, s[44:45]
	s_cbranch_vccz .LBB0_776
	s_barrier

; #define PG8_STAGE(bufoff, gbase, voff) do { _Pragma("unroll") for (int _i = 0; _i < 2; ++_i) \
;         __builtin_amdgcn_global_load_lds((const unsigned*)((const char*)(gbase) + (voff)[_i]), (LAS unsigned*)(lds + (bufoff) + ldsw + _i * 8192), 16, 0, 0); } while (0)
; #define PG8_LDA(dst, b, h) do { _Pragma("unroll") for (int m = 0; m < 4; ++m) _Pragma("unroll") for (int k = 0; k < 2; ++k) dst[m][k] = *(const LAS bf16x8*)(lds + PG8_SA(b, h) + aoff + m * 2048 + k * 1024); } while (0)
; #define PG8_LDB(dst, b, h) do { _Pragma("unroll") for (int n = 0; n < 2; ++n) _Pragma("unroll") for (int k = 0; k < 2; ++k) dst[n][k] = *(const LAS bf16x8*)(lds + PG8_SB(b, h) + boff + n * 2048 + k * 1024); } while (0)
; #define PG8_MMA(ai, bj, At, Bt) do { __builtin_amdgcn_s_setprio(1); _Pragma("unroll") for (int m = 0; m < 4; ++m) _Pragma("unroll") for (int n = 0; n < 2; ++n) _Pragma("unroll") for (int k = 0; k < 2; ++k) \
;         acc[ai][bj][m][n] = __builtin_amdgcn_mfma_f32_16x16x32_bf16(Bt[n][k], At[m][k], acc[ai][bj][m][n], 0, 0, 0); __builtin_amdgcn_s_setprio(0); } while (0)
; #define PG8_WAIT_V(n) asm volatile("s_waitcnt vmcnt(" #n ")" ::: "memory")
; #define PG8_WAIT_L(n) asm volatile("s_waitcnt lgkmcnt(" #n ")" ::: "memory")
; #define PG8_BAR __builtin_amdgcn_s_barrier()
; #define PG8_SCHED __builtin_amdgcn_sched_barrier(0)
; template <class Epi, class Sched, bool ALIGN_EPI = true, bool SP2 = true>
; DI void gemm_phase(LAS unsigned char* lds, const Gemm g, const Sched& S, const Epi& E) {
;     ...
;             const bool last = (t == nt - 2);
;             const char* a1 = cA + (size_t)(t + 1) * kstep;
;             const char* a2 = last ? nA : cA + (size_t)(t + 2) * kstep; const char* b2 = last ? nB : cB + (size_t)(t + 2) * kstep;
;             const char* a3 = a2 + kstep; const char* b3 = b2 + kstep;
;             PG8_LDB(B0, 0, 0); PG8_LDB(B1, 0, 1); PG8_SCHED; PG8_LDA(At, 0, 0); PG8_STAGE(PG8_SA(1, 1), a1 + hstepA, voffA);
;             PG8_WAIT_V(8); PG8_WAIT_L(0); PG8_BAR; PG8_MMA(0, 0, At, B0); PG8_MMA(0, 1, At, B1); PG8_BAR; PG8_SCHED;
;             PG8_LDA(At, 0, 1); PG8_STAGE(PG8_SB(0, 0), b2, voffB); PG8_STAGE(PG8_SB(0, 1), b2 + hstepB, voffB); PG8_STAGE(PG8_SA(0, 0), a2, voffA);
.LBB0_909:
	ds_read_b128 v[128:131], v168
	ds_read_b128 v[132:135], v168 offset:1024
	ds_read_b128 v[154:157], v168 offset:2048
	ds_read_b128 v[158:161], v168 offset:3072
	ds_read_b128 v[176:179], v169
	ds_read_b128 v[180:183], v169 offset:1024
	ds_read_b128 v[184:187], v169 offset:2048
	ds_read_b128 v[188:191], v169 offset:3072
	s_add_u32 s18, s16, 0xfffc0080
	s_addc_u32 s19, s17, -1
	s_cmp_eq_u32 s72, 12
	s_cselect_b32 s69, s13, s19
	s_cselect_b32 s68, s15, s18
	s_cselect_b32 s19, s61, s71
	s_cselect_b32 s18, s63, s70
	v_lshl_add_u64 v[224:225], s[16:17], 0, v[146:147]
	s_add_i32 m0, s57, 0xc000
	ds_read_b128 v[192:195], v170
	ds_read_b128 v[196:199], v170 offset:1024
	ds_read_b128 v[200:203], v170 offset:2048
	ds_read_b128 v[204:207], v170 offset:3072
	ds_read_b128 v[208:211], v170 offset:4096
	ds_read_b128 v[212:215], v170 offset:5120
	ds_read_b128 v[216:219], v170 offset:6144
	ds_read_b128 v[220:223], v170 offset:7168
	global_load_lds_dwordx4 v[224:225], off
	v_lshl_add_u64 v[224:225], s[16:17], 0, v[148:149]
	s_add_i32 m0, s57, 0xe000
	s_nop 0
	global_load_lds_dwordx4 v[224:225], off
	s_waitcnt vmcnt(8)
	s_waitcnt lgkmcnt(0)
	s_barrier
	s_waitcnt lgkmcnt(0)
	v_mfma_f32_16x16x32_bf16 v[124:127], v[128:131], v[192:195], v[124:127]
	v_mfma_f32_16x16x32_bf16 v[120:123], v[154:157], v[192:195], v[120:123]
	v_mfma_f32_16x16x32_bf16 v[108:111], v[128:131], v[200:203], v[108:111]
	v_mfma_f32_16x16x32_bf16 v[104:107], v[154:157], v[200:203], v[104:107]
	v_mfma_f32_16x16x32_bf16 v[92:95], v[128:131], v[208:211], v[92:95]
	v_mfma_f32_16x16x32_bf16 v[88:91], v[154:157], v[208:211], v[88:91]
	v_mfma_f32_16x16x32_bf16 v[76:79], v[128:131], v[216:219], v[76:79]
	v_mfma_f32_16x16x32_bf16 v[72:75], v[154:157], v[216:219], v[72:75]
	v_mfma_f32_16x16x32_bf16 v[124:127], v[132:135], v[196:199], v[124:127]
	v_mfma_f32_16x16x32_bf16 v[120:123], v[158:161], v[196:199], v[120:123]
	v_mfma_f32_16x16x32_bf16 v[108:111], v[132:135], v[204:207], v[108:111]
	v_mfma_f32_16x16x32_bf16 v[104:107], v[158:161], v[204:207], v[104:107]
	v_mfma_f32_16x16x32_bf16 v[92:95], v[132:135], v[212:215], v[92:95]
	v_mfma_f32_16x16x32_bf16 v[88:91], v[158:161], v[212:215], v[88:91]
	v_mfma_f32_16x16x32_bf16 v[76:79], v[132:135], v[220:223], v[76:79]
	v_mfma_f32_16x16x32_bf16 v[72:75], v[158:161], v[220:223], v[72:75]
	v_mfma_f32_16x16x32_bf16 v[116:119], v[176:179], v[192:195], v[116:119]
	v_mfma_f32_16x16x32_bf16 v[112:115], v[184:187], v[192:195], v[112:115]
	v_mfma_f32_16x16x32_bf16 v[100:103], v[176:179], v[200:203], v[100:103]
	v_mfma_f32_16x16x32_bf16 v[96:99], v[184:187], v[200:203], v[96:99]
	v_mfma_f32_16x16x32_bf16 v[84:87], v[176:179], v[208:211], v[84:87]
	v_mfma_f32_16x16x32_bf16 v[80:83], v[184:187], v[208:211], v[80:83]
	v_mfma_f32_16x16x32_bf16 v[68:71], v[176:179], v[216:219], v[68:71]
	v_mfma_f32_16x16x32_bf16 v[64:67], v[184:187], v[216:219], v[64:67]
	v_mfma_f32_16x16x32_bf16 v[116:119], v[180:183], v[196:199], v[116:119]
	v_mfma_f32_16x16x32_bf16 v[112:115], v[188:191], v[196:199], v[112:115]
	v_mfma_f32_16x16x32_bf16 v[100:103], v[180:183], v[204:207], v[100:103]
	v_mfma_f32_16x16x32_bf16 v[96:99], v[188:191], v[204:207], v[96:99]
	v_mfma_f32_16x16x32_bf16 v[84:87], v[180:183], v[212:215], v[84:87]
	v_mfma_f32_16x16x32_bf16 v[80:83], v[188:191], v[212:215], v[80:83]
	v_mfma_f32_16x16x32_bf16 v[68:71], v[180:183], v[220:223], v[68:71]
	v_mfma_f32_16x16x32_bf16 v[64:67], v[188:191], v[220:223], v[64:67]
	s_barrier
	s_add_i32 s73, s95, s3
	v_lshl_add_u64 v[224:225], s[18:19], 0, v[138:139]
	s_mov_b32 m0, s73
	ds_read_b128 v[192:195], v170 offset:16384
	ds_read_b128 v[196:199], v170 offset:17408
	ds_read_b128 v[200:203], v170 offset:18432
	ds_read_b128 v[204:207], v170 offset:19456
	ds_read_b128 v[208:211], v170 offset:20480
	ds_read_b128 v[212:215], v170 offset:21504
	ds_read_b128 v[216:219], v170 offset:22528
	ds_read_b128 v[220:223], v170 offset:23552
	global_load_lds_dwordx4 v[224:225], off
	s_add_i32 m0, s73, 0x2000
	s_add_u32 s74, s18, 0x40000
	v_lshl_add_u64 v[228:229], s[18:19], 0, v[142:143]
	s_addc_u32 s75, s19, 0
	s_add_i32 s73, s96, s3
	global_load_lds_dwordx4 v[228:229], off
	v_lshl_add_u64 v[230:231], s[74:75], 0, v[138:139]
	s_mov_b32 m0, s73
	v_lshl_add_u64 v[232:233], s[68:69], 0, v[140:141]
	global_load_lds_dwordx4 v[230:231], off
	v_lshl_add_u64 v[230:231], s[74:75], 0, v[142:143]
	s_add_i32 m0, s73, 0x2000
	s_nop 0
	global_load_lds_dwordx4 v[230:231], off
	v_lshl_add_u64 v[230:231], s[68:69], 0, v[136:137]
	s_mov_b32 m0, s57
	s_nop 0
	global_load_lds_dwordx4 v[230:231], off
	s_mov_b32 m0, s76
	s_nop 0
	global_load_lds_dwordx4 v[232:233], off
	s_waitcnt vmcnt(8)
	s_waitcnt lgkmcnt(0)
	s_barrier
; #define PG8_STAGE(bufoff, gbase, voff) do { _Pragma("unroll") for (int _i = 0; _i < 2; ++_i) \
;         __builtin_amdgcn_global_load_lds((const unsigned*)((const char*)(gbase) + (voff)[_i]), (LAS unsigned*)(lds + (bufoff) + ldsw + _i * 8192), 16, 0, 0); } while (0)
; #define PG8_LDA(dst, b, h) do { _Pragma("unroll") for (int m = 0; m < 4; ++m) _Pragma("unroll") for (int k = 0; k < 2; ++k) dst[m][k] = *(const LAS bf16x8*)(lds + PG8_SA(b, h) + aoff + m * 2048 + k * 1024); } while (0)
; #define PG8_LDB(dst, b, h) do { _Pragma("unroll") for (int n = 0; n < 2; ++n) _Pragma("unroll") for (int k = 0; k < 2; ++k) dst[n][k] = *(const LAS bf16x8*)(lds + PG8_SB(b, h) + boff + n * 2048 + k * 1024); } while (0)
; #define PG8_MMA(ai, bj, At, Bt) do { __builtin_amdgcn_s_setprio(1); _Pragma("unroll") for (int m = 0; m < 4; ++m) _Pragma("unroll") for (int n = 0; n < 2; ++n) _Pragma("unroll") for (int k = 0; k < 2; ++k) \
;         acc[ai][bj][m][n] = __builtin_amdgcn_mfma_f32_16x16x32_bf16(Bt[n][k], At[m][k], acc[ai][bj][m][n], 0, 0, 0); __builtin_amdgcn_s_setprio(0); } while (0)
; #define PG8_WAIT_V(n) asm volatile("s_waitcnt vmcnt(" #n ")" ::: "memory")
; #define PG8_WAIT_L(n) asm volatile("s_waitcnt lgkmcnt(" #n ")" ::: "memory")
; #define PG8_BAR __builtin_amdgcn_s_barrier()
; #define PG8_SCHED __builtin_amdgcn_sched_barrier(0)
; template <class Epi, class Sched, bool ALIGN_EPI = true, bool SP2 = true>
; DI void gemm_phase(LAS unsigned char* lds, const Gemm g, const Sched& S, const Epi& E) {
;     ...
;             PG8_WAIT_V(8); PG8_WAIT_L(0); PG8_BAR; PG8_MMA(1, 0, At, B0); PG8_MMA(1, 1, At, B1); PG8_BAR; PG8_SCHED;
;             PG8_LDB(B0, 1, 0); PG8_LDB(B1, 1, 1); PG8_SCHED; PG8_LDA(At, 1, 0); PG8_STAGE(PG8_SA(0, 1), a2 + hstepA, voffA);
;             PG8_WAIT_V(8); PG8_WAIT_L(0); PG8_BAR; PG8_MMA(0, 0, At, B0); PG8_MMA(0, 1, At, B1); PG8_BAR; PG8_SCHED;
	s_waitcnt lgkmcnt(0)
	v_mfma_f32_16x16x32_bf16 v[60:63], v[128:131], v[192:195], v[60:63]
	v_mfma_f32_16x16x32_bf16 v[56:59], v[154:157], v[192:195], v[56:59]
	v_mfma_f32_16x16x32_bf16 v[44:47], v[128:131], v[200:203], v[44:47]
	v_mfma_f32_16x16x32_bf16 v[40:43], v[154:157], v[200:203], v[40:43]
	v_mfma_f32_16x16x32_bf16 v[28:31], v[128:131], v[208:211], v[28:31]
	v_mfma_f32_16x16x32_bf16 v[24:27], v[154:157], v[208:211], v[24:27]
	v_mfma_f32_16x16x32_bf16 v[12:15], v[128:131], v[216:219], v[12:15]
	v_mfma_f32_16x16x32_bf16 v[8:11], v[154:157], v[216:219], v[8:11]
	v_mfma_f32_16x16x32_bf16 v[60:63], v[132:135], v[196:199], v[60:63]
	v_mfma_f32_16x16x32_bf16 v[56:59], v[158:161], v[196:199], v[56:59]
	v_mfma_f32_16x16x32_bf16 v[44:47], v[132:135], v[204:207], v[44:47]
	v_mfma_f32_16x16x32_bf16 v[40:43], v[158:161], v[204:207], v[40:43]
	v_mfma_f32_16x16x32_bf16 v[28:31], v[132:135], v[212:215], v[28:31]
	v_mfma_f32_16x16x32_bf16 v[24:27], v[158:161], v[212:215], v[24:27]
	v_mfma_f32_16x16x32_bf16 v[12:15], v[132:135], v[220:223], v[12:15]
	v_mfma_f32_16x16x32_bf16 v[8:11], v[158:161], v[220:223], v[8:11]
	v_mfma_f32_16x16x32_bf16 v[52:55], v[176:179], v[192:195], v[52:55]
	v_mfma_f32_16x16x32_bf16 v[48:51], v[184:187], v[192:195], v[48:51]
	v_mfma_f32_16x16x32_bf16 v[36:39], v[176:179], v[200:203], v[36:39]
	v_mfma_f32_16x16x32_bf16 v[32:35], v[184:187], v[200:203], v[32:35]
	v_mfma_f32_16x16x32_bf16 v[20:23], v[176:179], v[208:211], v[20:23]
	v_mfma_f32_16x16x32_bf16 v[16:19], v[184:187], v[208:211], v[16:19]
	v_mfma_f32_16x16x32_bf16 v[4:7], v[176:179], v[216:219], v[4:7]
	v_mfma_f32_16x16x32_bf16 v[0:3], v[184:187], v[216:219], v[0:3]
	v_mfma_f32_16x16x32_bf16 v[52:55], v[180:183], v[196:199], v[52:55]
	v_mfma_f32_16x16x32_bf16 v[48:51], v[188:191], v[196:199], v[48:51]
	v_mfma_f32_16x16x32_bf16 v[36:39], v[180:183], v[204:207], v[36:39]
	v_mfma_f32_16x16x32_bf16 v[32:35], v[188:191], v[204:207], v[32:35]
	v_mfma_f32_16x16x32_bf16 v[20:23], v[180:183], v[212:215], v[20:23]
	v_mfma_f32_16x16x32_bf16 v[16:19], v[188:191], v[212:215], v[16:19]
	v_mfma_f32_16x16x32_bf16 v[4:7], v[180:183], v[220:223], v[4:7]
	v_mfma_f32_16x16x32_bf16 v[0:3], v[188:191], v[220:223], v[0:3]
	s_barrier
	s_add_i32 s73, 0, 0x18000
	v_add_u32_e32 v144, s73, v164
	s_add_i32 s74, 0, 0x1c000
	ds_read_b128 v[128:131], v144
	ds_read_b128 v[132:135], v144 offset:1024
	ds_read_b128 v[154:157], v144 offset:2048
	ds_read_b128 v[158:161], v144 offset:3072
	v_add_u32_e32 v144, s74, v164
	ds_read_b128 v[176:179], v144
	ds_read_b128 v[180:183], v144 offset:1024
	ds_read_b128 v[184:187], v144 offset:2048
	ds_read_b128 v[188:191], v144 offset:3072
	s_add_u32 s68, s68, 0x40000
	s_addc_u32 s69, s69, 0
	s_mov_b32 m0, s77
	v_lshl_add_u64 v[234:235], s[68:69], 0, v[136:137]
	ds_read_b128 v[192:195], v170 offset:32768
	ds_read_b128 v[196:199], v170 offset:33792
	ds_read_b128 v[200:203], v170 offset:34816
	ds_read_b128 v[204:207], v170 offset:35840
	ds_read_b128 v[208:211], v170 offset:36864
	ds_read_b128 v[212:215], v170 offset:37888
	ds_read_b128 v[216:219], v170 offset:38912
	ds_read_b128 v[220:223], v170 offset:39936
	global_load_lds_dwordx4 v[234:235], off
	v_lshl_add_u64 v[234:235], s[68:69], 0, v[140:141]
	s_mov_b32 m0, s78
	s_nop 0
	global_load_lds_dwordx4 v[234:235], off
	s_waitcnt vmcnt(8)
	s_waitcnt lgkmcnt(0)
	s_barrier
	s_waitcnt lgkmcnt(0)
	v_mfma_f32_16x16x32_bf16 v[124:127], v[128:131], v[192:195], v[124:127]
	v_mfma_f32_16x16x32_bf16 v[120:123], v[154:157], v[192:195], v[120:123]
	v_mfma_f32_16x16x32_bf16 v[108:111], v[128:131], v[200:203], v[108:111]
	v_mfma_f32_16x16x32_bf16 v[104:107], v[154:157], v[200:203], v[104:107]
	v_mfma_f32_16x16x32_bf16 v[92:95], v[128:131], v[208:211], v[92:95]
	v_mfma_f32_16x16x32_bf16 v[88:91], v[154:157], v[208:211], v[88:91]
	v_mfma_f32_16x16x32_bf16 v[76:79], v[128:131], v[216:219], v[76:79]
	v_mfma_f32_16x16x32_bf16 v[72:75], v[154:157], v[216:219], v[72:75]
	v_mfma_f32_16x16x32_bf16 v[124:127], v[132:135], v[196:199], v[124:127]
	v_mfma_f32_16x16x32_bf16 v[120:123], v[158:161], v[196:199], v[120:123]
	v_mfma_f32_16x16x32_bf16 v[108:111], v[132:135], v[204:207], v[108:111]
	v_mfma_f32_16x16x32_bf16 v[104:107], v[158:161], v[204:207], v[104:107]
	v_mfma_f32_16x16x32_bf16 v[92:95], v[132:135], v[212:215], v[92:95]
	v_mfma_f32_16x16x32_bf16 v[88:91], v[158:161], v[212:215], v[88:91]
	v_mfma_f32_16x16x32_bf16 v[76:79], v[132:135], v[220:223], v[76:79]
	v_mfma_f32_16x16x32_bf16 v[72:75], v[158:161], v[220:223], v[72:75]
	v_mfma_f32_16x16x32_bf16 v[116:119], v[176:179], v[192:195], v[116:119]
	v_mfma_f32_16x16x32_bf16 v[112:115], v[184:187], v[192:195], v[112:115]
	v_mfma_f32_16x16x32_bf16 v[100:103], v[176:179], v[200:203], v[100:103]
	v_mfma_f32_16x16x32_bf16 v[96:99], v[184:187], v[200:203], v[96:99]
	v_mfma_f32_16x16x32_bf16 v[84:87], v[176:179], v[208:211], v[84:87]
	v_mfma_f32_16x16x32_bf16 v[80:83], v[184:187], v[208:211], v[80:83]
	v_mfma_f32_16x16x32_bf16 v[68:71], v[176:179], v[216:219], v[68:71]
	v_mfma_f32_16x16x32_bf16 v[64:67], v[184:187], v[216:219], v[64:67]
	v_mfma_f32_16x16x32_bf16 v[116:119], v[180:183], v[196:199], v[116:119]
	v_mfma_f32_16x16x32_bf16 v[112:115], v[188:191], v[196:199], v[112:115]
	v_mfma_f32_16x16x32_bf16 v[100:103], v[180:183], v[204:207], v[100:103]
	v_mfma_f32_16x16x32_bf16 v[96:99], v[188:191], v[204:207], v[96:99]
	v_mfma_f32_16x16x32_bf16 v[84:87], v[180:183], v[212:215], v[84:87]
	v_mfma_f32_16x16x32_bf16 v[80:83], v[188:191], v[212:215], v[80:83]
	v_mfma_f32_16x16x32_bf16 v[68:71], v[180:183], v[220:223], v[68:71]
	v_mfma_f32_16x16x32_bf16 v[64:67], v[188:191], v[220:223], v[64:67]
	s_barrier
; #define PG8_STAGE(bufoff, gbase, voff) do { _Pragma("unroll") for (int _i = 0; _i < 2; ++_i) \
;         __builtin_amdgcn_global_load_lds((const unsigned*)((const char*)(gbase) + (voff)[_i]), (LAS unsigned*)(lds + (bufoff) + ldsw + _i * 8192), 16, 0, 0); } while (0)
; #define PG8_LDA(dst, b, h) do { _Pragma("unroll") for (int m = 0; m < 4; ++m) _Pragma("unroll") for (int k = 0; k < 2; ++k) dst[m][k] = *(const LAS bf16x8*)(lds + PG8_SA(b, h) + aoff + m * 2048 + k * 1024); } while (0)
; #define PG8_MMA(ai, bj, At, Bt) do { __builtin_amdgcn_s_setprio(1); _Pragma("unroll") for (int m = 0; m < 4; ++m) _Pragma("unroll") for (int n = 0; n < 2; ++n) _Pragma("unroll") for (int k = 0; k < 2; ++k) \
;         acc[ai][bj][m][n] = __builtin_amdgcn_mfma_f32_16x16x32_bf16(Bt[n][k], At[m][k], acc[ai][bj][m][n], 0, 0, 0); __builtin_amdgcn_s_setprio(0); } while (0)
; #define PG8_WAIT_V(n) asm volatile("s_waitcnt vmcnt(" #n ")" ::: "memory")
; #define PG8_WAIT_L(n) asm volatile("s_waitcnt lgkmcnt(" #n ")" ::: "memory")
; #define PG8_BAR __builtin_amdgcn_s_barrier()
; #define PG8_SCHED __builtin_amdgcn_sched_barrier(0)
; template <class Epi, class Sched, bool ALIGN_EPI = true, bool SP2 = true>
; DI void gemm_phase(LAS unsigned char* lds, const Gemm g, const Sched& S, const Epi& E) {
;     ...
;         for (int t = 0; t < nt; t += 2) {
;             const bool last = (t == nt - 2);
;     ...
;             PG8_LDA(At, 1, 1); PG8_STAGE(PG8_SB(1, 0), b3, voffB); PG8_STAGE(PG8_SB(1, 1), b3 + hstepB, voffB); PG8_STAGE(PG8_SA(1, 0), a3, voffA);
;             PG8_WAIT_V(8); PG8_WAIT_L(0); PG8_BAR; PG8_MMA(1, 0, At, B0); PG8_MMA(1, 1, At, B1); PG8_BAR; PG8_SCHED;
	s_add_i32 s68, s73, s3
	v_lshl_add_u64 v[224:225], v[224:225], 0, s[48:49]
	s_mov_b32 m0, s68
	ds_read_b128 v[192:195], v170 offset:49152
	ds_read_b128 v[196:199], v170 offset:50176
	ds_read_b128 v[200:203], v170 offset:51200
	ds_read_b128 v[204:207], v170 offset:52224
	ds_read_b128 v[208:211], v170 offset:53248
	ds_read_b128 v[212:215], v170 offset:54272
	ds_read_b128 v[216:219], v170 offset:55296
	ds_read_b128 v[220:223], v170 offset:56320
	global_load_lds_dwordx4 v[224:225], off
	s_add_i32 m0, s68, 0x2000
	s_add_u32 s18, s18, 0x40080
	v_lshl_add_u64 v[224:225], v[228:229], 0, s[48:49]
	s_addc_u32 s19, s19, 0
	s_add_i32 s68, s74, s3
	global_load_lds_dwordx4 v[224:225], off
	v_lshl_add_u64 v[224:225], s[18:19], 0, v[138:139]
	s_mov_b32 m0, s68
	s_nop 0
	global_load_lds_dwordx4 v[224:225], off
	v_lshl_add_u64 v[224:225], s[18:19], 0, v[142:143]
	s_add_i32 m0, s68, 0x2000
	s_nop 0
	global_load_lds_dwordx4 v[224:225], off
	v_lshl_add_u64 v[224:225], v[230:231], 0, s[48:49]
	s_mov_b32 m0, s86
	s_nop 0
	global_load_lds_dwordx4 v[224:225], off
	v_lshl_add_u64 v[224:225], v[232:233], 0, s[48:49]
	s_mov_b32 m0, s87
	s_nop 0
	global_load_lds_dwordx4 v[224:225], off
	s_waitcnt vmcnt(8)
	s_waitcnt lgkmcnt(0)
	s_barrier
	s_waitcnt lgkmcnt(0)
	v_mfma_f32_16x16x32_bf16 v[60:63], v[128:131], v[192:195], v[60:63]
	v_mfma_f32_16x16x32_bf16 v[56:59], v[154:157], v[192:195], v[56:59]
	v_mfma_f32_16x16x32_bf16 v[44:47], v[128:131], v[200:203], v[44:47]
	v_mfma_f32_16x16x32_bf16 v[40:43], v[154:157], v[200:203], v[40:43]
	v_mfma_f32_16x16x32_bf16 v[28:31], v[128:131], v[208:211], v[28:31]
	v_mfma_f32_16x16x32_bf16 v[24:27], v[154:157], v[208:211], v[24:27]
	v_mfma_f32_16x16x32_bf16 v[12:15], v[128:131], v[216:219], v[12:15]
	v_mfma_f32_16x16x32_bf16 v[8:11], v[154:157], v[216:219], v[8:11]
	v_mfma_f32_16x16x32_bf16 v[60:63], v[132:135], v[196:199], v[60:63]
	v_mfma_f32_16x16x32_bf16 v[56:59], v[158:161], v[196:199], v[56:59]
	v_mfma_f32_16x16x32_bf16 v[44:47], v[132:135], v[204:207], v[44:47]
	v_mfma_f32_16x16x32_bf16 v[40:43], v[158:161], v[204:207], v[40:43]
	v_mfma_f32_16x16x32_bf16 v[28:31], v[132:135], v[212:215], v[28:31]
	v_mfma_f32_16x16x32_bf16 v[24:27], v[158:161], v[212:215], v[24:27]
	v_mfma_f32_16x16x32_bf16 v[12:15], v[132:135], v[220:223], v[12:15]
	v_mfma_f32_16x16x32_bf16 v[8:11], v[158:161], v[220:223], v[8:11]
	v_mfma_f32_16x16x32_bf16 v[52:55], v[176:179], v[192:195], v[52:55]
	v_mfma_f32_16x16x32_bf16 v[48:51], v[184:187], v[192:195], v[48:51]
	v_mfma_f32_16x16x32_bf16 v[36:39], v[176:179], v[200:203], v[36:39]
	v_mfma_f32_16x16x32_bf16 v[32:35], v[184:187], v[200:203], v[32:35]
	v_mfma_f32_16x16x32_bf16 v[20:23], v[176:179], v[208:211], v[20:23]
	v_mfma_f32_16x16x32_bf16 v[16:19], v[184:187], v[208:211], v[16:19]
	v_mfma_f32_16x16x32_bf16 v[4:7], v[176:179], v[216:219], v[4:7]
	v_mfma_f32_16x16x32_bf16 v[0:3], v[184:187], v[216:219], v[0:3]
	v_mfma_f32_16x16x32_bf16 v[52:55], v[180:183], v[196:199], v[52:55]
	v_mfma_f32_16x16x32_bf16 v[48:51], v[188:191], v[196:199], v[48:51]
	v_mfma_f32_16x16x32_bf16 v[36:39], v[180:183], v[204:207], v[36:39]
	v_mfma_f32_16x16x32_bf16 v[32:35], v[188:191], v[204:207], v[32:35]
	v_mfma_f32_16x16x32_bf16 v[20:23], v[180:183], v[212:215], v[20:23]
	v_mfma_f32_16x16x32_bf16 v[16:19], v[188:191], v[212:215], v[16:19]
	v_mfma_f32_16x16x32_bf16 v[4:7], v[180:183], v[220:223], v[4:7]
	v_mfma_f32_16x16x32_bf16 v[0:3], v[188:191], v[220:223], v[0:3]
	s_barrier
	s_add_i32 s72, s72, 2
	s_add_u32 s16, s16, 0x100
	s_addc_u32 s17, s17, 0
	s_add_u32 s70, s70, 0x100
	s_addc_u32 s71, s71, 0
	s_cmp_gt_u32 s72, 13
	s_cbranch_scc0 .LBB0_909
	s_and_b64 vcc, exec, s[54:55]
	s_cbranch_vccz .LBB0_912
	s_barrier

;     DI size_t offA(const Unit& u) const { return (size_t)u.pm * tA + (size_t)u.pn * aPn; }
;     DI size_t offB(const Unit& u) const { return (size_t)u.pn * tB; }
; #define PG8_STAGE(bufoff, gbase, voff) do { _Pragma("unroll") for (int _i = 0; _i < 2; ++_i) \
;         __builtin_amdgcn_global_load_lds((const unsigned*)((const char*)(gbase) + (voff)[_i]), (LAS unsigned*)(lds + (bufoff) + ldsw + _i * 8192), 16, 0, 0); } while (0)
; #define PG8_LDA(dst, b, h) do { _Pragma("unroll") for (int m = 0; m < 4; ++m) _Pragma("unroll") for (int k = 0; k < 2; ++k) dst[m][k] = *(const LAS bf16x8*)(lds + PG8_SA(b, h) + aoff + m * 2048 + k * 1024); } while (0)
; #define PG8_LDB(dst, b, h) do { _Pragma("unroll") for (int n = 0; n < 2; ++n) _Pragma("unroll") for (int k = 0; k < 2; ++k) dst[n][k] = *(const LAS bf16x8*)(lds + PG8_SB(b, h) + boff + n * 2048 + k * 1024); } while (0)
; #define PG8_MMA(ai, bj, At, Bt) do { __builtin_amdgcn_s_setprio(1); _Pragma("unroll") for (int m = 0; m < 4; ++m) _Pragma("unroll") for (int n = 0; n < 2; ++n) _Pragma("unroll") for (int k = 0; k < 2; ++k) \
;         acc[ai][bj][m][n] = __builtin_amdgcn_mfma_f32_16x16x32_bf16(Bt[n][k], At[m][k], acc[ai][bj][m][n], 0, 0, 0); __builtin_amdgcn_s_setprio(0); } while (0)
; #define PG8_BAR __builtin_amdgcn_s_barrier()
; template <class Epi, class Sched, bool ALIGN_EPI = true, bool SP2 = true>
; DI void gemm_phase(LAS unsigned char* lds, const Gemm g, const Sched& S, const Epi& E) {
;     ...
;         const char* nA = has_next ? (const char*)g.A + S.offA(nxt) : cA; const char* nB = has_next ? (const char*)g.Bt + S.offB(nxt) : cB;
; #pragma unroll 1
;         for (int t = 0; t < nt; t += 2) {
;             const bool last = (t == nt - 2);
;             const char* a1 = cA + (size_t)(t + 1) * kstep;
;             const char* a2 = last ? nA : cA + (size_t)(t + 2) * kstep; const char* b2 = last ? nB : cB + (size_t)(t + 2) * kstep;
;             const char* a3 = a2 + kstep; const char* b3 = b2 + kstep;
;             PG8_LDB(B0, 0, 0); PG8_LDB(B1, 0, 1); PG8_SCHED; PG8_LDA(At, 0, 0); PG8_STAGE(PG8_SA(1, 1), a1 + hstepA, voffA);
;             PG8_WAIT_V(8); PG8_WAIT_L(0); PG8_BAR; PG8_MMA(0, 0, At, B0); PG8_MMA(0, 1, At, B1); PG8_BAR; PG8_SCHED;
;             PG8_LDA(At, 0, 1); PG8_STAGE(PG8_SB(0, 0), b2, voffB); PG8_STAGE(PG8_SB(0, 1), b2 + hstepB, voffB); PG8_STAGE(PG8_SA(0, 0), a2, voffA);
.LBB0_1677:
	s_add_u32 s64, s44, s58
	s_addc_u32 s65, s45, s59
	s_add_u32 s62, s64, 0x100
	s_addc_u32 s63, s65, 0
	s_and_b64 s[60:61], s[56:57], exec
	s_cselect_b32 s61, s49, s63
	s_cselect_b32 s60, s95, s62
	s_add_u32 s58, s38, s58
	s_addc_u32 s59, s39, s59
	s_add_u32 s58, s58, 0x100
	ds_read_b128 v[146:149], v140
	ds_read_b128 v[150:153], v140 offset:1024
	ds_read_b128 v[154:157], v140 offset:2048
	ds_read_b128 v[158:161], v140 offset:3072
	ds_read_b128 v[162:165], v141
	ds_read_b128 v[166:169], v141 offset:1024
	ds_read_b128 v[172:175], v141 offset:2048
	ds_read_b128 v[176:179], v141 offset:3072
	s_addc_u32 s59, s59, 0
	s_and_b64 s[56:57], s[56:57], exec
	s_cselect_b32 s63, s15, s59
	s_cselect_b32 s62, s14, s58
	s_add_u32 s66, s64, 0x20080
	s_addc_u32 s67, s65, 0
	s_add_u32 s64, s62, 0x400000
	s_addc_u32 s65, s63, 0
	s_add_u32 s58, s60, 0x20000
	s_addc_u32 s59, s61, 0
	s_add_u32 s56, s62, 0x400080
	s_addc_u32 s57, s63, 0
	s_add_i32 s97, s89, s68
	s_add_i32 s96, s97, 0x2000
	s_mov_b32 m0, s0
	v_lshl_add_u64 v[138:139], s[66:67], 0, v[134:135]
	ds_read_b128 v[180:183], v142
	ds_read_b128 v[184:187], v142 offset:1024
	ds_read_b128 v[188:191], v142 offset:2048
	ds_read_b128 v[192:195], v142 offset:3072
	ds_read_b128 v[196:199], v142 offset:4096
	ds_read_b128 v[200:203], v142 offset:5120
	ds_read_b128 v[204:207], v142 offset:6144
	ds_read_b128 v[208:211], v142 offset:7168
	global_load_lds_dwordx4 v[138:139], off
	v_lshl_add_u64 v[138:139], s[66:67], 0, v[130:131]
	s_mov_b32 m0, s84
	s_nop 0
	global_load_lds_dwordx4 v[138:139], off
	s_waitcnt vmcnt(8)
	s_waitcnt lgkmcnt(0)
	s_barrier
	s_waitcnt lgkmcnt(0)
	v_mfma_f32_16x16x32_bf16 v[124:127], v[146:149], v[180:183], v[124:127]
	v_mfma_f32_16x16x32_bf16 v[120:123], v[154:157], v[180:183], v[120:123]
	v_mfma_f32_16x16x32_bf16 v[116:119], v[146:149], v[188:191], v[116:119]
	v_mfma_f32_16x16x32_bf16 v[108:111], v[154:157], v[188:191], v[108:111]
	v_mfma_f32_16x16x32_bf16 v[100:103], v[146:149], v[196:199], v[100:103]
	v_mfma_f32_16x16x32_bf16 v[92:95], v[154:157], v[196:199], v[92:95]
	v_mfma_f32_16x16x32_bf16 v[84:87], v[146:149], v[204:207], v[84:87]
	v_mfma_f32_16x16x32_bf16 v[76:79], v[154:157], v[204:207], v[76:79]
	v_mfma_f32_16x16x32_bf16 v[124:127], v[150:153], v[184:187], v[124:127]
	v_mfma_f32_16x16x32_bf16 v[120:123], v[158:161], v[184:187], v[120:123]
	v_mfma_f32_16x16x32_bf16 v[116:119], v[150:153], v[192:195], v[116:119]
	v_mfma_f32_16x16x32_bf16 v[108:111], v[158:161], v[192:195], v[108:111]
	v_mfma_f32_16x16x32_bf16 v[100:103], v[150:153], v[200:203], v[100:103]
	v_mfma_f32_16x16x32_bf16 v[92:95], v[158:161], v[200:203], v[92:95]
	v_mfma_f32_16x16x32_bf16 v[84:87], v[150:153], v[208:211], v[84:87]
	v_mfma_f32_16x16x32_bf16 v[76:79], v[158:161], v[208:211], v[76:79]
	v_mfma_f32_16x16x32_bf16 v[112:115], v[162:165], v[180:183], v[112:115]
	v_mfma_f32_16x16x32_bf16 v[104:107], v[172:175], v[180:183], v[104:107]
	v_mfma_f32_16x16x32_bf16 v[96:99], v[162:165], v[188:191], v[96:99]
	v_mfma_f32_16x16x32_bf16 v[88:91], v[172:175], v[188:191], v[88:91]
	v_mfma_f32_16x16x32_bf16 v[80:83], v[162:165], v[196:199], v[80:83]
	v_mfma_f32_16x16x32_bf16 v[72:75], v[172:175], v[196:199], v[72:75]
	v_mfma_f32_16x16x32_bf16 v[68:71], v[162:165], v[204:207], v[68:71]
	v_mfma_f32_16x16x32_bf16 v[64:67], v[172:175], v[204:207], v[64:67]
	v_mfma_f32_16x16x32_bf16 v[112:115], v[166:169], v[184:187], v[112:115]
	v_mfma_f32_16x16x32_bf16 v[104:107], v[176:179], v[184:187], v[104:107]
	v_mfma_f32_16x16x32_bf16 v[96:99], v[166:169], v[192:195], v[96:99]
	v_mfma_f32_16x16x32_bf16 v[88:91], v[176:179], v[192:195], v[88:91]
	v_mfma_f32_16x16x32_bf16 v[80:83], v[166:169], v[200:203], v[80:83]
	v_mfma_f32_16x16x32_bf16 v[72:75], v[176:179], v[200:203], v[72:75]
	v_mfma_f32_16x16x32_bf16 v[68:71], v[166:169], v[208:211], v[68:71]
	v_mfma_f32_16x16x32_bf16 v[64:67], v[176:179], v[208:211], v[64:67]
	s_barrier
	s_mov_b32 m0, s85
	v_lshl_add_u64 v[138:139], s[62:63], 0, v[132:133]
	ds_read_b128 v[180:183], v142 offset:16384
	ds_read_b128 v[184:187], v142 offset:17408
	ds_read_b128 v[188:191], v142 offset:18432
	ds_read_b128 v[192:195], v142 offset:19456
	ds_read_b128 v[196:199], v142 offset:20480
	ds_read_b128 v[200:203], v142 offset:21504
	ds_read_b128 v[204:207], v142 offset:22528
	ds_read_b128 v[208:211], v142 offset:23552
	global_load_lds_dwordx4 v[138:139], off
	v_lshl_add_u64 v[212:213], s[62:63], 0, v[128:129]
	s_mov_b32 m0, s86
	v_lshl_add_u64 v[214:215], s[64:65], 0, v[132:133]
	global_load_lds_dwordx4 v[212:213], off
	s_mov_b32 m0, s87
	v_lshl_add_u64 v[216:217], s[60:61], 0, v[130:131]
	global_load_lds_dwordx4 v[214:215], off
	v_lshl_add_u64 v[214:215], s[64:65], 0, v[128:129]
	s_mov_b32 m0, s88
	s_nop 0
	global_load_lds_dwordx4 v[214:215], off
	v_lshl_add_u64 v[214:215], s[60:61], 0, v[134:135]
	s_mov_b32 m0, s3
	s_nop 0
	global_load_lds_dwordx4 v[214:215], off
	s_mov_b32 m0, s69
	s_nop 0
	global_load_lds_dwordx4 v[216:217], off
	s_waitcnt vmcnt(8)
	s_waitcnt lgkmcnt(0)
	s_barrier
; #define PG8_STAGE(bufoff, gbase, voff) do { _Pragma("unroll") for (int _i = 0; _i < 2; ++_i) \
;         __builtin_amdgcn_global_load_lds((const unsigned*)((const char*)(gbase) + (voff)[_i]), (LAS unsigned*)(lds + (bufoff) + ldsw + _i * 8192), 16, 0, 0); } while (0)
; #define PG8_LDA(dst, b, h) do { _Pragma("unroll") for (int m = 0; m < 4; ++m) _Pragma("unroll") for (int k = 0; k < 2; ++k) dst[m][k] = *(const LAS bf16x8*)(lds + PG8_SA(b, h) + aoff + m * 2048 + k * 1024); } while (0)
; #define PG8_LDB(dst, b, h) do { _Pragma("unroll") for (int n = 0; n < 2; ++n) _Pragma("unroll") for (int k = 0; k < 2; ++k) dst[n][k] = *(const LAS bf16x8*)(lds + PG8_SB(b, h) + boff + n * 2048 + k * 1024); } while (0)
; #define PG8_MMA(ai, bj, At, Bt) do { __builtin_amdgcn_s_setprio(1); _Pragma("unroll") for (int m = 0; m < 4; ++m) _Pragma("unroll") for (int n = 0; n < 2; ++n) _Pragma("unroll") for (int k = 0; k < 2; ++k) \
;         acc[ai][bj][m][n] = __builtin_amdgcn_mfma_f32_16x16x32_bf16(Bt[n][k], At[m][k], acc[ai][bj][m][n], 0, 0, 0); __builtin_amdgcn_s_setprio(0); } while (0)
; #define PG8_WAIT_V(n) asm volatile("s_waitcnt vmcnt(" #n ")" ::: "memory")
; #define PG8_WAIT_L(n) asm volatile("s_waitcnt lgkmcnt(" #n ")" ::: "memory")
; #define PG8_BAR __builtin_amdgcn_s_barrier()
; #define PG8_SCHED __builtin_amdgcn_sched_barrier(0)
; template <class Epi, class Sched, bool ALIGN_EPI = true, bool SP2 = true>
; DI void gemm_phase(LAS unsigned char* lds, const Gemm g, const Sched& S, const Epi& E) {
;     ...
;             PG8_WAIT_V(8); PG8_WAIT_L(0); PG8_BAR; PG8_MMA(1, 0, At, B0); PG8_MMA(1, 1, At, B1); PG8_BAR; PG8_SCHED;
;             PG8_LDB(B0, 1, 0); PG8_LDB(B1, 1, 1); PG8_SCHED; PG8_LDA(At, 1, 0); PG8_STAGE(PG8_SA(0, 1), a2 + hstepA, voffA);
;             PG8_WAIT_V(8); PG8_WAIT_L(0); PG8_BAR; PG8_MMA(0, 0, At, B0); PG8_MMA(0, 1, At, B1); PG8_BAR; PG8_SCHED;
	s_waitcnt lgkmcnt(0)
	v_mfma_f32_16x16x32_bf16 v[60:63], v[146:149], v[180:183], v[60:63]
	v_mfma_f32_16x16x32_bf16 v[56:59], v[154:157], v[180:183], v[56:59]
	v_mfma_f32_16x16x32_bf16 v[52:55], v[146:149], v[188:191], v[52:55]
	v_mfma_f32_16x16x32_bf16 v[44:47], v[154:157], v[188:191], v[44:47]
	v_mfma_f32_16x16x32_bf16 v[36:39], v[146:149], v[196:199], v[36:39]
	v_mfma_f32_16x16x32_bf16 v[28:31], v[154:157], v[196:199], v[28:31]
	v_mfma_f32_16x16x32_bf16 v[20:23], v[146:149], v[204:207], v[20:23]
	v_mfma_f32_16x16x32_bf16 v[12:15], v[154:157], v[204:207], v[12:15]
	v_mfma_f32_16x16x32_bf16 v[60:63], v[150:153], v[184:187], v[60:63]
	v_mfma_f32_16x16x32_bf16 v[56:59], v[158:161], v[184:187], v[56:59]
	v_mfma_f32_16x16x32_bf16 v[52:55], v[150:153], v[192:195], v[52:55]
	v_mfma_f32_16x16x32_bf16 v[44:47], v[158:161], v[192:195], v[44:47]
	v_mfma_f32_16x16x32_bf16 v[36:39], v[150:153], v[200:203], v[36:39]
	v_mfma_f32_16x16x32_bf16 v[28:31], v[158:161], v[200:203], v[28:31]
	v_mfma_f32_16x16x32_bf16 v[20:23], v[150:153], v[208:211], v[20:23]
	v_mfma_f32_16x16x32_bf16 v[12:15], v[158:161], v[208:211], v[12:15]
	v_mfma_f32_16x16x32_bf16 v[48:51], v[162:165], v[180:183], v[48:51]
	v_mfma_f32_16x16x32_bf16 v[40:43], v[172:175], v[180:183], v[40:43]
	v_mfma_f32_16x16x32_bf16 v[32:35], v[162:165], v[188:191], v[32:35]
	v_mfma_f32_16x16x32_bf16 v[24:27], v[172:175], v[188:191], v[24:27]
	v_mfma_f32_16x16x32_bf16 v[16:19], v[162:165], v[196:199], v[16:19]
	v_mfma_f32_16x16x32_bf16 v[8:11], v[172:175], v[196:199], v[8:11]
	v_mfma_f32_16x16x32_bf16 v[4:7], v[162:165], v[204:207], v[4:7]
	v_mfma_f32_16x16x32_bf16 v[0:3], v[172:175], v[204:207], v[0:3]
	v_mfma_f32_16x16x32_bf16 v[48:51], v[166:169], v[184:187], v[48:51]
	v_mfma_f32_16x16x32_bf16 v[40:43], v[176:179], v[184:187], v[40:43]
	v_mfma_f32_16x16x32_bf16 v[32:35], v[166:169], v[192:195], v[32:35]
	v_mfma_f32_16x16x32_bf16 v[24:27], v[176:179], v[192:195], v[24:27]
	v_mfma_f32_16x16x32_bf16 v[16:19], v[166:169], v[200:203], v[16:19]
	v_mfma_f32_16x16x32_bf16 v[8:11], v[176:179], v[200:203], v[8:11]
	v_mfma_f32_16x16x32_bf16 v[4:7], v[166:169], v[208:211], v[4:7]
	v_mfma_f32_16x16x32_bf16 v[0:3], v[176:179], v[208:211], v[0:3]
	s_barrier
	ds_read_b128 v[146:149], v143
	ds_read_b128 v[150:153], v143 offset:1024
	ds_read_b128 v[154:157], v143 offset:2048
	ds_read_b128 v[158:161], v143 offset:3072
	ds_read_b128 v[162:165], v144
	ds_read_b128 v[166:169], v144 offset:1024
	ds_read_b128 v[172:175], v144 offset:2048
	ds_read_b128 v[176:179], v144 offset:3072
	s_mov_b32 m0, s70
	v_lshl_add_u64 v[218:219], s[58:59], 0, v[134:135]
	ds_read_b128 v[180:183], v142 offset:32768
	ds_read_b128 v[184:187], v142 offset:33792
	ds_read_b128 v[188:191], v142 offset:34816
	ds_read_b128 v[192:195], v142 offset:35840
	ds_read_b128 v[196:199], v142 offset:36864
	ds_read_b128 v[200:203], v142 offset:37888
	ds_read_b128 v[204:207], v142 offset:38912
	ds_read_b128 v[208:211], v142 offset:39936
	global_load_lds_dwordx4 v[218:219], off
	v_lshl_add_u64 v[218:219], s[58:59], 0, v[130:131]
	s_mov_b32 m0, s71
	s_nop 0
	global_load_lds_dwordx4 v[218:219], off
	s_waitcnt vmcnt(8)
	s_waitcnt lgkmcnt(0)
	s_barrier
	s_waitcnt lgkmcnt(0)
	v_mfma_f32_16x16x32_bf16 v[124:127], v[146:149], v[180:183], v[124:127]
	v_mfma_f32_16x16x32_bf16 v[120:123], v[154:157], v[180:183], v[120:123]
	v_mfma_f32_16x16x32_bf16 v[116:119], v[146:149], v[188:191], v[116:119]
	v_mfma_f32_16x16x32_bf16 v[108:111], v[154:157], v[188:191], v[108:111]
	v_mfma_f32_16x16x32_bf16 v[100:103], v[146:149], v[196:199], v[100:103]
	v_mfma_f32_16x16x32_bf16 v[92:95], v[154:157], v[196:199], v[92:95]
	v_mfma_f32_16x16x32_bf16 v[84:87], v[146:149], v[204:207], v[84:87]
	v_mfma_f32_16x16x32_bf16 v[76:79], v[154:157], v[204:207], v[76:79]
	v_mfma_f32_16x16x32_bf16 v[124:127], v[150:153], v[184:187], v[124:127]
	v_mfma_f32_16x16x32_bf16 v[120:123], v[158:161], v[184:187], v[120:123]
	v_mfma_f32_16x16x32_bf16 v[116:119], v[150:153], v[192:195], v[116:119]
	v_mfma_f32_16x16x32_bf16 v[108:111], v[158:161], v[192:195], v[108:111]
	v_mfma_f32_16x16x32_bf16 v[100:103], v[150:153], v[200:203], v[100:103]
	v_mfma_f32_16x16x32_bf16 v[92:95], v[158:161], v[200:203], v[92:95]
	v_mfma_f32_16x16x32_bf16 v[84:87], v[150:153], v[208:211], v[84:87]
	v_mfma_f32_16x16x32_bf16 v[76:79], v[158:161], v[208:211], v[76:79]
	v_mfma_f32_16x16x32_bf16 v[112:115], v[162:165], v[180:183], v[112:115]
	v_mfma_f32_16x16x32_bf16 v[104:107], v[172:175], v[180:183], v[104:107]
	v_mfma_f32_16x16x32_bf16 v[96:99], v[162:165], v[188:191], v[96:99]
	v_mfma_f32_16x16x32_bf16 v[88:91], v[172:175], v[188:191], v[88:91]
	v_mfma_f32_16x16x32_bf16 v[80:83], v[162:165], v[196:199], v[80:83]
	v_mfma_f32_16x16x32_bf16 v[72:75], v[172:175], v[196:199], v[72:75]
	v_mfma_f32_16x16x32_bf16 v[68:71], v[162:165], v[204:207], v[68:71]
	v_mfma_f32_16x16x32_bf16 v[64:67], v[172:175], v[204:207], v[64:67]
	v_mfma_f32_16x16x32_bf16 v[112:115], v[166:169], v[184:187], v[112:115]
	v_mfma_f32_16x16x32_bf16 v[104:107], v[176:179], v[184:187], v[104:107]
	v_mfma_f32_16x16x32_bf16 v[96:99], v[166:169], v[192:195], v[96:99]
	v_mfma_f32_16x16x32_bf16 v[88:91], v[176:179], v[192:195], v[88:91]
	v_mfma_f32_16x16x32_bf16 v[80:83], v[166:169], v[200:203], v[80:83]
	v_mfma_f32_16x16x32_bf16 v[72:75], v[176:179], v[200:203], v[72:75]
	v_mfma_f32_16x16x32_bf16 v[68:71], v[166:169], v[208:211], v[68:71]
	v_mfma_f32_16x16x32_bf16 v[64:67], v[176:179], v[208:211], v[64:67]
	s_barrier
;     DI size_t offA(const Unit& u) const { return (size_t)u.pm * tA + (size_t)u.pn * aPn; }
;     DI size_t offB(const Unit& u) const { return (size_t)u.pn * tB; }
; #define PG8_STAGE(bufoff, gbase, voff) do { _Pragma("unroll") for (int _i = 0; _i < 2; ++_i) \
;         __builtin_amdgcn_global_load_lds((const unsigned*)((const char*)(gbase) + (voff)[_i]), (LAS unsigned*)(lds + (bufoff) + ldsw + _i * 8192), 16, 0, 0); } while (0)
; #define PG8_LDA(dst, b, h) do { _Pragma("unroll") for (int m = 0; m < 4; ++m) _Pragma("unroll") for (int k = 0; k < 2; ++k) dst[m][k] = *(const LAS bf16x8*)(lds + PG8_SA(b, h) + aoff + m * 2048 + k * 1024); } while (0)
; #define PG8_MMA(ai, bj, At, Bt) do { __builtin_amdgcn_s_setprio(1); _Pragma("unroll") for (int m = 0; m < 4; ++m) _Pragma("unroll") for (int n = 0; n < 2; ++n) _Pragma("unroll") for (int k = 0; k < 2; ++k) \
;         acc[ai][bj][m][n] = __builtin_amdgcn_mfma_f32_16x16x32_bf16(Bt[n][k], At[m][k], acc[ai][bj][m][n], 0, 0, 0); __builtin_amdgcn_s_setprio(0); } while (0)
; #define PG8_WAIT_V(n) asm volatile("s_waitcnt vmcnt(" #n ")" ::: "memory")
; #define PG8_WAIT_L(n) asm volatile("s_waitcnt lgkmcnt(" #n ")" ::: "memory")
; #define PG8_BAR __builtin_amdgcn_s_barrier()
; #define PG8_SCHED __builtin_amdgcn_sched_barrier(0)
; template <class Epi, class Sched, bool ALIGN_EPI = true, bool SP2 = true>
; DI void gemm_phase(LAS unsigned char* lds, const Gemm g, const Sched& S, const Epi& E) {
;     ...
;         const char* nA = has_next ? (const char*)g.A + S.offA(nxt) : cA; const char* nB = has_next ? (const char*)g.Bt + S.offB(nxt) : cB;
; #pragma unroll 1
;         for (int t = 0; t < nt; t += 2) {
;     ...
;             PG8_LDA(At, 1, 1); PG8_STAGE(PG8_SB(1, 0), b3, voffB); PG8_STAGE(PG8_SB(1, 1), b3 + hstepB, voffB); PG8_STAGE(PG8_SA(1, 0), a3, voffA);
;             PG8_WAIT_V(8); PG8_WAIT_L(0); PG8_BAR; PG8_MMA(1, 0, At, B0); PG8_MMA(1, 1, At, B1); PG8_BAR; PG8_SCHED;
	s_mov_b32 m0, s92
	v_lshl_add_u64 v[138:139], v[138:139], 0, s[8:9]
	ds_read_b128 v[180:183], v142 offset:49152
	ds_read_b128 v[184:187], v142 offset:50176
	ds_read_b128 v[188:191], v142 offset:51200
	ds_read_b128 v[192:195], v142 offset:52224
	ds_read_b128 v[196:199], v142 offset:53248
	ds_read_b128 v[200:203], v142 offset:54272
	ds_read_b128 v[204:207], v142 offset:55296
	ds_read_b128 v[208:211], v142 offset:56320
	global_load_lds_dwordx4 v[138:139], off
	v_lshl_add_u64 v[138:139], v[212:213], 0, s[8:9]
	s_mov_b32 m0, s93
	s_nop 0
	global_load_lds_dwordx4 v[138:139], off
	v_lshl_add_u64 v[138:139], s[56:57], 0, v[132:133]
	s_mov_b32 m0, s97
	s_nop 0
	global_load_lds_dwordx4 v[138:139], off
	v_lshl_add_u64 v[138:139], s[56:57], 0, v[128:129]
	s_mov_b32 m0, s96
	s_nop 0
	global_load_lds_dwordx4 v[138:139], off
	v_lshl_add_u64 v[138:139], v[214:215], 0, s[8:9]
	s_mov_b32 m0, s79
	s_nop 0
	global_load_lds_dwordx4 v[138:139], off
	v_lshl_add_u64 v[138:139], v[216:217], 0, s[8:9]
	s_mov_b32 m0, s81
	s_nop 0
	global_load_lds_dwordx4 v[138:139], off
	s_waitcnt vmcnt(8)
	s_waitcnt lgkmcnt(0)
	s_barrier
	s_waitcnt lgkmcnt(0)
	v_mfma_f32_16x16x32_bf16 v[60:63], v[146:149], v[180:183], v[60:63]
	v_mfma_f32_16x16x32_bf16 v[56:59], v[154:157], v[180:183], v[56:59]
	v_mfma_f32_16x16x32_bf16 v[52:55], v[146:149], v[188:191], v[52:55]
	v_mfma_f32_16x16x32_bf16 v[44:47], v[154:157], v[188:191], v[44:47]
	v_mfma_f32_16x16x32_bf16 v[36:39], v[146:149], v[196:199], v[36:39]
	v_mfma_f32_16x16x32_bf16 v[28:31], v[154:157], v[196:199], v[28:31]
	v_mfma_f32_16x16x32_bf16 v[20:23], v[146:149], v[204:207], v[20:23]
	v_mfma_f32_16x16x32_bf16 v[12:15], v[154:157], v[204:207], v[12:15]
	v_mfma_f32_16x16x32_bf16 v[60:63], v[150:153], v[184:187], v[60:63]
	v_mfma_f32_16x16x32_bf16 v[56:59], v[158:161], v[184:187], v[56:59]
	v_mfma_f32_16x16x32_bf16 v[52:55], v[150:153], v[192:195], v[52:55]
	v_mfma_f32_16x16x32_bf16 v[44:47], v[158:161], v[192:195], v[44:47]
	v_mfma_f32_16x16x32_bf16 v[36:39], v[150:153], v[200:203], v[36:39]
	v_mfma_f32_16x16x32_bf16 v[28:31], v[158:161], v[200:203], v[28:31]
	v_mfma_f32_16x16x32_bf16 v[20:23], v[150:153], v[208:211], v[20:23]
	v_mfma_f32_16x16x32_bf16 v[12:15], v[158:161], v[208:211], v[12:15]
	v_mfma_f32_16x16x32_bf16 v[48:51], v[162:165], v[180:183], v[48:51]
	v_mfma_f32_16x16x32_bf16 v[40:43], v[172:175], v[180:183], v[40:43]
	v_mfma_f32_16x16x32_bf16 v[32:35], v[162:165], v[188:191], v[32:35]
	v_mfma_f32_16x16x32_bf16 v[24:27], v[172:175], v[188:191], v[24:27]
	v_mfma_f32_16x16x32_bf16 v[16:19], v[162:165], v[196:199], v[16:19]
	v_mfma_f32_16x16x32_bf16 v[8:11], v[172:175], v[196:199], v[8:11]
	v_mfma_f32_16x16x32_bf16 v[4:7], v[162:165], v[204:207], v[4:7]
	v_mfma_f32_16x16x32_bf16 v[0:3], v[172:175], v[204:207], v[0:3]
	v_mfma_f32_16x16x32_bf16 v[48:51], v[166:169], v[184:187], v[48:51]
	v_mfma_f32_16x16x32_bf16 v[40:43], v[176:179], v[184:187], v[40:43]
	v_mfma_f32_16x16x32_bf16 v[32:35], v[166:169], v[192:195], v[32:35]
	v_mfma_f32_16x16x32_bf16 v[24:27], v[176:179], v[192:195], v[24:27]
	v_mfma_f32_16x16x32_bf16 v[16:19], v[166:169], v[200:203], v[16:19]
	v_mfma_f32_16x16x32_bf16 v[8:11], v[176:179], v[200:203], v[8:11]
	v_mfma_f32_16x16x32_bf16 v[4:7], v[166:169], v[208:211], v[4:7]
	v_mfma_f32_16x16x32_bf16 v[0:3], v[176:179], v[208:211], v[0:3]
	s_barrier
	s_andn2_b64 vcc, exec, s[54:55]
	s_mov_b64 s[56:57], -1
	s_mov_b64 s[54:55], 0
	s_mov_b64 s[58:59], 0x100
	s_cbranch_vccz .LBB0_1677
	s_and_b64 vcc, exec, s[12:13]
	s_cbranch_vccz .LBB0_1680
	s_barrier

;     DI size_t offA(const Unit& u) const { return (size_t)u.pm * tA + (size_t)u.pn * aPn; }
;     DI size_t offB(const Unit& u) const { return (size_t)u.pn * tB; }
; #define PG8_STAGE(bufoff, gbase, voff) do { _Pragma("unroll") for (int _i = 0; _i < 2; ++_i) \
;         __builtin_amdgcn_global_load_lds((const unsigned*)((const char*)(gbase) + (voff)[_i]), (LAS unsigned*)(lds + (bufoff) + ldsw + _i * 8192), 16, 0, 0); } while (0)
; #define PG8_LDA(dst, b, h) do { _Pragma("unroll") for (int m = 0; m < 4; ++m) _Pragma("unroll") for (int k = 0; k < 2; ++k) dst[m][k] = *(const LAS bf16x8*)(lds + PG8_SA(b, h) + aoff + m * 2048 + k * 1024); } while (0)
; #define PG8_LDB(dst, b, h) do { _Pragma("unroll") for (int n = 0; n < 2; ++n) _Pragma("unroll") for (int k = 0; k < 2; ++k) dst[n][k] = *(const LAS bf16x8*)(lds + PG8_SB(b, h) + boff + n * 2048 + k * 1024); } while (0)
; #define PG8_MMA(ai, bj, At, Bt) do { __builtin_amdgcn_s_setprio(1); _Pragma("unroll") for (int m = 0; m < 4; ++m) _Pragma("unroll") for (int n = 0; n < 2; ++n) _Pragma("unroll") for (int k = 0; k < 2; ++k) \
;         acc[ai][bj][m][n] = __builtin_amdgcn_mfma_f32_16x16x32_bf16(Bt[n][k], At[m][k], acc[ai][bj][m][n], 0, 0, 0); __builtin_amdgcn_s_setprio(0); } while (0)
; #define PG8_BAR __builtin_amdgcn_s_barrier()
; template <class Epi, class Sched, bool ALIGN_EPI = true, bool SP2 = true>
; DI void gemm_phase(LAS unsigned char* lds, const Gemm g, const Sched& S, const Epi& E) {
;     ...
;         const char* nA = has_next ? (const char*)g.A + S.offA(nxt) : cA; const char* nB = has_next ? (const char*)g.Bt + S.offB(nxt) : cB;
; #pragma unroll 1
;         for (int t = 0; t < nt; t += 2) {
;             const bool last = (t == nt - 2);
;             const char* a1 = cA + (size_t)(t + 1) * kstep;
;             const char* a2 = last ? nA : cA + (size_t)(t + 2) * kstep; const char* b2 = last ? nB : cB + (size_t)(t + 2) * kstep;
;             const char* a3 = a2 + kstep; const char* b3 = b2 + kstep;
;             PG8_LDB(B0, 0, 0); PG8_LDB(B1, 0, 1); PG8_SCHED; PG8_LDA(At, 0, 0); PG8_STAGE(PG8_SA(1, 1), a1 + hstepA, voffA);
;             PG8_WAIT_V(8); PG8_WAIT_L(0); PG8_BAR; PG8_MMA(0, 0, At, B0); PG8_MMA(0, 1, At, B1); PG8_BAR; PG8_SCHED;
;             PG8_LDA(At, 0, 1); PG8_STAGE(PG8_SB(0, 0), b2, voffB); PG8_STAGE(PG8_SB(0, 1), b2 + hstepB, voffB); PG8_STAGE(PG8_SA(0, 0), a2, voffA);
.LBB0_1693:
	s_add_u32 s60, s0, s54
	s_addc_u32 s61, s1, s55
	s_add_u32 s58, s60, 0x100
	s_addc_u32 s59, s61, 0
	s_and_b64 s[56:57], s[48:49], exec
	s_cselect_b32 s57, s39, s59
	s_cselect_b32 s56, s78, s58
	s_add_u32 s54, s42, s54
	s_addc_u32 s55, s43, s55
	s_add_u32 s54, s54, 0x100
	s_addc_u32 s55, s55, 0
	s_and_b64 s[48:49], s[48:49], exec
	ds_read_b128 v[174:177], v137
	ds_read_b128 v[178:181], v137 offset:1024
	ds_read_b128 v[182:185], v137 offset:2048
	ds_read_b128 v[186:189], v137 offset:3072
	ds_read_b128 v[190:193], v141
	ds_read_b128 v[194:197], v141 offset:1024
	ds_read_b128 v[198:201], v141 offset:2048
	ds_read_b128 v[202:205], v141 offset:3072
	s_cselect_b32 s59, s15, s55
	s_cselect_b32 s58, s14, s54
	s_add_u32 s62, s60, 0x20080
	s_addc_u32 s63, s61, 0
	s_add_i32 s86, s76, 0x2000
	s_add_u32 s60, s58, 0x180000
	s_addc_u32 s61, s59, 0
	s_add_i32 s88, s71, s64
	s_add_i32 s87, s88, 0x2000
	s_add_i32 s85, 0, 0x18000
	s_add_i32 s84, 0, 0x1c000
	s_add_u32 s54, s56, 0x20000
	s_addc_u32 s55, s57, 0
	s_add_i32 s81, s85, s64
	s_add_i32 s79, s81, 0x2000
	s_add_u32 s48, s58, 0x180080
	s_addc_u32 s49, s59, 0
	s_add_i32 s92, s84, s64
	s_add_i32 s89, s92, 0x2000
	s_mov_b32 m0, s74
	v_lshl_add_u64 v[168:169], s[62:63], 0, v[134:135]
	ds_read_b128 v[206:209], v145
	ds_read_b128 v[210:213], v145 offset:1024
	ds_read_b128 v[214:217], v145 offset:2048
	ds_read_b128 v[218:221], v145 offset:3072
	ds_read_b128 v[222:225], v145 offset:4096
	ds_read_b128 v[228:231], v145 offset:5120
	ds_read_b128 v[232:235], v145 offset:6144
	ds_read_b128 v[236:239], v145 offset:7168
	global_load_lds_dwordx4 v[168:169], off
	v_lshl_add_u64 v[168:169], s[62:63], 0, v[130:131]
	s_mov_b32 m0, s75
	s_nop 0
	global_load_lds_dwordx4 v[168:169], off
	s_waitcnt vmcnt(8)
	s_waitcnt lgkmcnt(0)
	s_barrier
	s_waitcnt lgkmcnt(0)
	v_mfma_f32_16x16x32_bf16 v[124:127], v[174:177], v[206:209], v[124:127]
	v_mfma_f32_16x16x32_bf16 v[120:123], v[182:185], v[206:209], v[120:123]
	v_mfma_f32_16x16x32_bf16 v[108:111], v[174:177], v[214:217], v[108:111]
	v_mfma_f32_16x16x32_bf16 v[104:107], v[182:185], v[214:217], v[104:107]
	v_mfma_f32_16x16x32_bf16 v[92:95], v[174:177], v[222:225], v[92:95]
	v_mfma_f32_16x16x32_bf16 v[88:91], v[182:185], v[222:225], v[88:91]
	v_mfma_f32_16x16x32_bf16 v[76:79], v[174:177], v[232:235], v[76:79]
	v_mfma_f32_16x16x32_bf16 v[72:75], v[182:185], v[232:235], v[72:75]
	v_mfma_f32_16x16x32_bf16 v[124:127], v[178:181], v[210:213], v[124:127]
	v_mfma_f32_16x16x32_bf16 v[120:123], v[186:189], v[210:213], v[120:123]
	v_mfma_f32_16x16x32_bf16 v[108:111], v[178:181], v[218:221], v[108:111]
	v_mfma_f32_16x16x32_bf16 v[104:107], v[186:189], v[218:221], v[104:107]
	v_mfma_f32_16x16x32_bf16 v[92:95], v[178:181], v[228:231], v[92:95]
	v_mfma_f32_16x16x32_bf16 v[88:91], v[186:189], v[228:231], v[88:91]
	v_mfma_f32_16x16x32_bf16 v[76:79], v[178:181], v[236:239], v[76:79]
	v_mfma_f32_16x16x32_bf16 v[72:75], v[186:189], v[236:239], v[72:75]
	v_mfma_f32_16x16x32_bf16 v[116:119], v[190:193], v[206:209], v[116:119]
	v_mfma_f32_16x16x32_bf16 v[112:115], v[198:201], v[206:209], v[112:115]
	v_mfma_f32_16x16x32_bf16 v[100:103], v[190:193], v[214:217], v[100:103]
	v_mfma_f32_16x16x32_bf16 v[96:99], v[198:201], v[214:217], v[96:99]
	v_mfma_f32_16x16x32_bf16 v[84:87], v[190:193], v[222:225], v[84:87]
	v_mfma_f32_16x16x32_bf16 v[80:83], v[198:201], v[222:225], v[80:83]
	v_mfma_f32_16x16x32_bf16 v[68:71], v[190:193], v[232:235], v[68:71]
	v_mfma_f32_16x16x32_bf16 v[64:67], v[198:201], v[232:235], v[64:67]
	v_mfma_f32_16x16x32_bf16 v[116:119], v[194:197], v[210:213], v[116:119]
	v_mfma_f32_16x16x32_bf16 v[112:115], v[202:205], v[210:213], v[112:115]
	v_mfma_f32_16x16x32_bf16 v[100:103], v[194:197], v[218:221], v[100:103]
	v_mfma_f32_16x16x32_bf16 v[96:99], v[202:205], v[218:221], v[96:99]
	v_mfma_f32_16x16x32_bf16 v[84:87], v[194:197], v[228:231], v[84:87]
	v_mfma_f32_16x16x32_bf16 v[80:83], v[202:205], v[228:231], v[80:83]
	v_mfma_f32_16x16x32_bf16 v[68:71], v[194:197], v[236:239], v[68:71]
	v_mfma_f32_16x16x32_bf16 v[64:67], v[202:205], v[236:239], v[64:67]
	s_barrier
	s_mov_b32 m0, s76
	v_lshl_add_u64 v[168:169], s[58:59], 0, v[132:133]
	ds_read_b128 v[206:209], v145 offset:16384
	ds_read_b128 v[210:213], v145 offset:17408
	ds_read_b128 v[214:217], v145 offset:18432
	ds_read_b128 v[218:221], v145 offset:19456
	ds_read_b128 v[222:225], v145 offset:20480
	ds_read_b128 v[228:231], v145 offset:21504
	ds_read_b128 v[232:235], v145 offset:22528
	ds_read_b128 v[236:239], v145 offset:23552
	global_load_lds_dwordx4 v[168:169], off
	v_lshl_add_u64 v[240:241], s[58:59], 0, v[128:129]
	s_mov_b32 m0, s86
	v_lshl_add_u64 v[242:243], s[60:61], 0, v[132:133]
	global_load_lds_dwordx4 v[240:241], off
	s_mov_b32 m0, s88
	v_lshl_add_u64 v[244:245], s[56:57], 0, v[130:131]
	global_load_lds_dwordx4 v[242:243], off
	v_lshl_add_u64 v[242:243], s[60:61], 0, v[128:129]
	s_mov_b32 m0, s87
	s_nop 0
	global_load_lds_dwordx4 v[242:243], off
	v_lshl_add_u64 v[242:243], s[56:57], 0, v[134:135]
	s_mov_b32 m0, s3
	s_nop 0
	global_load_lds_dwordx4 v[242:243], off
	s_mov_b32 m0, s65
	s_nop 0
	global_load_lds_dwordx4 v[244:245], off
	s_waitcnt vmcnt(8)
	s_waitcnt lgkmcnt(0)
	s_barrier
; #define PG8_STAGE(bufoff, gbase, voff) do { _Pragma("unroll") for (int _i = 0; _i < 2; ++_i) \
;         __builtin_amdgcn_global_load_lds((const unsigned*)((const char*)(gbase) + (voff)[_i]), (LAS unsigned*)(lds + (bufoff) + ldsw + _i * 8192), 16, 0, 0); } while (0)
; #define PG8_LDA(dst, b, h) do { _Pragma("unroll") for (int m = 0; m < 4; ++m) _Pragma("unroll") for (int k = 0; k < 2; ++k) dst[m][k] = *(const LAS bf16x8*)(lds + PG8_SA(b, h) + aoff + m * 2048 + k * 1024); } while (0)
; #define PG8_LDB(dst, b, h) do { _Pragma("unroll") for (int n = 0; n < 2; ++n) _Pragma("unroll") for (int k = 0; k < 2; ++k) dst[n][k] = *(const LAS bf16x8*)(lds + PG8_SB(b, h) + boff + n * 2048 + k * 1024); } while (0)
; #define PG8_MMA(ai, bj, At, Bt) do { __builtin_amdgcn_s_setprio(1); _Pragma("unroll") for (int m = 0; m < 4; ++m) _Pragma("unroll") for (int n = 0; n < 2; ++n) _Pragma("unroll") for (int k = 0; k < 2; ++k) \
;         acc[ai][bj][m][n] = __builtin_amdgcn_mfma_f32_16x16x32_bf16(Bt[n][k], At[m][k], acc[ai][bj][m][n], 0, 0, 0); __builtin_amdgcn_s_setprio(0); } while (0)
; #define PG8_WAIT_V(n) asm volatile("s_waitcnt vmcnt(" #n ")" ::: "memory")
; #define PG8_WAIT_L(n) asm volatile("s_waitcnt lgkmcnt(" #n ")" ::: "memory")
; #define PG8_BAR __builtin_amdgcn_s_barrier()
; #define PG8_SCHED __builtin_amdgcn_sched_barrier(0)
; template <class Epi, class Sched, bool ALIGN_EPI = true, bool SP2 = true>
; DI void gemm_phase(LAS unsigned char* lds, const Gemm g, const Sched& S, const Epi& E) {
;     ...
;             PG8_WAIT_V(8); PG8_WAIT_L(0); PG8_BAR; PG8_MMA(1, 0, At, B0); PG8_MMA(1, 1, At, B1); PG8_BAR; PG8_SCHED;
;             PG8_LDB(B0, 1, 0); PG8_LDB(B1, 1, 1); PG8_SCHED; PG8_LDA(At, 1, 0); PG8_STAGE(PG8_SA(0, 1), a2 + hstepA, voffA);
;             PG8_WAIT_V(8); PG8_WAIT_L(0); PG8_BAR; PG8_MMA(0, 0, At, B0); PG8_MMA(0, 1, At, B1); PG8_BAR; PG8_SCHED;
	s_waitcnt lgkmcnt(0)
	v_mfma_f32_16x16x32_bf16 v[60:63], v[174:177], v[206:209], v[60:63]
	v_mfma_f32_16x16x32_bf16 v[56:59], v[182:185], v[206:209], v[56:59]
	v_mfma_f32_16x16x32_bf16 v[44:47], v[174:177], v[214:217], v[44:47]
	v_mfma_f32_16x16x32_bf16 v[40:43], v[182:185], v[214:217], v[40:43]
	v_mfma_f32_16x16x32_bf16 v[28:31], v[174:177], v[222:225], v[28:31]
	v_mfma_f32_16x16x32_bf16 v[24:27], v[182:185], v[222:225], v[24:27]
	v_mfma_f32_16x16x32_bf16 v[12:15], v[174:177], v[232:235], v[12:15]
	v_mfma_f32_16x16x32_bf16 v[8:11], v[182:185], v[232:235], v[8:11]
	v_mfma_f32_16x16x32_bf16 v[60:63], v[178:181], v[210:213], v[60:63]
	v_mfma_f32_16x16x32_bf16 v[56:59], v[186:189], v[210:213], v[56:59]
	v_mfma_f32_16x16x32_bf16 v[44:47], v[178:181], v[218:221], v[44:47]
	v_mfma_f32_16x16x32_bf16 v[40:43], v[186:189], v[218:221], v[40:43]
	v_mfma_f32_16x16x32_bf16 v[28:31], v[178:181], v[228:231], v[28:31]
	v_mfma_f32_16x16x32_bf16 v[24:27], v[186:189], v[228:231], v[24:27]
	v_mfma_f32_16x16x32_bf16 v[12:15], v[178:181], v[236:239], v[12:15]
	v_mfma_f32_16x16x32_bf16 v[8:11], v[186:189], v[236:239], v[8:11]
	v_mfma_f32_16x16x32_bf16 v[52:55], v[190:193], v[206:209], v[52:55]
	v_mfma_f32_16x16x32_bf16 v[48:51], v[198:201], v[206:209], v[48:51]
	v_mfma_f32_16x16x32_bf16 v[36:39], v[190:193], v[214:217], v[36:39]
	v_mfma_f32_16x16x32_bf16 v[32:35], v[198:201], v[214:217], v[32:35]
	v_mfma_f32_16x16x32_bf16 v[20:23], v[190:193], v[222:225], v[20:23]
	v_mfma_f32_16x16x32_bf16 v[16:19], v[198:201], v[222:225], v[16:19]
	v_mfma_f32_16x16x32_bf16 v[4:7], v[190:193], v[232:235], v[4:7]
	v_mfma_f32_16x16x32_bf16 v[0:3], v[198:201], v[232:235], v[0:3]
	v_mfma_f32_16x16x32_bf16 v[52:55], v[194:197], v[210:213], v[52:55]
	v_mfma_f32_16x16x32_bf16 v[48:51], v[202:205], v[210:213], v[48:51]
	v_mfma_f32_16x16x32_bf16 v[36:39], v[194:197], v[218:221], v[36:39]
	v_mfma_f32_16x16x32_bf16 v[32:35], v[202:205], v[218:221], v[32:35]
	v_mfma_f32_16x16x32_bf16 v[20:23], v[194:197], v[228:231], v[20:23]
	v_mfma_f32_16x16x32_bf16 v[16:19], v[202:205], v[228:231], v[16:19]
	v_mfma_f32_16x16x32_bf16 v[4:7], v[194:197], v[236:239], v[4:7]
	v_mfma_f32_16x16x32_bf16 v[0:3], v[202:205], v[236:239], v[0:3]
	s_barrier
	v_add_u32_e32 v161, s85, v171
	ds_read_b128 v[174:177], v161
	ds_read_b128 v[178:181], v161 offset:1024
	ds_read_b128 v[182:185], v161 offset:2048
	ds_read_b128 v[186:189], v161 offset:3072
	v_add_u32_e32 v161, s84, v171
	ds_read_b128 v[190:193], v161
	ds_read_b128 v[194:197], v161 offset:1024
	ds_read_b128 v[198:201], v161 offset:2048
	ds_read_b128 v[202:205], v161 offset:3072
	s_mov_b32 m0, s66
	v_lshl_add_u64 v[246:247], s[54:55], 0, v[134:135]
	ds_read_b128 v[206:209], v145 offset:32768
	ds_read_b128 v[210:213], v145 offset:33792
	ds_read_b128 v[214:217], v145 offset:34816
	ds_read_b128 v[218:221], v145 offset:35840
	ds_read_b128 v[222:225], v145 offset:36864
	ds_read_b128 v[228:231], v145 offset:37888
	ds_read_b128 v[232:235], v145 offset:38912
	ds_read_b128 v[236:239], v145 offset:39936
	global_load_lds_dwordx4 v[246:247], off
	v_lshl_add_u64 v[246:247], s[54:55], 0, v[130:131]
	s_mov_b32 m0, s67
	s_nop 0
	global_load_lds_dwordx4 v[246:247], off
	s_waitcnt vmcnt(8)
	s_waitcnt lgkmcnt(0)
	s_barrier
	s_waitcnt lgkmcnt(0)
	v_mfma_f32_16x16x32_bf16 v[124:127], v[174:177], v[206:209], v[124:127]
	v_mfma_f32_16x16x32_bf16 v[120:123], v[182:185], v[206:209], v[120:123]
	v_mfma_f32_16x16x32_bf16 v[108:111], v[174:177], v[214:217], v[108:111]
	v_mfma_f32_16x16x32_bf16 v[104:107], v[182:185], v[214:217], v[104:107]
	v_mfma_f32_16x16x32_bf16 v[92:95], v[174:177], v[222:225], v[92:95]
	v_mfma_f32_16x16x32_bf16 v[88:91], v[182:185], v[222:225], v[88:91]
	v_mfma_f32_16x16x32_bf16 v[76:79], v[174:177], v[232:235], v[76:79]
	v_mfma_f32_16x16x32_bf16 v[72:75], v[182:185], v[232:235], v[72:75]
	v_mfma_f32_16x16x32_bf16 v[124:127], v[178:181], v[210:213], v[124:127]
	v_mfma_f32_16x16x32_bf16 v[120:123], v[186:189], v[210:213], v[120:123]
	v_mfma_f32_16x16x32_bf16 v[108:111], v[178:181], v[218:221], v[108:111]
	v_mfma_f32_16x16x32_bf16 v[104:107], v[186:189], v[218:221], v[104:107]
	v_mfma_f32_16x16x32_bf16 v[92:95], v[178:181], v[228:231], v[92:95]
	v_mfma_f32_16x16x32_bf16 v[88:91], v[186:189], v[228:231], v[88:91]
	v_mfma_f32_16x16x32_bf16 v[76:79], v[178:181], v[236:239], v[76:79]
	v_mfma_f32_16x16x32_bf16 v[72:75], v[186:189], v[236:239], v[72:75]
	v_mfma_f32_16x16x32_bf16 v[116:119], v[190:193], v[206:209], v[116:119]
	v_mfma_f32_16x16x32_bf16 v[112:115], v[198:201], v[206:209], v[112:115]
	v_mfma_f32_16x16x32_bf16 v[100:103], v[190:193], v[214:217], v[100:103]
	v_mfma_f32_16x16x32_bf16 v[96:99], v[198:201], v[214:217], v[96:99]
	v_mfma_f32_16x16x32_bf16 v[84:87], v[190:193], v[222:225], v[84:87]
	v_mfma_f32_16x16x32_bf16 v[80:83], v[198:201], v[222:225], v[80:83]
	v_mfma_f32_16x16x32_bf16 v[68:71], v[190:193], v[232:235], v[68:71]
	v_mfma_f32_16x16x32_bf16 v[64:67], v[198:201], v[232:235], v[64:67]
	v_mfma_f32_16x16x32_bf16 v[116:119], v[194:197], v[210:213], v[116:119]
	v_mfma_f32_16x16x32_bf16 v[112:115], v[202:205], v[210:213], v[112:115]
	v_mfma_f32_16x16x32_bf16 v[100:103], v[194:197], v[218:221], v[100:103]
	v_mfma_f32_16x16x32_bf16 v[96:99], v[202:205], v[218:221], v[96:99]
	v_mfma_f32_16x16x32_bf16 v[84:87], v[194:197], v[228:231], v[84:87]
	v_mfma_f32_16x16x32_bf16 v[80:83], v[202:205], v[228:231], v[80:83]
	v_mfma_f32_16x16x32_bf16 v[68:71], v[194:197], v[236:239], v[68:71]
	v_mfma_f32_16x16x32_bf16 v[64:67], v[202:205], v[236:239], v[64:67]
	s_barrier
; #define PG8_STAGE(bufoff, gbase, voff) do { _Pragma("unroll") for (int _i = 0; _i < 2; ++_i) \
;         __builtin_amdgcn_global_load_lds((const unsigned*)((const char*)(gbase) + (voff)[_i]), (LAS unsigned*)(lds + (bufoff) + ldsw + _i * 8192), 16, 0, 0); } while (0)
; #define PG8_LDA(dst, b, h) do { _Pragma("unroll") for (int m = 0; m < 4; ++m) _Pragma("unroll") for (int k = 0; k < 2; ++k) dst[m][k] = *(const LAS bf16x8*)(lds + PG8_SA(b, h) + aoff + m * 2048 + k * 1024); } while (0)
; #define PG8_MMA(ai, bj, At, Bt) do { __builtin_amdgcn_s_setprio(1); _Pragma("unroll") for (int m = 0; m < 4; ++m) _Pragma("unroll") for (int n = 0; n < 2; ++n) _Pragma("unroll") for (int k = 0; k < 2; ++k) \
;         acc[ai][bj][m][n] = __builtin_amdgcn_mfma_f32_16x16x32_bf16(Bt[n][k], At[m][k], acc[ai][bj][m][n], 0, 0, 0); __builtin_amdgcn_s_setprio(0); } while (0)
; #define PG8_WAIT_V(n) asm volatile("s_waitcnt vmcnt(" #n ")" ::: "memory")
; #define PG8_WAIT_L(n) asm volatile("s_waitcnt lgkmcnt(" #n ")" ::: "memory")
; #define PG8_BAR __builtin_amdgcn_s_barrier()
; #define PG8_SCHED __builtin_amdgcn_sched_barrier(0)
; template <class Epi, class Sched, bool ALIGN_EPI = true, bool SP2 = true>
; DI void gemm_phase(LAS unsigned char* lds, const Gemm g, const Sched& S, const Epi& E) {
;     ...
;             PG8_LDA(At, 1, 1); PG8_STAGE(PG8_SB(1, 0), b3, voffB); PG8_STAGE(PG8_SB(1, 1), b3 + hstepB, voffB); PG8_STAGE(PG8_SA(1, 0), a3, voffA);
;             PG8_WAIT_V(8); PG8_WAIT_L(0); PG8_BAR; PG8_MMA(1, 0, At, B0); PG8_MMA(1, 1, At, B1); PG8_BAR; PG8_SCHED;
;         }
;         if constexpr (ALIGN_EPI) { if (wr == 0) PG8_BAR; }
;         E(acc, cur, wr, wc, fr, fq);
;         if (!has_next) break;
	s_mov_b32 m0, s81
	v_lshl_add_u64 v[168:169], v[168:169], 0, s[8:9]
	ds_read_b128 v[206:209], v145 offset:49152
	ds_read_b128 v[210:213], v145 offset:50176
	ds_read_b128 v[214:217], v145 offset:51200
	ds_read_b128 v[218:221], v145 offset:52224
	ds_read_b128 v[222:225], v145 offset:53248
	ds_read_b128 v[228:231], v145 offset:54272
	ds_read_b128 v[232:235], v145 offset:55296
	ds_read_b128 v[236:239], v145 offset:56320
	global_load_lds_dwordx4 v[168:169], off
	v_lshl_add_u64 v[168:169], v[240:241], 0, s[8:9]
	s_mov_b32 m0, s79
	s_nop 0
	global_load_lds_dwordx4 v[168:169], off
	v_lshl_add_u64 v[168:169], s[48:49], 0, v[132:133]
	s_mov_b32 m0, s92
	s_nop 0
	global_load_lds_dwordx4 v[168:169], off
	v_lshl_add_u64 v[168:169], s[48:49], 0, v[128:129]
	s_mov_b32 m0, s89
	s_nop 0
	global_load_lds_dwordx4 v[168:169], off
	v_lshl_add_u64 v[168:169], v[242:243], 0, s[8:9]
	s_mov_b32 m0, s69
	s_nop 0
	global_load_lds_dwordx4 v[168:169], off
	v_lshl_add_u64 v[168:169], v[244:245], 0, s[8:9]
	s_mov_b32 m0, s70
	s_nop 0
	global_load_lds_dwordx4 v[168:169], off
	s_waitcnt vmcnt(8)
	s_waitcnt lgkmcnt(0)
	s_barrier
	s_waitcnt lgkmcnt(0)
	v_mfma_f32_16x16x32_bf16 v[60:63], v[174:177], v[206:209], v[60:63]
	v_mfma_f32_16x16x32_bf16 v[56:59], v[182:185], v[206:209], v[56:59]
	v_mfma_f32_16x16x32_bf16 v[44:47], v[174:177], v[214:217], v[44:47]
	v_mfma_f32_16x16x32_bf16 v[40:43], v[182:185], v[214:217], v[40:43]
	v_mfma_f32_16x16x32_bf16 v[28:31], v[174:177], v[222:225], v[28:31]
	v_mfma_f32_16x16x32_bf16 v[24:27], v[182:185], v[222:225], v[24:27]
	v_mfma_f32_16x16x32_bf16 v[12:15], v[174:177], v[232:235], v[12:15]
	v_mfma_f32_16x16x32_bf16 v[8:11], v[182:185], v[232:235], v[8:11]
	v_mfma_f32_16x16x32_bf16 v[60:63], v[178:181], v[210:213], v[60:63]
	v_mfma_f32_16x16x32_bf16 v[56:59], v[186:189], v[210:213], v[56:59]
	v_mfma_f32_16x16x32_bf16 v[44:47], v[178:181], v[218:221], v[44:47]
	v_mfma_f32_16x16x32_bf16 v[40:43], v[186:189], v[218:221], v[40:43]
	v_mfma_f32_16x16x32_bf16 v[28:31], v[178:181], v[228:231], v[28:31]
	v_mfma_f32_16x16x32_bf16 v[24:27], v[186:189], v[228:231], v[24:27]
	v_mfma_f32_16x16x32_bf16 v[12:15], v[178:181], v[236:239], v[12:15]
	v_mfma_f32_16x16x32_bf16 v[8:11], v[186:189], v[236:239], v[8:11]
	v_mfma_f32_16x16x32_bf16 v[52:55], v[190:193], v[206:209], v[52:55]
	v_mfma_f32_16x16x32_bf16 v[48:51], v[198:201], v[206:209], v[48:51]
	v_mfma_f32_16x16x32_bf16 v[36:39], v[190:193], v[214:217], v[36:39]
	v_mfma_f32_16x16x32_bf16 v[32:35], v[198:201], v[214:217], v[32:35]
	v_mfma_f32_16x16x32_bf16 v[20:23], v[190:193], v[222:225], v[20:23]
	v_mfma_f32_16x16x32_bf16 v[16:19], v[198:201], v[222:225], v[16:19]
	v_mfma_f32_16x16x32_bf16 v[4:7], v[190:193], v[232:235], v[4:7]
	v_mfma_f32_16x16x32_bf16 v[0:3], v[198:201], v[232:235], v[0:3]
	v_mfma_f32_16x16x32_bf16 v[52:55], v[194:197], v[210:213], v[52:55]
	v_mfma_f32_16x16x32_bf16 v[48:51], v[202:205], v[210:213], v[48:51]
	v_mfma_f32_16x16x32_bf16 v[36:39], v[194:197], v[218:221], v[36:39]
	v_mfma_f32_16x16x32_bf16 v[32:35], v[202:205], v[218:221], v[32:35]
	v_mfma_f32_16x16x32_bf16 v[20:23], v[194:197], v[228:231], v[20:23]
	v_mfma_f32_16x16x32_bf16 v[16:19], v[202:205], v[228:231], v[16:19]
	v_mfma_f32_16x16x32_bf16 v[4:7], v[194:197], v[236:239], v[4:7]
	v_mfma_f32_16x16x32_bf16 v[0:3], v[202:205], v[236:239], v[0:3]
	s_barrier
	s_andn2_b64 vcc, exec, s[44:45]
	s_mov_b64 s[48:49], -1
	s_mov_b64 s[44:45], 0
	s_mov_b64 s[54:55], 0x100
	s_cbranch_vccz .LBB0_1693
	s_and_b64 vcc, exec, s[12:13]
	s_cbranch_vccz .LBB0_1696
	s_barrier

;     DI size_t offA(const Unit& u) const { return (size_t)u.pm * tA + (size_t)u.pn * aPn; }
;     DI size_t offB(const Unit& u) const { return (size_t)u.pn * tB; }
; #define PG8_STAGE(bufoff, gbase, voff) do { _Pragma("unroll") for (int _i = 0; _i < 2; ++_i) \
;         __builtin_amdgcn_global_load_lds((const unsigned*)((const char*)(gbase) + (voff)[_i]), (LAS unsigned*)(lds + (bufoff) + ldsw + _i * 8192), 16, 0, 0); } while (0)
; #define PG8_LDA(dst, b, h) do { _Pragma("unroll") for (int m = 0; m < 4; ++m) _Pragma("unroll") for (int k = 0; k < 2; ++k) dst[m][k] = *(const LAS bf16x8*)(lds + PG8_SA(b, h) + aoff + m * 2048 + k * 1024); } while (0)
; #define PG8_LDB(dst, b, h) do { _Pragma("unroll") for (int n = 0; n < 2; ++n) _Pragma("unroll") for (int k = 0; k < 2; ++k) dst[n][k] = *(const LAS bf16x8*)(lds + PG8_SB(b, h) + boff + n * 2048 + k * 1024); } while (0)
; #define PG8_MMA(ai, bj, At, Bt) do { __builtin_amdgcn_s_setprio(1); _Pragma("unroll") for (int m = 0; m < 4; ++m) _Pragma("unroll") for (int n = 0; n < 2; ++n) _Pragma("unroll") for (int k = 0; k < 2; ++k) \
;         acc[ai][bj][m][n] = __builtin_amdgcn_mfma_f32_16x16x32_bf16(Bt[n][k], At[m][k], acc[ai][bj][m][n], 0, 0, 0); __builtin_amdgcn_s_setprio(0); } while (0)
; #define PG8_BAR __builtin_amdgcn_s_barrier()
; template <class Epi, class Sched, bool ALIGN_EPI = true, bool SP2 = true>
; DI void gemm_phase(LAS unsigned char* lds, const Gemm g, const Sched& S, const Epi& E) {
;     ...
;         const char* nA = has_next ? (const char*)g.A + S.offA(nxt) : cA; const char* nB = has_next ? (const char*)g.Bt + S.offB(nxt) : cB;
; #pragma unroll 1
;         for (int t = 0; t < nt; t += 2) {
;             const bool last = (t == nt - 2);
;             const char* a1 = cA + (size_t)(t + 1) * kstep;
;             const char* a2 = last ? nA : cA + (size_t)(t + 2) * kstep; const char* b2 = last ? nB : cB + (size_t)(t + 2) * kstep;
;             const char* a3 = a2 + kstep; const char* b3 = b2 + kstep;
;             PG8_LDB(B0, 0, 0); PG8_LDB(B1, 0, 1); PG8_SCHED; PG8_LDA(At, 0, 0); PG8_STAGE(PG8_SA(1, 1), a1 + hstepA, voffA);
;             PG8_WAIT_V(8); PG8_WAIT_L(0); PG8_BAR; PG8_MMA(0, 0, At, B0); PG8_MMA(0, 1, At, B1); PG8_BAR; PG8_SCHED;
;             PG8_LDA(At, 0, 1); PG8_STAGE(PG8_SB(0, 0), b2, voffB); PG8_STAGE(PG8_SB(0, 1), b2 + hstepB, voffB); PG8_STAGE(PG8_SA(0, 0), a2, voffA);
.LBB0_1903:
	s_add_u32 s68, s56, s62
	s_addc_u32 s69, s57, s63
	s_add_u32 s66, s68, 0x100
	s_addc_u32 s67, s69, 0
	s_and_b64 s[64:65], s[60:61], exec
	s_cselect_b32 s65, s1, s67
	s_cselect_b32 s64, s0, s66
	s_add_u32 s62, s54, s62
	s_addc_u32 s63, s55, s63
	s_add_u32 s62, s62, 0x100
	s_addc_u32 s63, s63, 0
	s_and_b64 s[60:61], s[60:61], exec
	s_cselect_b32 s67, s39, s63
	s_cselect_b32 s66, s43, s62
	s_add_u32 s70, s68, 0x40080
	ds_read_b128 v[140:143], v152
	ds_read_b128 v[144:147], v152 offset:1024
	ds_read_b128 v[156:159], v152 offset:2048
	ds_read_b128 v[160:163], v152 offset:3072
	ds_read_b128 v[164:167], v153
	ds_read_b128 v[168:171], v153 offset:1024
	ds_read_b128 v[172:175], v153 offset:2048
	ds_read_b128 v[176:179], v153 offset:3072
	s_addc_u32 s71, s69, 0
	s_add_i32 s95, s84, s74
	s_add_i32 m0, s75, 0xc000
	s_add_i32 vcc_lo, s75, 0xe000
	s_add_i32 s92, s95, 0x2000
	s_add_u32 s68, s66, 0x10000
	s_addc_u32 s69, s67, 0
	s_add_i32 s94, s85, s74
	s_add_i32 s93, s94, 0x2000
	s_add_i32 s91, 0, 0x18000
	s_add_i32 s90, 0, 0x1c000
	s_add_u32 s62, s64, 0x40000
	s_addc_u32 s63, s65, 0
	s_add_i32 s89, s91, s74
	s_add_i32 s88, s89, 0x2000
	s_add_u32 s60, s66, 0x10080
	s_addc_u32 s61, s67, 0
	s_add_i32 s97, s90, s74
	s_add_i32 s96, s97, 0x2000
	v_lshl_add_u64 v[212:213], s[70:71], 0, v[128:129]
	ds_read_b128 v[180:183], v154
	ds_read_b128 v[184:187], v154 offset:1024
	ds_read_b128 v[188:191], v154 offset:2048
	ds_read_b128 v[192:195], v154 offset:3072
	ds_read_b128 v[196:199], v154 offset:4096
	ds_read_b128 v[200:203], v154 offset:5120
	ds_read_b128 v[204:207], v154 offset:6144
	ds_read_b128 v[208:211], v154 offset:7168
	global_load_lds_dwordx4 v[212:213], off
	v_lshl_add_u64 v[212:213], s[70:71], 0, v[132:133]
	s_mov_b32 m0, vcc_lo
	s_nop 0
	global_load_lds_dwordx4 v[212:213], off
	s_waitcnt vmcnt(8)
	s_waitcnt lgkmcnt(0)
	s_barrier
	s_waitcnt lgkmcnt(0)
	v_mfma_f32_16x16x32_bf16 v[124:127], v[140:143], v[180:183], v[124:127]
	v_mfma_f32_16x16x32_bf16 v[120:123], v[156:159], v[180:183], v[120:123]
	v_mfma_f32_16x16x32_bf16 v[108:111], v[140:143], v[188:191], v[108:111]
	v_mfma_f32_16x16x32_bf16 v[104:107], v[156:159], v[188:191], v[104:107]
	v_mfma_f32_16x16x32_bf16 v[92:95], v[140:143], v[196:199], v[92:95]
	v_mfma_f32_16x16x32_bf16 v[88:91], v[156:159], v[196:199], v[88:91]
	v_mfma_f32_16x16x32_bf16 v[76:79], v[140:143], v[204:207], v[76:79]
	v_mfma_f32_16x16x32_bf16 v[72:75], v[156:159], v[204:207], v[72:75]
	v_mfma_f32_16x16x32_bf16 v[124:127], v[144:147], v[184:187], v[124:127]
	v_mfma_f32_16x16x32_bf16 v[120:123], v[160:163], v[184:187], v[120:123]
	v_mfma_f32_16x16x32_bf16 v[108:111], v[144:147], v[192:195], v[108:111]
	v_mfma_f32_16x16x32_bf16 v[104:107], v[160:163], v[192:195], v[104:107]
	v_mfma_f32_16x16x32_bf16 v[92:95], v[144:147], v[200:203], v[92:95]
	v_mfma_f32_16x16x32_bf16 v[88:91], v[160:163], v[200:203], v[88:91]
	v_mfma_f32_16x16x32_bf16 v[76:79], v[144:147], v[208:211], v[76:79]
	v_mfma_f32_16x16x32_bf16 v[72:75], v[160:163], v[208:211], v[72:75]
	v_mfma_f32_16x16x32_bf16 v[116:119], v[164:167], v[180:183], v[116:119]
	v_mfma_f32_16x16x32_bf16 v[112:115], v[172:175], v[180:183], v[112:115]
	v_mfma_f32_16x16x32_bf16 v[100:103], v[164:167], v[188:191], v[100:103]
	v_mfma_f32_16x16x32_bf16 v[96:99], v[172:175], v[188:191], v[96:99]
	v_mfma_f32_16x16x32_bf16 v[84:87], v[164:167], v[196:199], v[84:87]
	v_mfma_f32_16x16x32_bf16 v[80:83], v[172:175], v[196:199], v[80:83]
	v_mfma_f32_16x16x32_bf16 v[68:71], v[164:167], v[204:207], v[68:71]
	v_mfma_f32_16x16x32_bf16 v[64:67], v[172:175], v[204:207], v[64:67]
	v_mfma_f32_16x16x32_bf16 v[116:119], v[168:171], v[184:187], v[116:119]
	v_mfma_f32_16x16x32_bf16 v[112:115], v[176:179], v[184:187], v[112:115]
	v_mfma_f32_16x16x32_bf16 v[100:103], v[168:171], v[192:195], v[100:103]
	v_mfma_f32_16x16x32_bf16 v[96:99], v[176:179], v[192:195], v[96:99]
	v_mfma_f32_16x16x32_bf16 v[84:87], v[168:171], v[200:203], v[84:87]
	v_mfma_f32_16x16x32_bf16 v[80:83], v[176:179], v[200:203], v[80:83]
	v_mfma_f32_16x16x32_bf16 v[68:71], v[168:171], v[208:211], v[68:71]
	v_mfma_f32_16x16x32_bf16 v[64:67], v[176:179], v[208:211], v[64:67]
	s_barrier
	s_mov_b32 m0, s95
	v_lshl_add_u64 v[212:213], s[66:67], 0, v[130:131]
	ds_read_b128 v[180:183], v154 offset:16384
	ds_read_b128 v[184:187], v154 offset:17408
	ds_read_b128 v[188:191], v154 offset:18432
	ds_read_b128 v[192:195], v154 offset:19456
	ds_read_b128 v[196:199], v154 offset:20480
	ds_read_b128 v[200:203], v154 offset:21504
	ds_read_b128 v[204:207], v154 offset:22528
	ds_read_b128 v[208:211], v154 offset:23552
	global_load_lds_dwordx4 v[212:213], off
	v_lshl_add_u64 v[214:215], s[66:67], 0, v[134:135]
	s_mov_b32 m0, s92
	v_lshl_add_u64 v[216:217], s[68:69], 0, v[130:131]
	global_load_lds_dwordx4 v[214:215], off
	s_mov_b32 m0, s94
	v_lshl_add_u64 v[218:219], s[64:65], 0, v[132:133]
	global_load_lds_dwordx4 v[216:217], off
	v_lshl_add_u64 v[216:217], s[68:69], 0, v[134:135]
	s_mov_b32 m0, s93
	s_nop 0
	global_load_lds_dwordx4 v[216:217], off
	v_lshl_add_u64 v[216:217], s[64:65], 0, v[128:129]
	s_mov_b32 m0, s75
	s_nop 0
	global_load_lds_dwordx4 v[216:217], off
	s_mov_b32 m0, s49
	s_nop 0
	global_load_lds_dwordx4 v[218:219], off
	s_waitcnt vmcnt(8)
	s_waitcnt lgkmcnt(0)
	s_barrier
; #define PG8_STAGE(bufoff, gbase, voff) do { _Pragma("unroll") for (int _i = 0; _i < 2; ++_i) \
;         __builtin_amdgcn_global_load_lds((const unsigned*)((const char*)(gbase) + (voff)[_i]), (LAS unsigned*)(lds + (bufoff) + ldsw + _i * 8192), 16, 0, 0); } while (0)
; #define PG8_LDA(dst, b, h) do { _Pragma("unroll") for (int m = 0; m < 4; ++m) _Pragma("unroll") for (int k = 0; k < 2; ++k) dst[m][k] = *(const LAS bf16x8*)(lds + PG8_SA(b, h) + aoff + m * 2048 + k * 1024); } while (0)
; #define PG8_LDB(dst, b, h) do { _Pragma("unroll") for (int n = 0; n < 2; ++n) _Pragma("unroll") for (int k = 0; k < 2; ++k) dst[n][k] = *(const LAS bf16x8*)(lds + PG8_SB(b, h) + boff + n * 2048 + k * 1024); } while (0)
; #define PG8_MMA(ai, bj, At, Bt) do { __builtin_amdgcn_s_setprio(1); _Pragma("unroll") for (int m = 0; m < 4; ++m) _Pragma("unroll") for (int n = 0; n < 2; ++n) _Pragma("unroll") for (int k = 0; k < 2; ++k) \
;         acc[ai][bj][m][n] = __builtin_amdgcn_mfma_f32_16x16x32_bf16(Bt[n][k], At[m][k], acc[ai][bj][m][n], 0, 0, 0); __builtin_amdgcn_s_setprio(0); } while (0)
; #define PG8_WAIT_V(n) asm volatile("s_waitcnt vmcnt(" #n ")" ::: "memory")
; #define PG8_WAIT_L(n) asm volatile("s_waitcnt lgkmcnt(" #n ")" ::: "memory")
; #define PG8_BAR __builtin_amdgcn_s_barrier()
; #define PG8_SCHED __builtin_amdgcn_sched_barrier(0)
; template <class Epi, class Sched, bool ALIGN_EPI = true, bool SP2 = true>
; DI void gemm_phase(LAS unsigned char* lds, const Gemm g, const Sched& S, const Epi& E) {
;     ...
;             PG8_WAIT_V(8); PG8_WAIT_L(0); PG8_BAR; PG8_MMA(1, 0, At, B0); PG8_MMA(1, 1, At, B1); PG8_BAR; PG8_SCHED;
;             PG8_LDB(B0, 1, 0); PG8_LDB(B1, 1, 1); PG8_SCHED; PG8_LDA(At, 1, 0); PG8_STAGE(PG8_SA(0, 1), a2 + hstepA, voffA);
;             PG8_WAIT_V(8); PG8_WAIT_L(0); PG8_BAR; PG8_MMA(0, 0, At, B0); PG8_MMA(0, 1, At, B1); PG8_BAR; PG8_SCHED;
	s_waitcnt lgkmcnt(0)
	v_mfma_f32_16x16x32_bf16 v[60:63], v[140:143], v[180:183], v[60:63]
	v_mfma_f32_16x16x32_bf16 v[56:59], v[156:159], v[180:183], v[56:59]
	v_mfma_f32_16x16x32_bf16 v[44:47], v[140:143], v[188:191], v[44:47]
	v_mfma_f32_16x16x32_bf16 v[40:43], v[156:159], v[188:191], v[40:43]
	v_mfma_f32_16x16x32_bf16 v[28:31], v[140:143], v[196:199], v[28:31]
	v_mfma_f32_16x16x32_bf16 v[24:27], v[156:159], v[196:199], v[24:27]
	v_mfma_f32_16x16x32_bf16 v[12:15], v[140:143], v[204:207], v[12:15]
	v_mfma_f32_16x16x32_bf16 v[8:11], v[156:159], v[204:207], v[8:11]
	v_mfma_f32_16x16x32_bf16 v[60:63], v[144:147], v[184:187], v[60:63]
	v_mfma_f32_16x16x32_bf16 v[56:59], v[160:163], v[184:187], v[56:59]
	v_mfma_f32_16x16x32_bf16 v[44:47], v[144:147], v[192:195], v[44:47]
	v_mfma_f32_16x16x32_bf16 v[40:43], v[160:163], v[192:195], v[40:43]
	v_mfma_f32_16x16x32_bf16 v[28:31], v[144:147], v[200:203], v[28:31]
	v_mfma_f32_16x16x32_bf16 v[24:27], v[160:163], v[200:203], v[24:27]
	v_mfma_f32_16x16x32_bf16 v[12:15], v[144:147], v[208:211], v[12:15]
	v_mfma_f32_16x16x32_bf16 v[8:11], v[160:163], v[208:211], v[8:11]
	v_mfma_f32_16x16x32_bf16 v[52:55], v[164:167], v[180:183], v[52:55]
	v_mfma_f32_16x16x32_bf16 v[48:51], v[172:175], v[180:183], v[48:51]
	v_mfma_f32_16x16x32_bf16 v[36:39], v[164:167], v[188:191], v[36:39]
	v_mfma_f32_16x16x32_bf16 v[32:35], v[172:175], v[188:191], v[32:35]
	v_mfma_f32_16x16x32_bf16 v[20:23], v[164:167], v[196:199], v[20:23]
	v_mfma_f32_16x16x32_bf16 v[16:19], v[172:175], v[196:199], v[16:19]
	v_mfma_f32_16x16x32_bf16 v[4:7], v[164:167], v[204:207], v[4:7]
	v_mfma_f32_16x16x32_bf16 v[0:3], v[172:175], v[204:207], v[0:3]
	v_mfma_f32_16x16x32_bf16 v[52:55], v[168:171], v[184:187], v[52:55]
	v_mfma_f32_16x16x32_bf16 v[48:51], v[176:179], v[184:187], v[48:51]
	v_mfma_f32_16x16x32_bf16 v[36:39], v[168:171], v[192:195], v[36:39]
	v_mfma_f32_16x16x32_bf16 v[32:35], v[176:179], v[192:195], v[32:35]
	v_mfma_f32_16x16x32_bf16 v[20:23], v[168:171], v[200:203], v[20:23]
	v_mfma_f32_16x16x32_bf16 v[16:19], v[176:179], v[200:203], v[16:19]
	v_mfma_f32_16x16x32_bf16 v[4:7], v[168:171], v[208:211], v[4:7]
	v_mfma_f32_16x16x32_bf16 v[0:3], v[176:179], v[208:211], v[0:3]
	s_barrier
	v_add_u32_e32 v155, s91, v150
	ds_read_b128 v[140:143], v155
	ds_read_b128 v[144:147], v155 offset:1024
	ds_read_b128 v[156:159], v155 offset:2048
	ds_read_b128 v[160:163], v155 offset:3072
	v_add_u32_e32 v155, s90, v150
	ds_read_b128 v[164:167], v155
	ds_read_b128 v[168:171], v155 offset:1024
	ds_read_b128 v[172:175], v155 offset:2048
	ds_read_b128 v[176:179], v155 offset:3072
	s_mov_b32 m0, s76
	v_lshl_add_u64 v[220:221], s[62:63], 0, v[128:129]
	ds_read_b128 v[180:183], v154 offset:32768
	ds_read_b128 v[184:187], v154 offset:33792
	ds_read_b128 v[188:191], v154 offset:34816
	ds_read_b128 v[192:195], v154 offset:35840
	ds_read_b128 v[196:199], v154 offset:36864
	ds_read_b128 v[200:203], v154 offset:37888
	ds_read_b128 v[204:207], v154 offset:38912
	ds_read_b128 v[208:211], v154 offset:39936
	global_load_lds_dwordx4 v[220:221], off
	v_lshl_add_u64 v[220:221], s[62:63], 0, v[132:133]
	s_mov_b32 m0, s77
	s_nop 0
	global_load_lds_dwordx4 v[220:221], off
	s_waitcnt vmcnt(8)
	s_waitcnt lgkmcnt(0)
	s_barrier
	s_waitcnt lgkmcnt(0)
	v_mfma_f32_16x16x32_bf16 v[124:127], v[140:143], v[180:183], v[124:127]
	v_mfma_f32_16x16x32_bf16 v[120:123], v[156:159], v[180:183], v[120:123]
	v_mfma_f32_16x16x32_bf16 v[108:111], v[140:143], v[188:191], v[108:111]
	v_mfma_f32_16x16x32_bf16 v[104:107], v[156:159], v[188:191], v[104:107]
	v_mfma_f32_16x16x32_bf16 v[92:95], v[140:143], v[196:199], v[92:95]
	v_mfma_f32_16x16x32_bf16 v[88:91], v[156:159], v[196:199], v[88:91]
	v_mfma_f32_16x16x32_bf16 v[76:79], v[140:143], v[204:207], v[76:79]
	v_mfma_f32_16x16x32_bf16 v[72:75], v[156:159], v[204:207], v[72:75]
	v_mfma_f32_16x16x32_bf16 v[124:127], v[144:147], v[184:187], v[124:127]
	v_mfma_f32_16x16x32_bf16 v[120:123], v[160:163], v[184:187], v[120:123]
	v_mfma_f32_16x16x32_bf16 v[108:111], v[144:147], v[192:195], v[108:111]
	v_mfma_f32_16x16x32_bf16 v[104:107], v[160:163], v[192:195], v[104:107]
	v_mfma_f32_16x16x32_bf16 v[92:95], v[144:147], v[200:203], v[92:95]
	v_mfma_f32_16x16x32_bf16 v[88:91], v[160:163], v[200:203], v[88:91]
	v_mfma_f32_16x16x32_bf16 v[76:79], v[144:147], v[208:211], v[76:79]
	v_mfma_f32_16x16x32_bf16 v[72:75], v[160:163], v[208:211], v[72:75]
	v_mfma_f32_16x16x32_bf16 v[116:119], v[164:167], v[180:183], v[116:119]
	v_mfma_f32_16x16x32_bf16 v[112:115], v[172:175], v[180:183], v[112:115]
	v_mfma_f32_16x16x32_bf16 v[100:103], v[164:167], v[188:191], v[100:103]
	v_mfma_f32_16x16x32_bf16 v[96:99], v[172:175], v[188:191], v[96:99]
	v_mfma_f32_16x16x32_bf16 v[84:87], v[164:167], v[196:199], v[84:87]
	v_mfma_f32_16x16x32_bf16 v[80:83], v[172:175], v[196:199], v[80:83]
	v_mfma_f32_16x16x32_bf16 v[68:71], v[164:167], v[204:207], v[68:71]
	v_mfma_f32_16x16x32_bf16 v[64:67], v[172:175], v[204:207], v[64:67]
	v_mfma_f32_16x16x32_bf16 v[116:119], v[168:171], v[184:187], v[116:119]
	v_mfma_f32_16x16x32_bf16 v[112:115], v[176:179], v[184:187], v[112:115]
	v_mfma_f32_16x16x32_bf16 v[100:103], v[168:171], v[192:195], v[100:103]
	v_mfma_f32_16x16x32_bf16 v[96:99], v[176:179], v[192:195], v[96:99]
	v_mfma_f32_16x16x32_bf16 v[84:87], v[168:171], v[200:203], v[84:87]
	v_mfma_f32_16x16x32_bf16 v[80:83], v[176:179], v[200:203], v[80:83]
	v_mfma_f32_16x16x32_bf16 v[68:71], v[168:171], v[208:211], v[68:71]
	v_mfma_f32_16x16x32_bf16 v[64:67], v[176:179], v[208:211], v[64:67]
	s_barrier
; #define PG8_STAGE(bufoff, gbase, voff) do { _Pragma("unroll") for (int _i = 0; _i < 2; ++_i) \
;         __builtin_amdgcn_global_load_lds((const unsigned*)((const char*)(gbase) + (voff)[_i]), (LAS unsigned*)(lds + (bufoff) + ldsw + _i * 8192), 16, 0, 0); } while (0)
; #define PG8_LDA(dst, b, h) do { _Pragma("unroll") for (int m = 0; m < 4; ++m) _Pragma("unroll") for (int k = 0; k < 2; ++k) dst[m][k] = *(const LAS bf16x8*)(lds + PG8_SA(b, h) + aoff + m * 2048 + k * 1024); } while (0)
; #define PG8_MMA(ai, bj, At, Bt) do { __builtin_amdgcn_s_setprio(1); _Pragma("unroll") for (int m = 0; m < 4; ++m) _Pragma("unroll") for (int n = 0; n < 2; ++n) _Pragma("unroll") for (int k = 0; k < 2; ++k) \
;         acc[ai][bj][m][n] = __builtin_amdgcn_mfma_f32_16x16x32_bf16(Bt[n][k], At[m][k], acc[ai][bj][m][n], 0, 0, 0); __builtin_amdgcn_s_setprio(0); } while (0)
; #define PG8_WAIT_V(n) asm volatile("s_waitcnt vmcnt(" #n ")" ::: "memory")
; #define PG8_WAIT_L(n) asm volatile("s_waitcnt lgkmcnt(" #n ")" ::: "memory")
; #define PG8_BAR __builtin_amdgcn_s_barrier()
; #define PG8_SCHED __builtin_amdgcn_sched_barrier(0)
; template <class Epi, class Sched, bool ALIGN_EPI = true, bool SP2 = true>
; DI void gemm_phase(LAS unsigned char* lds, const Gemm g, const Sched& S, const Epi& E) {
;     ...
;             PG8_LDA(At, 1, 1); PG8_STAGE(PG8_SB(1, 0), b3, voffB); PG8_STAGE(PG8_SB(1, 1), b3 + hstepB, voffB); PG8_STAGE(PG8_SA(1, 0), a3, voffA);
;             PG8_WAIT_V(8); PG8_WAIT_L(0); PG8_BAR; PG8_MMA(1, 0, At, B0); PG8_MMA(1, 1, At, B1); PG8_BAR; PG8_SCHED;
;         }
;         if constexpr (ALIGN_EPI) { if (wr == 0) PG8_BAR; }
;         E(acc, cur, wr, wc, fr, fq);
;         if (!has_next) break;
	s_mov_b32 m0, s89
	v_lshl_add_u64 v[212:213], v[212:213], 0, s[16:17]
	ds_read_b128 v[180:183], v154 offset:49152
	ds_read_b128 v[184:187], v154 offset:50176
	ds_read_b128 v[188:191], v154 offset:51200
	ds_read_b128 v[192:195], v154 offset:52224
	ds_read_b128 v[196:199], v154 offset:53248
	ds_read_b128 v[200:203], v154 offset:54272
	ds_read_b128 v[204:207], v154 offset:55296
	ds_read_b128 v[208:211], v154 offset:56320
	global_load_lds_dwordx4 v[212:213], off
	v_lshl_add_u64 v[212:213], v[214:215], 0, s[16:17]
	s_mov_b32 m0, s88
	s_nop 0
	global_load_lds_dwordx4 v[212:213], off
	v_lshl_add_u64 v[212:213], s[60:61], 0, v[130:131]
	s_mov_b32 m0, s97
	s_nop 0
	global_load_lds_dwordx4 v[212:213], off
	v_lshl_add_u64 v[212:213], s[60:61], 0, v[134:135]
	s_mov_b32 m0, s96
	s_nop 0
	global_load_lds_dwordx4 v[212:213], off
	v_lshl_add_u64 v[212:213], v[216:217], 0, s[16:17]
	s_mov_b32 m0, s79
	s_nop 0
	global_load_lds_dwordx4 v[212:213], off
	v_lshl_add_u64 v[212:213], v[218:219], 0, s[16:17]
	s_mov_b32 m0, s81
	s_nop 0
	global_load_lds_dwordx4 v[212:213], off
	s_waitcnt vmcnt(8)
	s_waitcnt lgkmcnt(0)
	s_barrier
	s_waitcnt lgkmcnt(0)
	v_mfma_f32_16x16x32_bf16 v[60:63], v[140:143], v[180:183], v[60:63]
	v_mfma_f32_16x16x32_bf16 v[56:59], v[156:159], v[180:183], v[56:59]
	v_mfma_f32_16x16x32_bf16 v[44:47], v[140:143], v[188:191], v[44:47]
	v_mfma_f32_16x16x32_bf16 v[40:43], v[156:159], v[188:191], v[40:43]
	v_mfma_f32_16x16x32_bf16 v[28:31], v[140:143], v[196:199], v[28:31]
	v_mfma_f32_16x16x32_bf16 v[24:27], v[156:159], v[196:199], v[24:27]
	v_mfma_f32_16x16x32_bf16 v[12:15], v[140:143], v[204:207], v[12:15]
	v_mfma_f32_16x16x32_bf16 v[8:11], v[156:159], v[204:207], v[8:11]
	v_mfma_f32_16x16x32_bf16 v[60:63], v[144:147], v[184:187], v[60:63]
	v_mfma_f32_16x16x32_bf16 v[56:59], v[160:163], v[184:187], v[56:59]
	v_mfma_f32_16x16x32_bf16 v[44:47], v[144:147], v[192:195], v[44:47]
	v_mfma_f32_16x16x32_bf16 v[40:43], v[160:163], v[192:195], v[40:43]
	v_mfma_f32_16x16x32_bf16 v[28:31], v[144:147], v[200:203], v[28:31]
	v_mfma_f32_16x16x32_bf16 v[24:27], v[160:163], v[200:203], v[24:27]
	v_mfma_f32_16x16x32_bf16 v[12:15], v[144:147], v[208:211], v[12:15]
	v_mfma_f32_16x16x32_bf16 v[8:11], v[160:163], v[208:211], v[8:11]
	v_mfma_f32_16x16x32_bf16 v[52:55], v[164:167], v[180:183], v[52:55]
	v_mfma_f32_16x16x32_bf16 v[48:51], v[172:175], v[180:183], v[48:51]
	v_mfma_f32_16x16x32_bf16 v[36:39], v[164:167], v[188:191], v[36:39]
	v_mfma_f32_16x16x32_bf16 v[32:35], v[172:175], v[188:191], v[32:35]
	v_mfma_f32_16x16x32_bf16 v[20:23], v[164:167], v[196:199], v[20:23]
	v_mfma_f32_16x16x32_bf16 v[16:19], v[172:175], v[196:199], v[16:19]
	v_mfma_f32_16x16x32_bf16 v[4:7], v[164:167], v[204:207], v[4:7]
	v_mfma_f32_16x16x32_bf16 v[0:3], v[172:175], v[204:207], v[0:3]
	v_mfma_f32_16x16x32_bf16 v[52:55], v[168:171], v[184:187], v[52:55]
	v_mfma_f32_16x16x32_bf16 v[48:51], v[176:179], v[184:187], v[48:51]
	v_mfma_f32_16x16x32_bf16 v[36:39], v[168:171], v[192:195], v[36:39]
	v_mfma_f32_16x16x32_bf16 v[32:35], v[176:179], v[192:195], v[32:35]
	v_mfma_f32_16x16x32_bf16 v[20:23], v[168:171], v[200:203], v[20:23]
	v_mfma_f32_16x16x32_bf16 v[16:19], v[176:179], v[200:203], v[16:19]
	v_mfma_f32_16x16x32_bf16 v[4:7], v[168:171], v[208:211], v[4:7]
	v_mfma_f32_16x16x32_bf16 v[0:3], v[176:179], v[208:211], v[0:3]
	s_barrier
	s_andn2_b64 vcc, exec, s[58:59]
	s_mov_b64 s[60:61], -1
	s_mov_b64 s[58:59], 0
	s_mov_b64 s[62:63], 0x100
	s_cbranch_vccz .LBB0_1903
	s_and_b64 vcc, exec, s[18:19]
	s_cbranch_vccz .LBB0_1906
	s_barrier

;     DI size_t offA(const Unit& u) const { return (size_t)u.pm * tA + (size_t)u.pn * aPn; }
;     DI size_t offB(const Unit& u) const { return (size_t)u.pn * tB; }
; #define PG8_STAGE(bufoff, gbase, voff) do { _Pragma("unroll") for (int _i = 0; _i < 2; ++_i) \
;         __builtin_amdgcn_global_load_lds((const unsigned*)((const char*)(gbase) + (voff)[_i]), (LAS unsigned*)(lds + (bufoff) + ldsw + _i * 8192), 16, 0, 0); } while (0)
; #define PG8_LDA(dst, b, h) do { _Pragma("unroll") for (int m = 0; m < 4; ++m) _Pragma("unroll") for (int k = 0; k < 2; ++k) dst[m][k] = *(const LAS bf16x8*)(lds + PG8_SA(b, h) + aoff + m * 2048 + k * 1024); } while (0)
; #define PG8_LDB(dst, b, h) do { _Pragma("unroll") for (int n = 0; n < 2; ++n) _Pragma("unroll") for (int k = 0; k < 2; ++k) dst[n][k] = *(const LAS bf16x8*)(lds + PG8_SB(b, h) + boff + n * 2048 + k * 1024); } while (0)
; #define PG8_MMA(ai, bj, At, Bt) do { __builtin_amdgcn_s_setprio(1); _Pragma("unroll") for (int m = 0; m < 4; ++m) _Pragma("unroll") for (int n = 0; n < 2; ++n) _Pragma("unroll") for (int k = 0; k < 2; ++k) \
;         acc[ai][bj][m][n] = __builtin_amdgcn_mfma_f32_16x16x32_bf16(Bt[n][k], At[m][k], acc[ai][bj][m][n], 0, 0, 0); __builtin_amdgcn_s_setprio(0); } while (0)
; #define PG8_BAR __builtin_amdgcn_s_barrier()
; template <class Epi, class Sched, bool ALIGN_EPI = true, bool SP2 = true>
; DI void gemm_phase(LAS unsigned char* lds, const Gemm g, const Sched& S, const Epi& E) {
;     ...
;         const char* nA = has_next ? (const char*)g.A + S.offA(nxt) : cA; const char* nB = has_next ? (const char*)g.Bt + S.offB(nxt) : cB;
; #pragma unroll 1
;         for (int t = 0; t < nt; t += 2) {
;             const bool last = (t == nt - 2);
;             const char* a1 = cA + (size_t)(t + 1) * kstep;
;             const char* a2 = last ? nA : cA + (size_t)(t + 2) * kstep; const char* b2 = last ? nB : cB + (size_t)(t + 2) * kstep;
;             const char* a3 = a2 + kstep; const char* b3 = b2 + kstep;
;             PG8_LDB(B0, 0, 0); PG8_LDB(B1, 0, 1); PG8_SCHED; PG8_LDA(At, 0, 0); PG8_STAGE(PG8_SA(1, 1), a1 + hstepA, voffA);
;             PG8_WAIT_V(8); PG8_WAIT_L(0); PG8_BAR; PG8_MMA(0, 0, At, B0); PG8_MMA(0, 1, At, B1); PG8_BAR; PG8_SCHED;
;             PG8_LDA(At, 0, 1); PG8_STAGE(PG8_SB(0, 0), b2, voffB); PG8_STAGE(PG8_SB(0, 1), b2 + hstepB, voffB); PG8_STAGE(PG8_SA(0, 0), a2, voffA);
.LBB0_2015:
	v_add_u32_e32 v158, s59, v160
	ds_read_b128 v[174:177], v158
	ds_read_b128 v[178:181], v158 offset:1024
	ds_read_b128 v[182:185], v158 offset:2048
	ds_read_b128 v[186:189], v158 offset:3072
	v_add_u32_e32 v158, s60, v160
	ds_read_b128 v[190:193], v158
	ds_read_b128 v[194:197], v158 offset:1024
	ds_read_b128 v[198:201], v158 offset:2048
	ds_read_b128 v[202:205], v158 offset:3072
	s_add_u32 s46, s44, 0xfffe0080
	s_addc_u32 s47, s45, -1
	s_cmp_eq_u32 s80, 4
	s_cselect_b32 s49, s74, s47
	s_cselect_b32 s48, s75, s46
	s_cselect_b32 s47, s76, s79
	s_cselect_b32 s46, s77, s78
	s_mov_b32 m0, s63
	v_lshl_add_u64 v[158:159], s[44:45], 0, v[154:155]
	ds_read_b128 v[206:209], v169
	ds_read_b128 v[210:213], v169 offset:1024
	ds_read_b128 v[214:217], v169 offset:2048
	ds_read_b128 v[218:221], v169 offset:3072
	ds_read_b128 v[222:225], v169 offset:4096
	ds_read_b128 v[228:231], v169 offset:5120
	ds_read_b128 v[232:235], v169 offset:6144
	ds_read_b128 v[236:239], v169 offset:7168
	global_load_lds_dwordx4 v[158:159], off
	v_lshl_add_u64 v[158:159], s[44:45], 0, v[156:157]
	s_mov_b32 m0, s64
	s_nop 0
	global_load_lds_dwordx4 v[158:159], off
	s_waitcnt vmcnt(8)
	s_waitcnt lgkmcnt(0)
	s_barrier
	s_waitcnt lgkmcnt(0)
	v_mfma_f32_16x16x32_bf16 v[124:127], v[174:177], v[206:209], v[124:127]
	v_mfma_f32_16x16x32_bf16 v[120:123], v[182:185], v[206:209], v[120:123]
	v_mfma_f32_16x16x32_bf16 v[108:111], v[174:177], v[214:217], v[108:111]
	v_mfma_f32_16x16x32_bf16 v[104:107], v[182:185], v[214:217], v[104:107]
	v_mfma_f32_16x16x32_bf16 v[92:95], v[174:177], v[222:225], v[92:95]
	v_mfma_f32_16x16x32_bf16 v[88:91], v[182:185], v[222:225], v[88:91]
	v_mfma_f32_16x16x32_bf16 v[76:79], v[174:177], v[232:235], v[76:79]
	v_mfma_f32_16x16x32_bf16 v[72:75], v[182:185], v[232:235], v[72:75]
	v_mfma_f32_16x16x32_bf16 v[124:127], v[178:181], v[210:213], v[124:127]
	v_mfma_f32_16x16x32_bf16 v[120:123], v[186:189], v[210:213], v[120:123]
	v_mfma_f32_16x16x32_bf16 v[108:111], v[178:181], v[218:221], v[108:111]
	v_mfma_f32_16x16x32_bf16 v[104:107], v[186:189], v[218:221], v[104:107]
	v_mfma_f32_16x16x32_bf16 v[92:95], v[178:181], v[228:231], v[92:95]
	v_mfma_f32_16x16x32_bf16 v[88:91], v[186:189], v[228:231], v[88:91]
	v_mfma_f32_16x16x32_bf16 v[76:79], v[178:181], v[236:239], v[76:79]
	v_mfma_f32_16x16x32_bf16 v[72:75], v[186:189], v[236:239], v[72:75]
	v_mfma_f32_16x16x32_bf16 v[116:119], v[190:193], v[206:209], v[116:119]
	v_mfma_f32_16x16x32_bf16 v[112:115], v[198:201], v[206:209], v[112:115]
	v_mfma_f32_16x16x32_bf16 v[100:103], v[190:193], v[214:217], v[100:103]
	v_mfma_f32_16x16x32_bf16 v[96:99], v[198:201], v[214:217], v[96:99]
	v_mfma_f32_16x16x32_bf16 v[84:87], v[190:193], v[222:225], v[84:87]
	v_mfma_f32_16x16x32_bf16 v[80:83], v[198:201], v[222:225], v[80:83]
	v_mfma_f32_16x16x32_bf16 v[68:71], v[190:193], v[232:235], v[68:71]
	v_mfma_f32_16x16x32_bf16 v[64:67], v[198:201], v[232:235], v[64:67]
	v_mfma_f32_16x16x32_bf16 v[116:119], v[194:197], v[210:213], v[116:119]
	v_mfma_f32_16x16x32_bf16 v[112:115], v[202:205], v[210:213], v[112:115]
	v_mfma_f32_16x16x32_bf16 v[100:103], v[194:197], v[218:221], v[100:103]
	v_mfma_f32_16x16x32_bf16 v[96:99], v[202:205], v[218:221], v[96:99]
	v_mfma_f32_16x16x32_bf16 v[84:87], v[194:197], v[228:231], v[84:87]
	v_mfma_f32_16x16x32_bf16 v[80:83], v[202:205], v[228:231], v[80:83]
	v_mfma_f32_16x16x32_bf16 v[68:71], v[194:197], v[236:239], v[68:71]
	v_mfma_f32_16x16x32_bf16 v[64:67], v[202:205], v[236:239], v[64:67]
	s_barrier
	s_mov_b32 m0, s65
	v_lshl_add_u64 v[158:159], s[46:47], 0, v[132:133]
	s_add_u32 s82, s46, 0x20000
	ds_read_b128 v[206:209], v169 offset:16384
	ds_read_b128 v[210:213], v169 offset:17408
	ds_read_b128 v[214:217], v169 offset:18432
	ds_read_b128 v[218:221], v169 offset:19456
	ds_read_b128 v[222:225], v169 offset:20480
	ds_read_b128 v[228:231], v169 offset:21504
	ds_read_b128 v[232:235], v169 offset:22528
	ds_read_b128 v[236:239], v169 offset:23552
	global_load_lds_dwordx4 v[158:159], off
	v_lshl_add_u64 v[240:241], s[46:47], 0, v[128:129]
	s_mov_b32 m0, s66
	s_addc_u32 s83, s47, 0
	global_load_lds_dwordx4 v[240:241], off
	v_lshl_add_u64 v[242:243], s[82:83], 0, v[132:133]
	s_mov_b32 m0, s67
	v_lshl_add_u64 v[244:245], s[48:49], 0, v[130:131]
	global_load_lds_dwordx4 v[242:243], off
	v_lshl_add_u64 v[242:243], s[82:83], 0, v[128:129]
	s_mov_b32 m0, s68
	s_nop 0
	global_load_lds_dwordx4 v[242:243], off
	v_lshl_add_u64 v[242:243], s[48:49], 0, v[134:135]
	s_mov_b32 m0, s3
	s_nop 0
	global_load_lds_dwordx4 v[242:243], off
	s_mov_b32 m0, s53
	s_nop 0
	global_load_lds_dwordx4 v[244:245], off
	s_waitcnt vmcnt(8)
	s_waitcnt lgkmcnt(0)
	s_barrier
; #define PG8_STAGE(bufoff, gbase, voff) do { _Pragma("unroll") for (int _i = 0; _i < 2; ++_i) \
;         __builtin_amdgcn_global_load_lds((const unsigned*)((const char*)(gbase) + (voff)[_i]), (LAS unsigned*)(lds + (bufoff) + ldsw + _i * 8192), 16, 0, 0); } while (0)
; #define PG8_LDA(dst, b, h) do { _Pragma("unroll") for (int m = 0; m < 4; ++m) _Pragma("unroll") for (int k = 0; k < 2; ++k) dst[m][k] = *(const LAS bf16x8*)(lds + PG8_SA(b, h) + aoff + m * 2048 + k * 1024); } while (0)
; #define PG8_LDB(dst, b, h) do { _Pragma("unroll") for (int n = 0; n < 2; ++n) _Pragma("unroll") for (int k = 0; k < 2; ++k) dst[n][k] = *(const LAS bf16x8*)(lds + PG8_SB(b, h) + boff + n * 2048 + k * 1024); } while (0)
; #define PG8_MMA(ai, bj, At, Bt) do { __builtin_amdgcn_s_setprio(1); _Pragma("unroll") for (int m = 0; m < 4; ++m) _Pragma("unroll") for (int n = 0; n < 2; ++n) _Pragma("unroll") for (int k = 0; k < 2; ++k) \
;         acc[ai][bj][m][n] = __builtin_amdgcn_mfma_f32_16x16x32_bf16(Bt[n][k], At[m][k], acc[ai][bj][m][n], 0, 0, 0); __builtin_amdgcn_s_setprio(0); } while (0)
; #define PG8_WAIT_V(n) asm volatile("s_waitcnt vmcnt(" #n ")" ::: "memory")
; #define PG8_WAIT_L(n) asm volatile("s_waitcnt lgkmcnt(" #n ")" ::: "memory")
; #define PG8_BAR __builtin_amdgcn_s_barrier()
; #define PG8_SCHED __builtin_amdgcn_sched_barrier(0)
; template <class Epi, class Sched, bool ALIGN_EPI = true, bool SP2 = true>
; DI void gemm_phase(LAS unsigned char* lds, const Gemm g, const Sched& S, const Epi& E) {
;     ...
;             PG8_WAIT_V(8); PG8_WAIT_L(0); PG8_BAR; PG8_MMA(1, 0, At, B0); PG8_MMA(1, 1, At, B1); PG8_BAR; PG8_SCHED;
;             PG8_LDB(B0, 1, 0); PG8_LDB(B1, 1, 1); PG8_SCHED; PG8_LDA(At, 1, 0); PG8_STAGE(PG8_SA(0, 1), a2 + hstepA, voffA);
;             PG8_WAIT_V(8); PG8_WAIT_L(0); PG8_BAR; PG8_MMA(0, 0, At, B0); PG8_MMA(0, 1, At, B1); PG8_BAR; PG8_SCHED;
	s_waitcnt lgkmcnt(0)
	v_mfma_f32_16x16x32_bf16 v[60:63], v[174:177], v[206:209], v[60:63]
	v_mfma_f32_16x16x32_bf16 v[56:59], v[182:185], v[206:209], v[56:59]
	v_mfma_f32_16x16x32_bf16 v[44:47], v[174:177], v[214:217], v[44:47]
	v_mfma_f32_16x16x32_bf16 v[40:43], v[182:185], v[214:217], v[40:43]
	v_mfma_f32_16x16x32_bf16 v[28:31], v[174:177], v[222:225], v[28:31]
	v_mfma_f32_16x16x32_bf16 v[24:27], v[182:185], v[222:225], v[24:27]
	v_mfma_f32_16x16x32_bf16 v[12:15], v[174:177], v[232:235], v[12:15]
	v_mfma_f32_16x16x32_bf16 v[8:11], v[182:185], v[232:235], v[8:11]
	v_mfma_f32_16x16x32_bf16 v[60:63], v[178:181], v[210:213], v[60:63]
	v_mfma_f32_16x16x32_bf16 v[56:59], v[186:189], v[210:213], v[56:59]
	v_mfma_f32_16x16x32_bf16 v[44:47], v[178:181], v[218:221], v[44:47]
	v_mfma_f32_16x16x32_bf16 v[40:43], v[186:189], v[218:221], v[40:43]
	v_mfma_f32_16x16x32_bf16 v[28:31], v[178:181], v[228:231], v[28:31]
	v_mfma_f32_16x16x32_bf16 v[24:27], v[186:189], v[228:231], v[24:27]
	v_mfma_f32_16x16x32_bf16 v[12:15], v[178:181], v[236:239], v[12:15]
	v_mfma_f32_16x16x32_bf16 v[8:11], v[186:189], v[236:239], v[8:11]
	v_mfma_f32_16x16x32_bf16 v[52:55], v[190:193], v[206:209], v[52:55]
	v_mfma_f32_16x16x32_bf16 v[48:51], v[198:201], v[206:209], v[48:51]
	v_mfma_f32_16x16x32_bf16 v[36:39], v[190:193], v[214:217], v[36:39]
	v_mfma_f32_16x16x32_bf16 v[32:35], v[198:201], v[214:217], v[32:35]
	v_mfma_f32_16x16x32_bf16 v[20:23], v[190:193], v[222:225], v[20:23]
	v_mfma_f32_16x16x32_bf16 v[16:19], v[198:201], v[222:225], v[16:19]
	v_mfma_f32_16x16x32_bf16 v[4:7], v[190:193], v[232:235], v[4:7]
	v_mfma_f32_16x16x32_bf16 v[0:3], v[198:201], v[232:235], v[0:3]
	v_mfma_f32_16x16x32_bf16 v[52:55], v[194:197], v[210:213], v[52:55]
	v_mfma_f32_16x16x32_bf16 v[48:51], v[202:205], v[210:213], v[48:51]
	v_mfma_f32_16x16x32_bf16 v[36:39], v[194:197], v[218:221], v[36:39]
	v_mfma_f32_16x16x32_bf16 v[32:35], v[202:205], v[218:221], v[32:35]
	v_mfma_f32_16x16x32_bf16 v[20:23], v[194:197], v[228:231], v[20:23]
	v_mfma_f32_16x16x32_bf16 v[16:19], v[202:205], v[228:231], v[16:19]
	v_mfma_f32_16x16x32_bf16 v[4:7], v[194:197], v[236:239], v[4:7]
	v_mfma_f32_16x16x32_bf16 v[0:3], v[202:205], v[236:239], v[0:3]
	s_barrier
	v_add_u32_e32 v173, s69, v160
	ds_read_b128 v[174:177], v173
	ds_read_b128 v[178:181], v173 offset:1024
	ds_read_b128 v[182:185], v173 offset:2048
	ds_read_b128 v[186:189], v173 offset:3072
	v_add_u32_e32 v173, s70, v160
	ds_read_b128 v[190:193], v173
	ds_read_b128 v[194:197], v173 offset:1024
	ds_read_b128 v[198:201], v173 offset:2048
	ds_read_b128 v[202:205], v173 offset:3072
	s_add_u32 s48, s48, 0x20000
	s_addc_u32 s49, s49, 0
	s_mov_b32 m0, s54
	v_lshl_add_u64 v[246:247], s[48:49], 0, v[134:135]
	ds_read_b128 v[206:209], v169 offset:32768
	ds_read_b128 v[210:213], v169 offset:33792
	ds_read_b128 v[214:217], v169 offset:34816
	ds_read_b128 v[218:221], v169 offset:35840
	ds_read_b128 v[222:225], v169 offset:36864
	ds_read_b128 v[228:231], v169 offset:37888
	ds_read_b128 v[232:235], v169 offset:38912
	ds_read_b128 v[236:239], v169 offset:39936
	global_load_lds_dwordx4 v[246:247], off
	v_lshl_add_u64 v[246:247], s[48:49], 0, v[130:131]
	s_mov_b32 m0, s55
	s_nop 0
	global_load_lds_dwordx4 v[246:247], off
	s_waitcnt vmcnt(8)
	s_waitcnt lgkmcnt(0)
	s_barrier
	s_waitcnt lgkmcnt(0)
	v_mfma_f32_16x16x32_bf16 v[124:127], v[174:177], v[206:209], v[124:127]
	v_mfma_f32_16x16x32_bf16 v[120:123], v[182:185], v[206:209], v[120:123]
	v_mfma_f32_16x16x32_bf16 v[108:111], v[174:177], v[214:217], v[108:111]
	v_mfma_f32_16x16x32_bf16 v[104:107], v[182:185], v[214:217], v[104:107]
	v_mfma_f32_16x16x32_bf16 v[92:95], v[174:177], v[222:225], v[92:95]
	v_mfma_f32_16x16x32_bf16 v[88:91], v[182:185], v[222:225], v[88:91]
	v_mfma_f32_16x16x32_bf16 v[76:79], v[174:177], v[232:235], v[76:79]
	v_mfma_f32_16x16x32_bf16 v[72:75], v[182:185], v[232:235], v[72:75]
	v_mfma_f32_16x16x32_bf16 v[124:127], v[178:181], v[210:213], v[124:127]
	v_mfma_f32_16x16x32_bf16 v[120:123], v[186:189], v[210:213], v[120:123]
	v_mfma_f32_16x16x32_bf16 v[108:111], v[178:181], v[218:221], v[108:111]
	v_mfma_f32_16x16x32_bf16 v[104:107], v[186:189], v[218:221], v[104:107]
	v_mfma_f32_16x16x32_bf16 v[92:95], v[178:181], v[228:231], v[92:95]
	v_mfma_f32_16x16x32_bf16 v[88:91], v[186:189], v[228:231], v[88:91]
	v_mfma_f32_16x16x32_bf16 v[76:79], v[178:181], v[236:239], v[76:79]
	v_mfma_f32_16x16x32_bf16 v[72:75], v[186:189], v[236:239], v[72:75]
	v_mfma_f32_16x16x32_bf16 v[116:119], v[190:193], v[206:209], v[116:119]
	v_mfma_f32_16x16x32_bf16 v[112:115], v[198:201], v[206:209], v[112:115]
	v_mfma_f32_16x16x32_bf16 v[100:103], v[190:193], v[214:217], v[100:103]
	v_mfma_f32_16x16x32_bf16 v[96:99], v[198:201], v[214:217], v[96:99]
	v_mfma_f32_16x16x32_bf16 v[84:87], v[190:193], v[222:225], v[84:87]
	v_mfma_f32_16x16x32_bf16 v[80:83], v[198:201], v[222:225], v[80:83]
	v_mfma_f32_16x16x32_bf16 v[68:71], v[190:193], v[232:235], v[68:71]
	v_mfma_f32_16x16x32_bf16 v[64:67], v[198:201], v[232:235], v[64:67]
	v_mfma_f32_16x16x32_bf16 v[116:119], v[194:197], v[210:213], v[116:119]
	v_mfma_f32_16x16x32_bf16 v[112:115], v[202:205], v[210:213], v[112:115]
	v_mfma_f32_16x16x32_bf16 v[100:103], v[194:197], v[218:221], v[100:103]
	v_mfma_f32_16x16x32_bf16 v[96:99], v[202:205], v[218:221], v[96:99]
	v_mfma_f32_16x16x32_bf16 v[84:87], v[194:197], v[228:231], v[84:87]
	v_mfma_f32_16x16x32_bf16 v[80:83], v[202:205], v[228:231], v[80:83]
	v_mfma_f32_16x16x32_bf16 v[68:71], v[194:197], v[236:239], v[68:71]
	v_mfma_f32_16x16x32_bf16 v[64:67], v[202:205], v[236:239], v[64:67]
	s_barrier
; #define PG8_STAGE(bufoff, gbase, voff) do { _Pragma("unroll") for (int _i = 0; _i < 2; ++_i) \
;         __builtin_amdgcn_global_load_lds((const unsigned*)((const char*)(gbase) + (voff)[_i]), (LAS unsigned*)(lds + (bufoff) + ldsw + _i * 8192), 16, 0, 0); } while (0)
; #define PG8_LDA(dst, b, h) do { _Pragma("unroll") for (int m = 0; m < 4; ++m) _Pragma("unroll") for (int k = 0; k < 2; ++k) dst[m][k] = *(const LAS bf16x8*)(lds + PG8_SA(b, h) + aoff + m * 2048 + k * 1024); } while (0)
; #define PG8_MMA(ai, bj, At, Bt) do { __builtin_amdgcn_s_setprio(1); _Pragma("unroll") for (int m = 0; m < 4; ++m) _Pragma("unroll") for (int n = 0; n < 2; ++n) _Pragma("unroll") for (int k = 0; k < 2; ++k) \
;         acc[ai][bj][m][n] = __builtin_amdgcn_mfma_f32_16x16x32_bf16(Bt[n][k], At[m][k], acc[ai][bj][m][n], 0, 0, 0); __builtin_amdgcn_s_setprio(0); } while (0)
; #define PG8_WAIT_V(n) asm volatile("s_waitcnt vmcnt(" #n ")" ::: "memory")
; #define PG8_WAIT_L(n) asm volatile("s_waitcnt lgkmcnt(" #n ")" ::: "memory")
; #define PG8_BAR __builtin_amdgcn_s_barrier()
; #define PG8_SCHED __builtin_amdgcn_sched_barrier(0)
; template <class Epi, class Sched, bool ALIGN_EPI = true, bool SP2 = true>
; DI void gemm_phase(LAS unsigned char* lds, const Gemm g, const Sched& S, const Epi& E) {
;     ...
;             PG8_LDA(At, 1, 1); PG8_STAGE(PG8_SB(1, 0), b3, voffB); PG8_STAGE(PG8_SB(1, 1), b3 + hstepB, voffB); PG8_STAGE(PG8_SA(1, 0), a3, voffA);
;             PG8_WAIT_V(8); PG8_WAIT_L(0); PG8_BAR; PG8_MMA(1, 0, At, B0); PG8_MMA(1, 1, At, B1); PG8_BAR; PG8_SCHED;
;         }
	s_mov_b32 m0, s71
	v_lshl_add_u64 v[158:159], v[158:159], 0, s[16:17]
	ds_read_b128 v[206:209], v169 offset:49152
	ds_read_b128 v[210:213], v169 offset:50176
	ds_read_b128 v[214:217], v169 offset:51200
	ds_read_b128 v[218:221], v169 offset:52224
	ds_read_b128 v[222:225], v169 offset:53248
	ds_read_b128 v[228:231], v169 offset:54272
	ds_read_b128 v[232:235], v169 offset:55296
	ds_read_b128 v[236:239], v169 offset:56320
	global_load_lds_dwordx4 v[158:159], off
	s_add_i32 m0, s71, 0x2000
	s_add_u32 s46, s46, 0x20080
	v_lshl_add_u64 v[158:159], v[240:241], 0, s[16:17]
	s_addc_u32 s47, s47, 0
	s_add_i32 s48, s70, s52
	global_load_lds_dwordx4 v[158:159], off
	v_lshl_add_u64 v[158:159], s[46:47], 0, v[132:133]
	s_mov_b32 m0, s48
	s_nop 0
	global_load_lds_dwordx4 v[158:159], off
	v_lshl_add_u64 v[158:159], s[46:47], 0, v[128:129]
	s_add_i32 m0, s48, 0x2000
	s_nop 0
	global_load_lds_dwordx4 v[158:159], off
	v_lshl_add_u64 v[158:159], v[242:243], 0, s[16:17]
	s_mov_b32 m0, s57
	s_nop 0
	global_load_lds_dwordx4 v[158:159], off
	v_lshl_add_u64 v[158:159], v[244:245], 0, s[16:17]
	s_mov_b32 m0, s58
	s_nop 0
	global_load_lds_dwordx4 v[158:159], off
	s_waitcnt vmcnt(8)
	s_waitcnt lgkmcnt(0)
	s_barrier
	s_waitcnt lgkmcnt(0)
	v_mfma_f32_16x16x32_bf16 v[60:63], v[174:177], v[206:209], v[60:63]
	v_mfma_f32_16x16x32_bf16 v[56:59], v[182:185], v[206:209], v[56:59]
	v_mfma_f32_16x16x32_bf16 v[44:47], v[174:177], v[214:217], v[44:47]
	v_mfma_f32_16x16x32_bf16 v[40:43], v[182:185], v[214:217], v[40:43]
	v_mfma_f32_16x16x32_bf16 v[28:31], v[174:177], v[222:225], v[28:31]
	v_mfma_f32_16x16x32_bf16 v[24:27], v[182:185], v[222:225], v[24:27]
	v_mfma_f32_16x16x32_bf16 v[12:15], v[174:177], v[232:235], v[12:15]
	v_mfma_f32_16x16x32_bf16 v[8:11], v[182:185], v[232:235], v[8:11]
	v_mfma_f32_16x16x32_bf16 v[60:63], v[178:181], v[210:213], v[60:63]
	v_mfma_f32_16x16x32_bf16 v[56:59], v[186:189], v[210:213], v[56:59]
	v_mfma_f32_16x16x32_bf16 v[44:47], v[178:181], v[218:221], v[44:47]
	v_mfma_f32_16x16x32_bf16 v[40:43], v[186:189], v[218:221], v[40:43]
	v_mfma_f32_16x16x32_bf16 v[28:31], v[178:181], v[228:231], v[28:31]
	v_mfma_f32_16x16x32_bf16 v[24:27], v[186:189], v[228:231], v[24:27]
	v_mfma_f32_16x16x32_bf16 v[12:15], v[178:181], v[236:239], v[12:15]
	v_mfma_f32_16x16x32_bf16 v[8:11], v[186:189], v[236:239], v[8:11]
	v_mfma_f32_16x16x32_bf16 v[52:55], v[190:193], v[206:209], v[52:55]
	v_mfma_f32_16x16x32_bf16 v[48:51], v[198:201], v[206:209], v[48:51]
	v_mfma_f32_16x16x32_bf16 v[36:39], v[190:193], v[214:217], v[36:39]
	v_mfma_f32_16x16x32_bf16 v[32:35], v[198:201], v[214:217], v[32:35]
	v_mfma_f32_16x16x32_bf16 v[20:23], v[190:193], v[222:225], v[20:23]
	v_mfma_f32_16x16x32_bf16 v[16:19], v[198:201], v[222:225], v[16:19]
	v_mfma_f32_16x16x32_bf16 v[4:7], v[190:193], v[232:235], v[4:7]
	v_mfma_f32_16x16x32_bf16 v[0:3], v[198:201], v[232:235], v[0:3]
	v_mfma_f32_16x16x32_bf16 v[52:55], v[194:197], v[210:213], v[52:55]
	v_mfma_f32_16x16x32_bf16 v[48:51], v[202:205], v[210:213], v[48:51]
	v_mfma_f32_16x16x32_bf16 v[36:39], v[194:197], v[218:221], v[36:39]
	v_mfma_f32_16x16x32_bf16 v[32:35], v[202:205], v[218:221], v[32:35]
	v_mfma_f32_16x16x32_bf16 v[20:23], v[194:197], v[228:231], v[20:23]
	v_mfma_f32_16x16x32_bf16 v[16:19], v[202:205], v[228:231], v[16:19]
	v_mfma_f32_16x16x32_bf16 v[4:7], v[194:197], v[236:239], v[4:7]
	v_mfma_f32_16x16x32_bf16 v[0:3], v[202:205], v[236:239], v[0:3]
	s_barrier
	s_add_i32 s80, s80, 2
	s_add_u32 s44, s44, 0x100
	s_addc_u32 s45, s45, 0
	s_add_u32 s78, s78, 0x100
	s_addc_u32 s79, s79, 0
	s_cmp_gt_u32 s80, 5
	s_cbranch_scc0 .LBB0_2015
	s_and_b64 vcc, exec, s[18:19]
	s_cbranch_vccz .LBB0_2018
	s_barrier

;     DI size_t offA(const Unit& u) const { return (size_t)u.pm * tA + (size_t)u.pn * aPn; }
;     DI size_t offB(const Unit& u) const { return (size_t)u.pn * tB; }
; #define PG8_STAGE(bufoff, gbase, voff) do { _Pragma("unroll") for (int _i = 0; _i < 2; ++_i) \
;         __builtin_amdgcn_global_load_lds((const unsigned*)((const char*)(gbase) + (voff)[_i]), (LAS unsigned*)(lds + (bufoff) + ldsw + _i * 8192), 16, 0, 0); } while (0)
; #define PG8_LDA(dst, b, h) do { _Pragma("unroll") for (int m = 0; m < 4; ++m) _Pragma("unroll") for (int k = 0; k < 2; ++k) dst[m][k] = *(const LAS bf16x8*)(lds + PG8_SA(b, h) + aoff + m * 2048 + k * 1024); } while (0)
; #define PG8_LDB(dst, b, h) do { _Pragma("unroll") for (int n = 0; n < 2; ++n) _Pragma("unroll") for (int k = 0; k < 2; ++k) dst[n][k] = *(const LAS bf16x8*)(lds + PG8_SB(b, h) + boff + n * 2048 + k * 1024); } while (0)
; #define PG8_MMA(ai, bj, At, Bt) do { __builtin_amdgcn_s_setprio(1); _Pragma("unroll") for (int m = 0; m < 4; ++m) _Pragma("unroll") for (int n = 0; n < 2; ++n) _Pragma("unroll") for (int k = 0; k < 2; ++k) \
;         acc[ai][bj][m][n] = __builtin_amdgcn_mfma_f32_16x16x32_bf16(Bt[n][k], At[m][k], acc[ai][bj][m][n], 0, 0, 0); __builtin_amdgcn_s_setprio(0); } while (0)
; #define PG8_BAR __builtin_amdgcn_s_barrier()
; template <class Epi, class Sched, bool ALIGN_EPI = true, bool SP2 = true>
; DI void gemm_phase(LAS unsigned char* lds, const Gemm g, const Sched& S, const Epi& E) {
;     ...
;         const char* nA = has_next ? (const char*)g.A + S.offA(nxt) : cA; const char* nB = has_next ? (const char*)g.Bt + S.offB(nxt) : cB;
; #pragma unroll 1
;         for (int t = 0; t < nt; t += 2) {
;             const bool last = (t == nt - 2);
;             const char* a1 = cA + (size_t)(t + 1) * kstep;
;             const char* a2 = last ? nA : cA + (size_t)(t + 2) * kstep; const char* b2 = last ? nB : cB + (size_t)(t + 2) * kstep;
;             const char* a3 = a2 + kstep; const char* b3 = b2 + kstep;
;             PG8_LDB(B0, 0, 0); PG8_LDB(B1, 0, 1); PG8_SCHED; PG8_LDA(At, 0, 0); PG8_STAGE(PG8_SA(1, 1), a1 + hstepA, voffA);
;             PG8_WAIT_V(8); PG8_WAIT_L(0); PG8_BAR; PG8_MMA(0, 0, At, B0); PG8_MMA(0, 1, At, B1); PG8_BAR; PG8_SCHED;
;             PG8_LDA(At, 0, 1); PG8_STAGE(PG8_SB(0, 0), b2, voffB); PG8_STAGE(PG8_SB(0, 1), b2 + hstepB, voffB); PG8_STAGE(PG8_SA(0, 0), a2, voffA);
.LBB0_2108:
	ds_read_b128 v[140:143], v157
	ds_read_b128 v[144:147], v157 offset:1024
	ds_read_b128 v[148:151], v157 offset:2048
	ds_read_b128 v[160:163], v157 offset:3072
	ds_read_b128 v[164:167], v158
	ds_read_b128 v[168:171], v158 offset:1024
	ds_read_b128 v[172:175], v158 offset:2048
	ds_read_b128 v[176:179], v158 offset:3072
	s_add_u32 s52, s48, 0xfff80080
	s_addc_u32 s53, s49, -1
	s_cmp_eq_u32 s78, 28
	s_cselect_b32 s55, s41, s53
	s_cselect_b32 s54, s74, s52
	s_cselect_b32 s53, s39, s77
	s_cselect_b32 s52, s75, s76
	v_lshl_add_u64 v[152:153], s[48:49], 0, v[132:133]
	s_add_i32 m0, s59, 0xc000
	ds_read_b128 v[180:183], v159
	ds_read_b128 v[184:187], v159 offset:1024
	ds_read_b128 v[188:191], v159 offset:2048
	ds_read_b128 v[192:195], v159 offset:3072
	ds_read_b128 v[196:199], v159 offset:4096
	ds_read_b128 v[200:203], v159 offset:5120
	ds_read_b128 v[204:207], v159 offset:6144
	ds_read_b128 v[208:211], v159 offset:7168
	global_load_lds_dwordx4 v[152:153], off
	v_lshl_add_u64 v[152:153], s[48:49], 0, v[134:135]
	s_add_i32 m0, s59, 0xe000
	s_nop 0
	global_load_lds_dwordx4 v[152:153], off
	s_waitcnt vmcnt(8)
	s_waitcnt lgkmcnt(0)
	s_barrier
	s_waitcnt lgkmcnt(0)
	v_mfma_f32_16x16x32_bf16 v[124:127], v[140:143], v[180:183], v[124:127]
	v_mfma_f32_16x16x32_bf16 v[120:123], v[148:151], v[180:183], v[120:123]
	v_mfma_f32_16x16x32_bf16 v[108:111], v[140:143], v[188:191], v[108:111]
	v_mfma_f32_16x16x32_bf16 v[104:107], v[148:151], v[188:191], v[104:107]
	v_mfma_f32_16x16x32_bf16 v[92:95], v[140:143], v[196:199], v[92:95]
	v_mfma_f32_16x16x32_bf16 v[88:91], v[148:151], v[196:199], v[88:91]
	v_mfma_f32_16x16x32_bf16 v[76:79], v[140:143], v[204:207], v[76:79]
	v_mfma_f32_16x16x32_bf16 v[72:75], v[148:151], v[204:207], v[72:75]
	v_mfma_f32_16x16x32_bf16 v[124:127], v[144:147], v[184:187], v[124:127]
	v_mfma_f32_16x16x32_bf16 v[120:123], v[160:163], v[184:187], v[120:123]
	v_mfma_f32_16x16x32_bf16 v[108:111], v[144:147], v[192:195], v[108:111]
	v_mfma_f32_16x16x32_bf16 v[104:107], v[160:163], v[192:195], v[104:107]
	v_mfma_f32_16x16x32_bf16 v[92:95], v[144:147], v[200:203], v[92:95]
	v_mfma_f32_16x16x32_bf16 v[88:91], v[160:163], v[200:203], v[88:91]
	v_mfma_f32_16x16x32_bf16 v[76:79], v[144:147], v[208:211], v[76:79]
	v_mfma_f32_16x16x32_bf16 v[72:75], v[160:163], v[208:211], v[72:75]
	v_mfma_f32_16x16x32_bf16 v[116:119], v[164:167], v[180:183], v[116:119]
	v_mfma_f32_16x16x32_bf16 v[112:115], v[172:175], v[180:183], v[112:115]
	v_mfma_f32_16x16x32_bf16 v[100:103], v[164:167], v[188:191], v[100:103]
	v_mfma_f32_16x16x32_bf16 v[96:99], v[172:175], v[188:191], v[96:99]
	v_mfma_f32_16x16x32_bf16 v[84:87], v[164:167], v[196:199], v[84:87]
	v_mfma_f32_16x16x32_bf16 v[80:83], v[172:175], v[196:199], v[80:83]
	v_mfma_f32_16x16x32_bf16 v[68:71], v[164:167], v[204:207], v[68:71]
	v_mfma_f32_16x16x32_bf16 v[64:67], v[172:175], v[204:207], v[64:67]
	v_mfma_f32_16x16x32_bf16 v[116:119], v[168:171], v[184:187], v[116:119]
	v_mfma_f32_16x16x32_bf16 v[112:115], v[176:179], v[184:187], v[112:115]
	v_mfma_f32_16x16x32_bf16 v[100:103], v[168:171], v[192:195], v[100:103]
	v_mfma_f32_16x16x32_bf16 v[96:99], v[176:179], v[192:195], v[96:99]
	v_mfma_f32_16x16x32_bf16 v[84:87], v[168:171], v[200:203], v[84:87]
	v_mfma_f32_16x16x32_bf16 v[80:83], v[176:179], v[200:203], v[80:83]
	v_mfma_f32_16x16x32_bf16 v[68:71], v[168:171], v[208:211], v[68:71]
	v_mfma_f32_16x16x32_bf16 v[64:67], v[176:179], v[208:211], v[64:67]
	s_barrier
	s_add_i32 s79, s69, s58
	v_lshl_add_u64 v[152:153], s[52:53], 0, v[128:129]
	s_mov_b32 m0, s79
	ds_read_b128 v[180:183], v159 offset:16384
	ds_read_b128 v[184:187], v159 offset:17408
	ds_read_b128 v[188:191], v159 offset:18432
	ds_read_b128 v[192:195], v159 offset:19456
	ds_read_b128 v[196:199], v159 offset:20480
	ds_read_b128 v[200:203], v159 offset:21504
	ds_read_b128 v[204:207], v159 offset:22528
	ds_read_b128 v[208:211], v159 offset:23552
	global_load_lds_dwordx4 v[152:153], off
	s_add_i32 m0, s79, 0x2000
	s_add_u32 s80, s52, 0x80000
	v_lshl_add_u64 v[212:213], s[52:53], 0, v[130:131]
	s_addc_u32 s81, s53, 0
	s_add_i32 s79, s70, s58
	global_load_lds_dwordx4 v[212:213], off
	v_lshl_add_u64 v[214:215], s[80:81], 0, v[128:129]
	s_mov_b32 m0, s79
	v_lshl_add_u64 v[216:217], s[54:55], 0, v[130:131]
	global_load_lds_dwordx4 v[214:215], off
	v_lshl_add_u64 v[214:215], s[80:81], 0, v[130:131]
	s_add_i32 m0, s79, 0x2000
	s_nop 0
	global_load_lds_dwordx4 v[214:215], off
	v_lshl_add_u64 v[214:215], s[54:55], 0, v[128:129]
	s_mov_b32 m0, s59
	s_nop 0
	global_load_lds_dwordx4 v[214:215], off
	s_mov_b32 m0, s60
	s_nop 0
	global_load_lds_dwordx4 v[216:217], off
	s_waitcnt vmcnt(8)
	s_waitcnt lgkmcnt(0)
	s_barrier
; #define PG8_STAGE(bufoff, gbase, voff) do { _Pragma("unroll") for (int _i = 0; _i < 2; ++_i) \
;         __builtin_amdgcn_global_load_lds((const unsigned*)((const char*)(gbase) + (voff)[_i]), (LAS unsigned*)(lds + (bufoff) + ldsw + _i * 8192), 16, 0, 0); } while (0)
; #define PG8_LDA(dst, b, h) do { _Pragma("unroll") for (int m = 0; m < 4; ++m) _Pragma("unroll") for (int k = 0; k < 2; ++k) dst[m][k] = *(const LAS bf16x8*)(lds + PG8_SA(b, h) + aoff + m * 2048 + k * 1024); } while (0)
; #define PG8_LDB(dst, b, h) do { _Pragma("unroll") for (int n = 0; n < 2; ++n) _Pragma("unroll") for (int k = 0; k < 2; ++k) dst[n][k] = *(const LAS bf16x8*)(lds + PG8_SB(b, h) + boff + n * 2048 + k * 1024); } while (0)
; #define PG8_MMA(ai, bj, At, Bt) do { __builtin_amdgcn_s_setprio(1); _Pragma("unroll") for (int m = 0; m < 4; ++m) _Pragma("unroll") for (int n = 0; n < 2; ++n) _Pragma("unroll") for (int k = 0; k < 2; ++k) \
;         acc[ai][bj][m][n] = __builtin_amdgcn_mfma_f32_16x16x32_bf16(Bt[n][k], At[m][k], acc[ai][bj][m][n], 0, 0, 0); __builtin_amdgcn_s_setprio(0); } while (0)
; #define PG8_WAIT_V(n) asm volatile("s_waitcnt vmcnt(" #n ")" ::: "memory")
; #define PG8_WAIT_L(n) asm volatile("s_waitcnt lgkmcnt(" #n ")" ::: "memory")
; #define PG8_BAR __builtin_amdgcn_s_barrier()
; #define PG8_SCHED __builtin_amdgcn_sched_barrier(0)
; template <class Epi, class Sched, bool ALIGN_EPI = true, bool SP2 = true>
; DI void gemm_phase(LAS unsigned char* lds, const Gemm g, const Sched& S, const Epi& E) {
;     ...
;             PG8_WAIT_V(8); PG8_WAIT_L(0); PG8_BAR; PG8_MMA(1, 0, At, B0); PG8_MMA(1, 1, At, B1); PG8_BAR; PG8_SCHED;
;             PG8_LDB(B0, 1, 0); PG8_LDB(B1, 1, 1); PG8_SCHED; PG8_LDA(At, 1, 0); PG8_STAGE(PG8_SA(0, 1), a2 + hstepA, voffA);
;             PG8_WAIT_V(8); PG8_WAIT_L(0); PG8_BAR; PG8_MMA(0, 0, At, B0); PG8_MMA(0, 1, At, B1); PG8_BAR; PG8_SCHED;
	s_waitcnt lgkmcnt(0)
	v_mfma_f32_16x16x32_bf16 v[60:63], v[140:143], v[180:183], v[60:63]
	v_mfma_f32_16x16x32_bf16 v[56:59], v[148:151], v[180:183], v[56:59]
	v_mfma_f32_16x16x32_bf16 v[44:47], v[140:143], v[188:191], v[44:47]
	v_mfma_f32_16x16x32_bf16 v[40:43], v[148:151], v[188:191], v[40:43]
	v_mfma_f32_16x16x32_bf16 v[28:31], v[140:143], v[196:199], v[28:31]
	v_mfma_f32_16x16x32_bf16 v[24:27], v[148:151], v[196:199], v[24:27]
	v_mfma_f32_16x16x32_bf16 v[12:15], v[140:143], v[204:207], v[12:15]
	v_mfma_f32_16x16x32_bf16 v[8:11], v[148:151], v[204:207], v[8:11]
	v_mfma_f32_16x16x32_bf16 v[60:63], v[144:147], v[184:187], v[60:63]
	v_mfma_f32_16x16x32_bf16 v[56:59], v[160:163], v[184:187], v[56:59]
	v_mfma_f32_16x16x32_bf16 v[44:47], v[144:147], v[192:195], v[44:47]
	v_mfma_f32_16x16x32_bf16 v[40:43], v[160:163], v[192:195], v[40:43]
	v_mfma_f32_16x16x32_bf16 v[28:31], v[144:147], v[200:203], v[28:31]
	v_mfma_f32_16x16x32_bf16 v[24:27], v[160:163], v[200:203], v[24:27]
	v_mfma_f32_16x16x32_bf16 v[12:15], v[144:147], v[208:211], v[12:15]
	v_mfma_f32_16x16x32_bf16 v[8:11], v[160:163], v[208:211], v[8:11]
	v_mfma_f32_16x16x32_bf16 v[52:55], v[164:167], v[180:183], v[52:55]
	v_mfma_f32_16x16x32_bf16 v[48:51], v[172:175], v[180:183], v[48:51]
	v_mfma_f32_16x16x32_bf16 v[36:39], v[164:167], v[188:191], v[36:39]
	v_mfma_f32_16x16x32_bf16 v[32:35], v[172:175], v[188:191], v[32:35]
	v_mfma_f32_16x16x32_bf16 v[20:23], v[164:167], v[196:199], v[20:23]
	v_mfma_f32_16x16x32_bf16 v[16:19], v[172:175], v[196:199], v[16:19]
	v_mfma_f32_16x16x32_bf16 v[4:7], v[164:167], v[204:207], v[4:7]
	v_mfma_f32_16x16x32_bf16 v[0:3], v[172:175], v[204:207], v[0:3]
	v_mfma_f32_16x16x32_bf16 v[52:55], v[168:171], v[184:187], v[52:55]
	v_mfma_f32_16x16x32_bf16 v[48:51], v[176:179], v[184:187], v[48:51]
	v_mfma_f32_16x16x32_bf16 v[36:39], v[168:171], v[192:195], v[36:39]
	v_mfma_f32_16x16x32_bf16 v[32:35], v[176:179], v[192:195], v[32:35]
	v_mfma_f32_16x16x32_bf16 v[20:23], v[168:171], v[200:203], v[20:23]
	v_mfma_f32_16x16x32_bf16 v[16:19], v[176:179], v[200:203], v[16:19]
	v_mfma_f32_16x16x32_bf16 v[4:7], v[168:171], v[208:211], v[4:7]
	v_mfma_f32_16x16x32_bf16 v[0:3], v[176:179], v[208:211], v[0:3]
	s_barrier
	s_add_i32 s79, 0, 0x18000
	s_add_i32 s80, 0, 0x1c000
	v_add_u32_e32 v160, s79, v155
	v_add_u32_e32 v176, s80, v155
	ds_read_b128 v[140:143], v160
	ds_read_b128 v[144:147], v160 offset:1024
	ds_read_b128 v[148:151], v160 offset:2048
	ds_read_b128 v[160:163], v160 offset:3072
	ds_read_b128 v[164:167], v176
	ds_read_b128 v[168:171], v176 offset:1024
	ds_read_b128 v[172:175], v176 offset:2048
	ds_read_b128 v[176:179], v176 offset:3072
	s_add_u32 s54, s54, 0x80000
	s_addc_u32 s55, s55, 0
	s_mov_b32 m0, s61
	v_lshl_add_u64 v[218:219], s[54:55], 0, v[128:129]
	ds_read_b128 v[180:183], v159 offset:32768
	ds_read_b128 v[184:187], v159 offset:33792
	ds_read_b128 v[188:191], v159 offset:34816
	ds_read_b128 v[192:195], v159 offset:35840
	ds_read_b128 v[196:199], v159 offset:36864
	ds_read_b128 v[200:203], v159 offset:37888
	ds_read_b128 v[204:207], v159 offset:38912
	ds_read_b128 v[208:211], v159 offset:39936
	global_load_lds_dwordx4 v[218:219], off
	v_lshl_add_u64 v[218:219], s[54:55], 0, v[130:131]
	s_mov_b32 m0, s62
	s_nop 0
	global_load_lds_dwordx4 v[218:219], off
	s_waitcnt vmcnt(8)
	s_waitcnt lgkmcnt(0)
	s_barrier
	s_waitcnt lgkmcnt(0)
	v_mfma_f32_16x16x32_bf16 v[124:127], v[140:143], v[180:183], v[124:127]
	v_mfma_f32_16x16x32_bf16 v[120:123], v[148:151], v[180:183], v[120:123]
	v_mfma_f32_16x16x32_bf16 v[108:111], v[140:143], v[188:191], v[108:111]
	v_mfma_f32_16x16x32_bf16 v[104:107], v[148:151], v[188:191], v[104:107]
	v_mfma_f32_16x16x32_bf16 v[92:95], v[140:143], v[196:199], v[92:95]
	v_mfma_f32_16x16x32_bf16 v[88:91], v[148:151], v[196:199], v[88:91]
	v_mfma_f32_16x16x32_bf16 v[76:79], v[140:143], v[204:207], v[76:79]
	v_mfma_f32_16x16x32_bf16 v[72:75], v[148:151], v[204:207], v[72:75]
	v_mfma_f32_16x16x32_bf16 v[124:127], v[144:147], v[184:187], v[124:127]
	v_mfma_f32_16x16x32_bf16 v[120:123], v[160:163], v[184:187], v[120:123]
	v_mfma_f32_16x16x32_bf16 v[108:111], v[144:147], v[192:195], v[108:111]
	v_mfma_f32_16x16x32_bf16 v[104:107], v[160:163], v[192:195], v[104:107]
	v_mfma_f32_16x16x32_bf16 v[92:95], v[144:147], v[200:203], v[92:95]
	v_mfma_f32_16x16x32_bf16 v[88:91], v[160:163], v[200:203], v[88:91]
	v_mfma_f32_16x16x32_bf16 v[76:79], v[144:147], v[208:211], v[76:79]
	v_mfma_f32_16x16x32_bf16 v[72:75], v[160:163], v[208:211], v[72:75]
	v_mfma_f32_16x16x32_bf16 v[116:119], v[164:167], v[180:183], v[116:119]
	v_mfma_f32_16x16x32_bf16 v[112:115], v[172:175], v[180:183], v[112:115]
	v_mfma_f32_16x16x32_bf16 v[100:103], v[164:167], v[188:191], v[100:103]
	v_mfma_f32_16x16x32_bf16 v[96:99], v[172:175], v[188:191], v[96:99]
	v_mfma_f32_16x16x32_bf16 v[84:87], v[164:167], v[196:199], v[84:87]
	v_mfma_f32_16x16x32_bf16 v[80:83], v[172:175], v[196:199], v[80:83]
	v_mfma_f32_16x16x32_bf16 v[68:71], v[164:167], v[204:207], v[68:71]
	v_mfma_f32_16x16x32_bf16 v[64:67], v[172:175], v[204:207], v[64:67]
	v_mfma_f32_16x16x32_bf16 v[116:119], v[168:171], v[184:187], v[116:119]
	v_mfma_f32_16x16x32_bf16 v[112:115], v[176:179], v[184:187], v[112:115]
	v_mfma_f32_16x16x32_bf16 v[100:103], v[168:171], v[192:195], v[100:103]
	v_mfma_f32_16x16x32_bf16 v[96:99], v[176:179], v[192:195], v[96:99]
	v_mfma_f32_16x16x32_bf16 v[84:87], v[168:171], v[200:203], v[84:87]
	v_mfma_f32_16x16x32_bf16 v[80:83], v[176:179], v[200:203], v[80:83]
	v_mfma_f32_16x16x32_bf16 v[68:71], v[168:171], v[208:211], v[68:71]
	v_mfma_f32_16x16x32_bf16 v[64:67], v[176:179], v[208:211], v[64:67]
	s_barrier
; #define PG8_STAGE(bufoff, gbase, voff) do { _Pragma("unroll") for (int _i = 0; _i < 2; ++_i) \
;         __builtin_amdgcn_global_load_lds((const unsigned*)((const char*)(gbase) + (voff)[_i]), (LAS unsigned*)(lds + (bufoff) + ldsw + _i * 8192), 16, 0, 0); } while (0)
; #define PG8_LDA(dst, b, h) do { _Pragma("unroll") for (int m = 0; m < 4; ++m) _Pragma("unroll") for (int k = 0; k < 2; ++k) dst[m][k] = *(const LAS bf16x8*)(lds + PG8_SA(b, h) + aoff + m * 2048 + k * 1024); } while (0)
; #define PG8_MMA(ai, bj, At, Bt) do { __builtin_amdgcn_s_setprio(1); _Pragma("unroll") for (int m = 0; m < 4; ++m) _Pragma("unroll") for (int n = 0; n < 2; ++n) _Pragma("unroll") for (int k = 0; k < 2; ++k) \
;         acc[ai][bj][m][n] = __builtin_amdgcn_mfma_f32_16x16x32_bf16(Bt[n][k], At[m][k], acc[ai][bj][m][n], 0, 0, 0); __builtin_amdgcn_s_setprio(0); } while (0)
; #define PG8_WAIT_V(n) asm volatile("s_waitcnt vmcnt(" #n ")" ::: "memory")
; #define PG8_WAIT_L(n) asm volatile("s_waitcnt lgkmcnt(" #n ")" ::: "memory")
; #define PG8_BAR __builtin_amdgcn_s_barrier()
; #define PG8_SCHED __builtin_amdgcn_sched_barrier(0)
; template <class Epi, class Sched, bool ALIGN_EPI = true, bool SP2 = true>
; DI void gemm_phase(LAS unsigned char* lds, const Gemm g, const Sched& S, const Epi& E) {
;     ...
;             PG8_LDA(At, 1, 1); PG8_STAGE(PG8_SB(1, 0), b3, voffB); PG8_STAGE(PG8_SB(1, 1), b3 + hstepB, voffB); PG8_STAGE(PG8_SA(1, 0), a3, voffA);
;             PG8_WAIT_V(8); PG8_WAIT_L(0); PG8_BAR; PG8_MMA(1, 0, At, B0); PG8_MMA(1, 1, At, B1); PG8_BAR; PG8_SCHED;
;         }
	s_add_i32 s54, s79, s58
	v_lshl_add_u64 v[152:153], v[152:153], 0, s[14:15]
	s_mov_b32 m0, s54
	ds_read_b128 v[180:183], v159 offset:49152
	ds_read_b128 v[184:187], v159 offset:50176
	ds_read_b128 v[188:191], v159 offset:51200
	ds_read_b128 v[192:195], v159 offset:52224
	ds_read_b128 v[196:199], v159 offset:53248
	ds_read_b128 v[200:203], v159 offset:54272
	ds_read_b128 v[204:207], v159 offset:55296
	ds_read_b128 v[208:211], v159 offset:56320
	global_load_lds_dwordx4 v[152:153], off
	s_add_i32 m0, s54, 0x2000
	s_add_u32 s52, s52, 0x80080
	v_lshl_add_u64 v[152:153], v[212:213], 0, s[14:15]
	s_addc_u32 s53, s53, 0
	s_add_i32 s54, s80, s58
	global_load_lds_dwordx4 v[152:153], off
	v_lshl_add_u64 v[152:153], s[52:53], 0, v[128:129]
	s_mov_b32 m0, s54
	s_nop 0
	global_load_lds_dwordx4 v[152:153], off
	v_lshl_add_u64 v[152:153], s[52:53], 0, v[130:131]
	s_add_i32 m0, s54, 0x2000
	s_nop 0
	global_load_lds_dwordx4 v[152:153], off
	v_lshl_add_u64 v[152:153], v[214:215], 0, s[14:15]
	s_mov_b32 m0, s65
	s_nop 0
	global_load_lds_dwordx4 v[152:153], off
	v_lshl_add_u64 v[152:153], v[216:217], 0, s[14:15]
	s_mov_b32 m0, s66
	s_nop 0
	global_load_lds_dwordx4 v[152:153], off
	s_waitcnt vmcnt(8)
	s_waitcnt lgkmcnt(0)
	s_barrier
	s_waitcnt lgkmcnt(0)
	v_mfma_f32_16x16x32_bf16 v[60:63], v[140:143], v[180:183], v[60:63]
	v_mfma_f32_16x16x32_bf16 v[56:59], v[148:151], v[180:183], v[56:59]
	v_mfma_f32_16x16x32_bf16 v[44:47], v[140:143], v[188:191], v[44:47]
	v_mfma_f32_16x16x32_bf16 v[40:43], v[148:151], v[188:191], v[40:43]
	v_mfma_f32_16x16x32_bf16 v[28:31], v[140:143], v[196:199], v[28:31]
	v_mfma_f32_16x16x32_bf16 v[24:27], v[148:151], v[196:199], v[24:27]
	v_mfma_f32_16x16x32_bf16 v[12:15], v[140:143], v[204:207], v[12:15]
	v_mfma_f32_16x16x32_bf16 v[8:11], v[148:151], v[204:207], v[8:11]
	v_mfma_f32_16x16x32_bf16 v[60:63], v[144:147], v[184:187], v[60:63]
	v_mfma_f32_16x16x32_bf16 v[56:59], v[160:163], v[184:187], v[56:59]
	v_mfma_f32_16x16x32_bf16 v[44:47], v[144:147], v[192:195], v[44:47]
	v_mfma_f32_16x16x32_bf16 v[40:43], v[160:163], v[192:195], v[40:43]
	v_mfma_f32_16x16x32_bf16 v[28:31], v[144:147], v[200:203], v[28:31]
	v_mfma_f32_16x16x32_bf16 v[24:27], v[160:163], v[200:203], v[24:27]
	v_mfma_f32_16x16x32_bf16 v[12:15], v[144:147], v[208:211], v[12:15]
	v_mfma_f32_16x16x32_bf16 v[8:11], v[160:163], v[208:211], v[8:11]
	v_mfma_f32_16x16x32_bf16 v[52:55], v[164:167], v[180:183], v[52:55]
	v_mfma_f32_16x16x32_bf16 v[48:51], v[172:175], v[180:183], v[48:51]
	v_mfma_f32_16x16x32_bf16 v[36:39], v[164:167], v[188:191], v[36:39]
	v_mfma_f32_16x16x32_bf16 v[32:35], v[172:175], v[188:191], v[32:35]
	v_mfma_f32_16x16x32_bf16 v[20:23], v[164:167], v[196:199], v[20:23]
	v_mfma_f32_16x16x32_bf16 v[16:19], v[172:175], v[196:199], v[16:19]
	v_mfma_f32_16x16x32_bf16 v[4:7], v[164:167], v[204:207], v[4:7]
	v_mfma_f32_16x16x32_bf16 v[0:3], v[172:175], v[204:207], v[0:3]
	v_mfma_f32_16x16x32_bf16 v[52:55], v[168:171], v[184:187], v[52:55]
	v_mfma_f32_16x16x32_bf16 v[48:51], v[176:179], v[184:187], v[48:51]
	v_mfma_f32_16x16x32_bf16 v[36:39], v[168:171], v[192:195], v[36:39]
	v_mfma_f32_16x16x32_bf16 v[32:35], v[176:179], v[192:195], v[32:35]
	v_mfma_f32_16x16x32_bf16 v[20:23], v[168:171], v[200:203], v[20:23]
	v_mfma_f32_16x16x32_bf16 v[16:19], v[176:179], v[200:203], v[16:19]
	v_mfma_f32_16x16x32_bf16 v[4:7], v[168:171], v[208:211], v[4:7]
	v_mfma_f32_16x16x32_bf16 v[0:3], v[176:179], v[208:211], v[0:3]
	s_barrier
	s_add_i32 s78, s78, 2
	s_add_u32 s48, s48, 0x100
	s_addc_u32 s49, s49, 0
	s_add_u32 s76, s76, 0x100
	s_addc_u32 s77, s77, 0
	s_cmp_gt_u32 s78, 29
	s_cbranch_scc0 .LBB0_2108
	s_and_b64 vcc, exec, s[16:17]
	s_cbranch_vccz .LBB0_2111
	s_barrier

;     DI size_t offA(const Unit& u) const { return (size_t)u.pm * tA + (size_t)u.pn * aPn; }
;     DI size_t offB(const Unit& u) const { return (size_t)u.pn * tB; }
; #define PG8_STAGE(bufoff, gbase, voff) do { _Pragma("unroll") for (int _i = 0; _i < 2; ++_i) \
;         __builtin_amdgcn_global_load_lds((const unsigned*)((const char*)(gbase) + (voff)[_i]), (LAS unsigned*)(lds + (bufoff) + ldsw + _i * 8192), 16, 0, 0); } while (0)
; #define PG8_LDA(dst, b, h) do { _Pragma("unroll") for (int m = 0; m < 4; ++m) _Pragma("unroll") for (int k = 0; k < 2; ++k) dst[m][k] = *(const LAS bf16x8*)(lds + PG8_SA(b, h) + aoff + m * 2048 + k * 1024); } while (0)
; #define PG8_LDB(dst, b, h) do { _Pragma("unroll") for (int n = 0; n < 2; ++n) _Pragma("unroll") for (int k = 0; k < 2; ++k) dst[n][k] = *(const LAS bf16x8*)(lds + PG8_SB(b, h) + boff + n * 2048 + k * 1024); } while (0)
; #define PG8_MMA(ai, bj, At, Bt) do { __builtin_amdgcn_s_setprio(1); _Pragma("unroll") for (int m = 0; m < 4; ++m) _Pragma("unroll") for (int n = 0; n < 2; ++n) _Pragma("unroll") for (int k = 0; k < 2; ++k) \
;         acc[ai][bj][m][n] = __builtin_amdgcn_mfma_f32_16x16x32_bf16(Bt[n][k], At[m][k], acc[ai][bj][m][n], 0, 0, 0); __builtin_amdgcn_s_setprio(0); } while (0)
; #define PG8_BAR __builtin_amdgcn_s_barrier()
; template <class Epi, class Sched, bool ALIGN_EPI = true, bool SP2 = true>
; DI void gemm_phase(LAS unsigned char* lds, const Gemm g, const Sched& S, const Epi& E) {
;     ...
;         const char* nA = has_next ? (const char*)g.A + S.offA(nxt) : cA; const char* nB = has_next ? (const char*)g.Bt + S.offB(nxt) : cB;
; #pragma unroll 1
;         for (int t = 0; t < nt; t += 2) {
;             const bool last = (t == nt - 2);
;             const char* a1 = cA + (size_t)(t + 1) * kstep;
;             const char* a2 = last ? nA : cA + (size_t)(t + 2) * kstep; const char* b2 = last ? nB : cB + (size_t)(t + 2) * kstep;
;             const char* a3 = a2 + kstep; const char* b3 = b2 + kstep;
;             PG8_LDB(B0, 0, 0); PG8_LDB(B1, 0, 1); PG8_SCHED; PG8_LDA(At, 0, 0); PG8_STAGE(PG8_SA(1, 1), a1 + hstepA, voffA);
;             PG8_WAIT_V(8); PG8_WAIT_L(0); PG8_BAR; PG8_MMA(0, 0, At, B0); PG8_MMA(0, 1, At, B1); PG8_BAR; PG8_SCHED;
;             PG8_LDA(At, 0, 1); PG8_STAGE(PG8_SB(0, 0), b2, voffB); PG8_STAGE(PG8_SB(0, 1), b2 + hstepB, voffB); PG8_STAGE(PG8_SA(0, 0), a2, voffA);
.LBB0_2199:
	v_add_u32_e32 v168, s63, v178
	v_add_u32_e32 v193, s64, v178
	ds_read_b128 v[156:159], v168
	ds_read_b128 v[160:163], v168 offset:1024
	ds_read_b128 v[164:167], v168 offset:2048
	ds_read_b128 v[168:171], v168 offset:3072
	ds_read_b128 v[172:175], v193
	ds_read_b128 v[194:197], v193 offset:1024
	ds_read_b128 v[198:201], v193 offset:2048
	ds_read_b128 v[202:205], v193 offset:3072
	s_add_u32 s46, s6, 0xfff80080
	s_addc_u32 s47, s7, -1
	s_cmp_eq_u32 s68, 28
	s_cselect_b32 s49, s35, s47
	s_cselect_b32 s48, s43, s46
	s_cselect_b32 s47, s37, s67
	s_cselect_b32 s46, s45, s66
	v_lshl_add_u64 v[240:241], s[6:7], 0, v[148:149]
	s_add_i32 m0, s53, 0xc000
	ds_read_b128 v[206:209], v190
	ds_read_b128 v[210:213], v190 offset:1024
	ds_read_b128 v[214:217], v190 offset:2048
	ds_read_b128 v[218:221], v190 offset:3072
	ds_read_b128 v[222:225], v190 offset:4096
	ds_read_b128 v[228:231], v190 offset:5120
	ds_read_b128 v[232:235], v190 offset:6144
	ds_read_b128 v[236:239], v190 offset:7168
	global_load_lds_dwordx4 v[240:241], off
	v_lshl_add_u64 v[240:241], s[6:7], 0, v[150:151]
	s_add_i32 m0, s53, 0xe000
	s_nop 0
	global_load_lds_dwordx4 v[240:241], off
	s_waitcnt vmcnt(8)
	s_waitcnt lgkmcnt(0)
	s_barrier
	s_waitcnt lgkmcnt(0)
	v_mfma_f32_16x16x32_bf16 v[124:127], v[156:159], v[206:209], v[124:127]
	v_mfma_f32_16x16x32_bf16 v[120:123], v[164:167], v[206:209], v[120:123]
	v_mfma_f32_16x16x32_bf16 v[108:111], v[156:159], v[214:217], v[108:111]
	v_mfma_f32_16x16x32_bf16 v[104:107], v[164:167], v[214:217], v[104:107]
	v_mfma_f32_16x16x32_bf16 v[92:95], v[156:159], v[222:225], v[92:95]
	v_mfma_f32_16x16x32_bf16 v[88:91], v[164:167], v[222:225], v[88:91]
	v_mfma_f32_16x16x32_bf16 v[76:79], v[156:159], v[232:235], v[76:79]
	v_mfma_f32_16x16x32_bf16 v[72:75], v[164:167], v[232:235], v[72:75]
	v_mfma_f32_16x16x32_bf16 v[124:127], v[160:163], v[210:213], v[124:127]
	v_mfma_f32_16x16x32_bf16 v[120:123], v[168:171], v[210:213], v[120:123]
	v_mfma_f32_16x16x32_bf16 v[108:111], v[160:163], v[218:221], v[108:111]
	v_mfma_f32_16x16x32_bf16 v[104:107], v[168:171], v[218:221], v[104:107]
	v_mfma_f32_16x16x32_bf16 v[92:95], v[160:163], v[228:231], v[92:95]
	v_mfma_f32_16x16x32_bf16 v[88:91], v[168:171], v[228:231], v[88:91]
	v_mfma_f32_16x16x32_bf16 v[76:79], v[160:163], v[236:239], v[76:79]
	v_mfma_f32_16x16x32_bf16 v[72:75], v[168:171], v[236:239], v[72:75]
	v_mfma_f32_16x16x32_bf16 v[116:119], v[172:175], v[206:209], v[116:119]
	v_mfma_f32_16x16x32_bf16 v[112:115], v[198:201], v[206:209], v[112:115]
	v_mfma_f32_16x16x32_bf16 v[100:103], v[172:175], v[214:217], v[100:103]
	v_mfma_f32_16x16x32_bf16 v[96:99], v[198:201], v[214:217], v[96:99]
	v_mfma_f32_16x16x32_bf16 v[84:87], v[172:175], v[222:225], v[84:87]
	v_mfma_f32_16x16x32_bf16 v[80:83], v[198:201], v[222:225], v[80:83]
	v_mfma_f32_16x16x32_bf16 v[68:71], v[172:175], v[232:235], v[68:71]
	v_mfma_f32_16x16x32_bf16 v[64:67], v[198:201], v[232:235], v[64:67]
	v_mfma_f32_16x16x32_bf16 v[116:119], v[194:197], v[210:213], v[116:119]
	v_mfma_f32_16x16x32_bf16 v[112:115], v[202:205], v[210:213], v[112:115]
	v_mfma_f32_16x16x32_bf16 v[100:103], v[194:197], v[218:221], v[100:103]
	v_mfma_f32_16x16x32_bf16 v[96:99], v[202:205], v[218:221], v[96:99]
	v_mfma_f32_16x16x32_bf16 v[84:87], v[194:197], v[228:231], v[84:87]
	v_mfma_f32_16x16x32_bf16 v[80:83], v[202:205], v[228:231], v[80:83]
	v_mfma_f32_16x16x32_bf16 v[68:71], v[194:197], v[236:239], v[68:71]
	v_mfma_f32_16x16x32_bf16 v[64:67], v[202:205], v[236:239], v[64:67]
	s_barrier
	s_add_i32 s69, s63, s52
	v_lshl_add_u64 v[240:241], s[46:47], 0, v[128:129]
	s_mov_b32 m0, s69
	ds_read_b128 v[206:209], v190 offset:16384
	ds_read_b128 v[210:213], v190 offset:17408
	ds_read_b128 v[214:217], v190 offset:18432
	ds_read_b128 v[218:221], v190 offset:19456
	ds_read_b128 v[222:225], v190 offset:20480
	ds_read_b128 v[228:231], v190 offset:21504
	ds_read_b128 v[232:235], v190 offset:22528
	ds_read_b128 v[236:239], v190 offset:23552
	global_load_lds_dwordx4 v[240:241], off
	s_add_i32 m0, s69, 0x2000
	s_add_u32 s70, s46, 0x80000
	v_lshl_add_u64 v[242:243], s[46:47], 0, v[130:131]
	s_addc_u32 s71, s47, 0
	s_add_i32 s69, s64, s52
	global_load_lds_dwordx4 v[242:243], off
	v_lshl_add_u64 v[244:245], s[70:71], 0, v[128:129]
	s_mov_b32 m0, s69
	v_lshl_add_u64 v[246:247], s[48:49], 0, v[130:131]
	global_load_lds_dwordx4 v[244:245], off
	v_lshl_add_u64 v[244:245], s[70:71], 0, v[130:131]
	s_add_i32 m0, s69, 0x2000
	s_nop 0
	global_load_lds_dwordx4 v[244:245], off
	v_lshl_add_u64 v[244:245], s[48:49], 0, v[128:129]
	s_mov_b32 m0, s53
	s_nop 0
	global_load_lds_dwordx4 v[244:245], off
	s_mov_b32 m0, s54
	s_nop 0
	global_load_lds_dwordx4 v[246:247], off
	s_waitcnt vmcnt(8)
	s_waitcnt lgkmcnt(0)
	s_barrier
; #define PG8_STAGE(bufoff, gbase, voff) do { _Pragma("unroll") for (int _i = 0; _i < 2; ++_i) \
;         __builtin_amdgcn_global_load_lds((const unsigned*)((const char*)(gbase) + (voff)[_i]), (LAS unsigned*)(lds + (bufoff) + ldsw + _i * 8192), 16, 0, 0); } while (0)
; #define PG8_LDA(dst, b, h) do { _Pragma("unroll") for (int m = 0; m < 4; ++m) _Pragma("unroll") for (int k = 0; k < 2; ++k) dst[m][k] = *(const LAS bf16x8*)(lds + PG8_SA(b, h) + aoff + m * 2048 + k * 1024); } while (0)
; #define PG8_LDB(dst, b, h) do { _Pragma("unroll") for (int n = 0; n < 2; ++n) _Pragma("unroll") for (int k = 0; k < 2; ++k) dst[n][k] = *(const LAS bf16x8*)(lds + PG8_SB(b, h) + boff + n * 2048 + k * 1024); } while (0)
; #define PG8_MMA(ai, bj, At, Bt) do { __builtin_amdgcn_s_setprio(1); _Pragma("unroll") for (int m = 0; m < 4; ++m) _Pragma("unroll") for (int n = 0; n < 2; ++n) _Pragma("unroll") for (int k = 0; k < 2; ++k) \
;         acc[ai][bj][m][n] = __builtin_amdgcn_mfma_f32_16x16x32_bf16(Bt[n][k], At[m][k], acc[ai][bj][m][n], 0, 0, 0); __builtin_amdgcn_s_setprio(0); } while (0)
; #define PG8_WAIT_V(n) asm volatile("s_waitcnt vmcnt(" #n ")" ::: "memory")
; #define PG8_WAIT_L(n) asm volatile("s_waitcnt lgkmcnt(" #n ")" ::: "memory")
; #define PG8_BAR __builtin_amdgcn_s_barrier()
; #define PG8_SCHED __builtin_amdgcn_sched_barrier(0)
; template <class Epi, class Sched, bool ALIGN_EPI = true, bool SP2 = true>
; DI void gemm_phase(LAS unsigned char* lds, const Gemm g, const Sched& S, const Epi& E) {
;     ...
;             PG8_WAIT_V(8); PG8_WAIT_L(0); PG8_BAR; PG8_MMA(1, 0, At, B0); PG8_MMA(1, 1, At, B1); PG8_BAR; PG8_SCHED;
;             PG8_LDB(B0, 1, 0); PG8_LDB(B1, 1, 1); PG8_SCHED; PG8_LDA(At, 1, 0); PG8_STAGE(PG8_SA(0, 1), a2 + hstepA, voffA);
;             PG8_WAIT_V(8); PG8_WAIT_L(0); PG8_BAR; PG8_MMA(0, 0, At, B0); PG8_MMA(0, 1, At, B1); PG8_BAR; PG8_SCHED;
	s_waitcnt lgkmcnt(0)
	v_mfma_f32_16x16x32_bf16 v[60:63], v[156:159], v[206:209], v[60:63]
	v_mfma_f32_16x16x32_bf16 v[56:59], v[164:167], v[206:209], v[56:59]
	v_mfma_f32_16x16x32_bf16 v[44:47], v[156:159], v[214:217], v[44:47]
	v_mfma_f32_16x16x32_bf16 v[40:43], v[164:167], v[214:217], v[40:43]
	v_mfma_f32_16x16x32_bf16 v[28:31], v[156:159], v[222:225], v[28:31]
	v_mfma_f32_16x16x32_bf16 v[24:27], v[164:167], v[222:225], v[24:27]
	v_mfma_f32_16x16x32_bf16 v[12:15], v[156:159], v[232:235], v[12:15]
	v_mfma_f32_16x16x32_bf16 v[8:11], v[164:167], v[232:235], v[8:11]
	v_mfma_f32_16x16x32_bf16 v[60:63], v[160:163], v[210:213], v[60:63]
	v_mfma_f32_16x16x32_bf16 v[56:59], v[168:171], v[210:213], v[56:59]
	v_mfma_f32_16x16x32_bf16 v[44:47], v[160:163], v[218:221], v[44:47]
	v_mfma_f32_16x16x32_bf16 v[40:43], v[168:171], v[218:221], v[40:43]
	v_mfma_f32_16x16x32_bf16 v[28:31], v[160:163], v[228:231], v[28:31]
	v_mfma_f32_16x16x32_bf16 v[24:27], v[168:171], v[228:231], v[24:27]
	v_mfma_f32_16x16x32_bf16 v[12:15], v[160:163], v[236:239], v[12:15]
	v_mfma_f32_16x16x32_bf16 v[8:11], v[168:171], v[236:239], v[8:11]
	v_mfma_f32_16x16x32_bf16 v[52:55], v[172:175], v[206:209], v[52:55]
	v_mfma_f32_16x16x32_bf16 v[48:51], v[198:201], v[206:209], v[48:51]
	v_mfma_f32_16x16x32_bf16 v[36:39], v[172:175], v[214:217], v[36:39]
	v_mfma_f32_16x16x32_bf16 v[32:35], v[198:201], v[214:217], v[32:35]
	v_mfma_f32_16x16x32_bf16 v[20:23], v[172:175], v[222:225], v[20:23]
	v_mfma_f32_16x16x32_bf16 v[16:19], v[198:201], v[222:225], v[16:19]
	v_mfma_f32_16x16x32_bf16 v[4:7], v[172:175], v[232:235], v[4:7]
	v_mfma_f32_16x16x32_bf16 v[0:3], v[198:201], v[232:235], v[0:3]
	v_mfma_f32_16x16x32_bf16 v[52:55], v[194:197], v[210:213], v[52:55]
	v_mfma_f32_16x16x32_bf16 v[48:51], v[202:205], v[210:213], v[48:51]
	v_mfma_f32_16x16x32_bf16 v[36:39], v[194:197], v[218:221], v[36:39]
	v_mfma_f32_16x16x32_bf16 v[32:35], v[202:205], v[218:221], v[32:35]
	v_mfma_f32_16x16x32_bf16 v[20:23], v[194:197], v[228:231], v[20:23]
	v_mfma_f32_16x16x32_bf16 v[16:19], v[202:205], v[228:231], v[16:19]
	v_mfma_f32_16x16x32_bf16 v[4:7], v[194:197], v[236:239], v[4:7]
	v_mfma_f32_16x16x32_bf16 v[0:3], v[202:205], v[236:239], v[0:3]
	s_barrier
	s_add_i32 s69, 0, 0x18000
	s_add_i32 s70, 0, 0x1c000
	v_add_u32_e32 v168, s69, v178
	v_add_u32_e32 v193, s70, v178
	ds_read_b128 v[156:159], v168
	ds_read_b128 v[160:163], v168 offset:1024
	ds_read_b128 v[164:167], v168 offset:2048
	ds_read_b128 v[168:171], v168 offset:3072
	ds_read_b128 v[172:175], v193
	ds_read_b128 v[194:197], v193 offset:1024
	ds_read_b128 v[198:201], v193 offset:2048
	ds_read_b128 v[202:205], v193 offset:3072
	s_add_u32 s48, s48, 0x80000
	s_addc_u32 s49, s49, 0
	s_mov_b32 m0, s55
	v_lshl_add_u64 v[248:249], s[48:49], 0, v[128:129]
	ds_read_b128 v[206:209], v190 offset:32768
	ds_read_b128 v[210:213], v190 offset:33792
	ds_read_b128 v[214:217], v190 offset:34816
	ds_read_b128 v[218:221], v190 offset:35840
	ds_read_b128 v[222:225], v190 offset:36864
	ds_read_b128 v[228:231], v190 offset:37888
	ds_read_b128 v[232:235], v190 offset:38912
	ds_read_b128 v[236:239], v190 offset:39936
	global_load_lds_dwordx4 v[248:249], off
	v_lshl_add_u64 v[248:249], s[48:49], 0, v[130:131]
	s_mov_b32 m0, s56
	s_nop 0
	global_load_lds_dwordx4 v[248:249], off
	s_waitcnt vmcnt(8)
	s_waitcnt lgkmcnt(0)
	s_barrier
	s_waitcnt lgkmcnt(0)
	v_mfma_f32_16x16x32_bf16 v[124:127], v[156:159], v[206:209], v[124:127]
	v_mfma_f32_16x16x32_bf16 v[120:123], v[164:167], v[206:209], v[120:123]
	v_mfma_f32_16x16x32_bf16 v[108:111], v[156:159], v[214:217], v[108:111]
	v_mfma_f32_16x16x32_bf16 v[104:107], v[164:167], v[214:217], v[104:107]
	v_mfma_f32_16x16x32_bf16 v[92:95], v[156:159], v[222:225], v[92:95]
	v_mfma_f32_16x16x32_bf16 v[88:91], v[164:167], v[222:225], v[88:91]
	v_mfma_f32_16x16x32_bf16 v[76:79], v[156:159], v[232:235], v[76:79]
	v_mfma_f32_16x16x32_bf16 v[72:75], v[164:167], v[232:235], v[72:75]
	v_mfma_f32_16x16x32_bf16 v[124:127], v[160:163], v[210:213], v[124:127]
	v_mfma_f32_16x16x32_bf16 v[120:123], v[168:171], v[210:213], v[120:123]
	v_mfma_f32_16x16x32_bf16 v[108:111], v[160:163], v[218:221], v[108:111]
	v_mfma_f32_16x16x32_bf16 v[104:107], v[168:171], v[218:221], v[104:107]
	v_mfma_f32_16x16x32_bf16 v[92:95], v[160:163], v[228:231], v[92:95]
	v_mfma_f32_16x16x32_bf16 v[88:91], v[168:171], v[228:231], v[88:91]
	v_mfma_f32_16x16x32_bf16 v[76:79], v[160:163], v[236:239], v[76:79]
	v_mfma_f32_16x16x32_bf16 v[72:75], v[168:171], v[236:239], v[72:75]
	v_mfma_f32_16x16x32_bf16 v[116:119], v[172:175], v[206:209], v[116:119]
	v_mfma_f32_16x16x32_bf16 v[112:115], v[198:201], v[206:209], v[112:115]
	v_mfma_f32_16x16x32_bf16 v[100:103], v[172:175], v[214:217], v[100:103]
	v_mfma_f32_16x16x32_bf16 v[96:99], v[198:201], v[214:217], v[96:99]
	v_mfma_f32_16x16x32_bf16 v[84:87], v[172:175], v[222:225], v[84:87]
	v_mfma_f32_16x16x32_bf16 v[80:83], v[198:201], v[222:225], v[80:83]
	v_mfma_f32_16x16x32_bf16 v[68:71], v[172:175], v[232:235], v[68:71]
	v_mfma_f32_16x16x32_bf16 v[64:67], v[198:201], v[232:235], v[64:67]
	v_mfma_f32_16x16x32_bf16 v[116:119], v[194:197], v[210:213], v[116:119]
	v_mfma_f32_16x16x32_bf16 v[112:115], v[202:205], v[210:213], v[112:115]
	v_mfma_f32_16x16x32_bf16 v[100:103], v[194:197], v[218:221], v[100:103]
	v_mfma_f32_16x16x32_bf16 v[96:99], v[202:205], v[218:221], v[96:99]
	v_mfma_f32_16x16x32_bf16 v[84:87], v[194:197], v[228:231], v[84:87]
	v_mfma_f32_16x16x32_bf16 v[80:83], v[202:205], v[228:231], v[80:83]
	v_mfma_f32_16x16x32_bf16 v[68:71], v[194:197], v[236:239], v[68:71]
	v_mfma_f32_16x16x32_bf16 v[64:67], v[202:205], v[236:239], v[64:67]
	s_barrier
; #define PG8_STAGE(bufoff, gbase, voff) do { _Pragma("unroll") for (int _i = 0; _i < 2; ++_i) \
;         __builtin_amdgcn_global_load_lds((const unsigned*)((const char*)(gbase) + (voff)[_i]), (LAS unsigned*)(lds + (bufoff) + ldsw + _i * 8192), 16, 0, 0); } while (0)
; #define PG8_LDA(dst, b, h) do { _Pragma("unroll") for (int m = 0; m < 4; ++m) _Pragma("unroll") for (int k = 0; k < 2; ++k) dst[m][k] = *(const LAS bf16x8*)(lds + PG8_SA(b, h) + aoff + m * 2048 + k * 1024); } while (0)
; #define PG8_MMA(ai, bj, At, Bt) do { __builtin_amdgcn_s_setprio(1); _Pragma("unroll") for (int m = 0; m < 4; ++m) _Pragma("unroll") for (int n = 0; n < 2; ++n) _Pragma("unroll") for (int k = 0; k < 2; ++k) \
;         acc[ai][bj][m][n] = __builtin_amdgcn_mfma_f32_16x16x32_bf16(Bt[n][k], At[m][k], acc[ai][bj][m][n], 0, 0, 0); __builtin_amdgcn_s_setprio(0); } while (0)
; #define PG8_WAIT_V(n) asm volatile("s_waitcnt vmcnt(" #n ")" ::: "memory")
; #define PG8_WAIT_L(n) asm volatile("s_waitcnt lgkmcnt(" #n ")" ::: "memory")
; #define PG8_BAR __builtin_amdgcn_s_barrier()
; #define PG8_SCHED __builtin_amdgcn_sched_barrier(0)
; template <class Epi, class Sched, bool ALIGN_EPI = true, bool SP2 = true>
; DI void gemm_phase(LAS unsigned char* lds, const Gemm g, const Sched& S, const Epi& E) {
;     ...
;             PG8_LDA(At, 1, 1); PG8_STAGE(PG8_SB(1, 0), b3, voffB); PG8_STAGE(PG8_SB(1, 1), b3 + hstepB, voffB); PG8_STAGE(PG8_SA(1, 0), a3, voffA);
;             PG8_WAIT_V(8); PG8_WAIT_L(0); PG8_BAR; PG8_MMA(1, 0, At, B0); PG8_MMA(1, 1, At, B1); PG8_BAR; PG8_SCHED;
;         }
	s_add_i32 s48, s69, s52
	v_lshl_add_u64 v[240:241], v[240:241], 0, s[22:23]
	s_mov_b32 m0, s48
	ds_read_b128 v[206:209], v190 offset:49152
	ds_read_b128 v[210:213], v190 offset:50176
	ds_read_b128 v[214:217], v190 offset:51200
	ds_read_b128 v[218:221], v190 offset:52224
	ds_read_b128 v[222:225], v190 offset:53248
	ds_read_b128 v[228:231], v190 offset:54272
	ds_read_b128 v[232:235], v190 offset:55296
	ds_read_b128 v[236:239], v190 offset:56320
	global_load_lds_dwordx4 v[240:241], off
	s_add_i32 m0, s48, 0x2000
	s_add_u32 s46, s46, 0x80080
	v_lshl_add_u64 v[240:241], v[242:243], 0, s[22:23]
	s_addc_u32 s47, s47, 0
	s_add_i32 s48, s70, s52
	global_load_lds_dwordx4 v[240:241], off
	v_lshl_add_u64 v[240:241], s[46:47], 0, v[128:129]
	s_mov_b32 m0, s48
	s_nop 0
	global_load_lds_dwordx4 v[240:241], off
	v_lshl_add_u64 v[240:241], s[46:47], 0, v[130:131]
	s_add_i32 m0, s48, 0x2000
	s_nop 0
	global_load_lds_dwordx4 v[240:241], off
	v_lshl_add_u64 v[240:241], v[244:245], 0, s[22:23]
	s_mov_b32 m0, s58
	s_nop 0
	global_load_lds_dwordx4 v[240:241], off
	v_lshl_add_u64 v[240:241], v[246:247], 0, s[22:23]
	s_mov_b32 m0, s59
	s_nop 0
	global_load_lds_dwordx4 v[240:241], off
	s_waitcnt vmcnt(8)
	s_waitcnt lgkmcnt(0)
	s_barrier
	s_waitcnt lgkmcnt(0)
	v_mfma_f32_16x16x32_bf16 v[60:63], v[156:159], v[206:209], v[60:63]
	v_mfma_f32_16x16x32_bf16 v[56:59], v[164:167], v[206:209], v[56:59]
	v_mfma_f32_16x16x32_bf16 v[44:47], v[156:159], v[214:217], v[44:47]
	v_mfma_f32_16x16x32_bf16 v[40:43], v[164:167], v[214:217], v[40:43]
	v_mfma_f32_16x16x32_bf16 v[28:31], v[156:159], v[222:225], v[28:31]
	v_mfma_f32_16x16x32_bf16 v[24:27], v[164:167], v[222:225], v[24:27]
	v_mfma_f32_16x16x32_bf16 v[12:15], v[156:159], v[232:235], v[12:15]
	v_mfma_f32_16x16x32_bf16 v[8:11], v[164:167], v[232:235], v[8:11]
	v_mfma_f32_16x16x32_bf16 v[60:63], v[160:163], v[210:213], v[60:63]
	v_mfma_f32_16x16x32_bf16 v[56:59], v[168:171], v[210:213], v[56:59]
	v_mfma_f32_16x16x32_bf16 v[44:47], v[160:163], v[218:221], v[44:47]
	v_mfma_f32_16x16x32_bf16 v[40:43], v[168:171], v[218:221], v[40:43]
	v_mfma_f32_16x16x32_bf16 v[28:31], v[160:163], v[228:231], v[28:31]
	v_mfma_f32_16x16x32_bf16 v[24:27], v[168:171], v[228:231], v[24:27]
	v_mfma_f32_16x16x32_bf16 v[12:15], v[160:163], v[236:239], v[12:15]
	v_mfma_f32_16x16x32_bf16 v[8:11], v[168:171], v[236:239], v[8:11]
	v_mfma_f32_16x16x32_bf16 v[52:55], v[172:175], v[206:209], v[52:55]
	v_mfma_f32_16x16x32_bf16 v[48:51], v[198:201], v[206:209], v[48:51]
	v_mfma_f32_16x16x32_bf16 v[36:39], v[172:175], v[214:217], v[36:39]
	v_mfma_f32_16x16x32_bf16 v[32:35], v[198:201], v[214:217], v[32:35]
	v_mfma_f32_16x16x32_bf16 v[20:23], v[172:175], v[222:225], v[20:23]
	v_mfma_f32_16x16x32_bf16 v[16:19], v[198:201], v[222:225], v[16:19]
	v_mfma_f32_16x16x32_bf16 v[4:7], v[172:175], v[232:235], v[4:7]
	v_mfma_f32_16x16x32_bf16 v[0:3], v[198:201], v[232:235], v[0:3]
	v_mfma_f32_16x16x32_bf16 v[52:55], v[194:197], v[210:213], v[52:55]
	v_mfma_f32_16x16x32_bf16 v[48:51], v[202:205], v[210:213], v[48:51]
	v_mfma_f32_16x16x32_bf16 v[36:39], v[194:197], v[218:221], v[36:39]
	v_mfma_f32_16x16x32_bf16 v[32:35], v[202:205], v[218:221], v[32:35]
	v_mfma_f32_16x16x32_bf16 v[20:23], v[194:197], v[228:231], v[20:23]
	v_mfma_f32_16x16x32_bf16 v[16:19], v[202:205], v[228:231], v[16:19]
	v_mfma_f32_16x16x32_bf16 v[4:7], v[194:197], v[236:239], v[4:7]
	v_mfma_f32_16x16x32_bf16 v[0:3], v[202:205], v[236:239], v[0:3]
	s_barrier
	s_add_i32 s68, s68, 2
	s_add_u32 s6, s6, 0x100
	s_addc_u32 s7, s7, 0
	s_add_u32 s66, s66, 0x100
	s_addc_u32 s67, s67, 0
	s_cmp_gt_u32 s68, 29
	s_cbranch_scc0 .LBB0_2199
	s_and_b64 vcc, exec, s[28:29]
	s_cbranch_vccz .LBB0_2202
	s_barrier
